# aligned_tuples_serpentine
# baseline (speedup 1.0000x reference)
; template <class Epi, class Sched, bool ALIGN_EPI = false, bool SP2 = false>
; __device__ __forceinline__ void gemm_phase(PG8_LAS unsigned char* lds, const Gemm g, const Sched& S, const Epi& E) {
;     ...
;     const int tid = tid_, wid = __builtin_amdgcn_readfirstlane(tid >> 6), lane = tid & 63, wr = wid >> 2, wc = wid & 3, fr = lane & 15, fq = lane >> 4;
;     const int K = g.K, nt = K / BK;
;     unsigned voffA[2], voffB[2];
; #pragma unroll
;     for (int i = 0; i < 2; ++i) { int R, C; stage_rc(tid * 16 + i * 8192, R, C); const int Rb = Epi::PERM ? ((R & ~31) + perm32(R & 31)) : R;
;         voffA[i] = (unsigned)(R * K + C) * 2u; voffB[i] = (unsigned)(Rb * K + C) * 2u; }
;     const size_t kstep = (size_t)(BK * 2);
;     const size_t hstep = (size_t)HALF * K * 2;
;     const size_t tstep = 2 * hstep;
;     const unsigned ldsw = (unsigned)wid * 1024u;
;     const int aoff = lds_byte(wr * 64 + fr, fq * 8), boff = lds_byte(wc * 32 + fr, fq * 8);
;     ...
;     Unit cur, nxt; int ui = 0;
;     if (!S.next(0, cur)) return;
;     f32x4 acc[2][2][4][2];
; #pragma unroll
;     for (int a = 0; a < 2; ++a)
; #pragma unroll
;         for (int b = 0; b < 2; ++b)
; #pragma unroll
;             for (int m = 0; m < 4; ++m)
; #pragma unroll
;                 for (int n = 0; n < 2; ++n) acc[a][b][m][n] = (f32x4){0.f, 0.f, 0.f, 0.f};
;     bf16x8 At[4][2], B0[2][2], B1[2][2];
;     const char* cA = (const char*)g.A + (size_t)cur.pm * tstep; const char* cB = (const char*)g.Bt + (size_t)cur.pn * tstep;
;     S.a_ready(cur);
;     if constexpr (SP2) {
;         PG8_STAGE(PG8_SB(0, 0), cB, voffB); PG8_STAGE(PG8_SB(0, 1), cB + hstep, voffB); PG8_STAGE(PG8_SA(0, 0), cA, voffA); PG8_STAGE(PG8_SA(0, 1), cA + hstep, voffA);
;         if (wr == 1) PG8_BAR;
;         PG8_WAIT_V(2); PG8_BAR;
;         PG8_STAGE(PG8_SB(1, 0), cB + kstep, voffB); PG8_STAGE(PG8_SA(1, 0), cA + kstep, voffA); PG8_STAGE(PG8_SB(1, 1), cB + hstep + kstep, voffB);
;         PG8_WAIT_V(6); PG8_BAR;
;     } else {
;         PG8_STAGE(PG8_SB(0, 0), cB, voffB); PG8_STAGE(PG8_SA(0, 0), cA, voffA); PG8_STAGE(PG8_SB(0, 1), cB + hstep, voffB); PG8_STAGE(PG8_SA(0, 1), cA + hstep, voffA);
;         if (wr == 1) PG8_BAR;
;         PG8_WAIT_V(4); PG8_BAR;
;         PG8_STAGE(PG8_SB(1, 0), cB + kstep, voffB); PG8_STAGE(PG8_SA(1, 0), cA + kstep, voffA); PG8_STAGE(PG8_SB(1, 1), cB + hstep + kstep, voffB);
;         PG8_WAIT_V(6); PG8_BAR;
.LBB0_769:
	s_cmp_lt_i32 s70, 6
	s_cselect_b64 s[4:5], -1, 0
	s_and_b64 s[4:5], s[4:5], s[0:1]
	s_andn2_b64 vcc, exec, s[4:5]
	s_cbranch_vccnz .LBB0_786
	v_writelane_b32 v253, s4, 0
	v_writelane_b32 v253, s5, 1
	v_writelane_b32 v253, s6, 2
	v_writelane_b32 v253, s7, 3
	v_writelane_b32 v253, s8, 4
	v_writelane_b32 v253, s9, 5
	v_writelane_b32 v253, s10, 6
	v_writelane_b32 v253, s11, 7
	v_writelane_b32 v253, s12, 8
	v_writelane_b32 v253, s13, 9
	v_writelane_b32 v253, s14, 10
	v_writelane_b32 v253, s15, 11
	v_writelane_b32 v253, s16, 12
	v_writelane_b32 v253, s17, 13
	v_writelane_b32 v253, s18, 14
	v_writelane_b32 v253, s19, 15
	v_writelane_b32 v253, s20, 16
	v_writelane_b32 v253, s21, 17
	v_writelane_b32 v253, s22, 18
	v_writelane_b32 v253, s23, 19
	v_writelane_b32 v253, s24, 20
	v_writelane_b32 v253, s25, 21
	v_writelane_b32 v253, s26, 22
	v_writelane_b32 v253, s27, 23
	v_writelane_b32 v253, s28, 24
	v_writelane_b32 v253, s29, 25
	v_writelane_b32 v253, s30, 26
	v_writelane_b32 v253, s31, 27
	v_writelane_b32 v253, s32, 28
	v_writelane_b32 v253, s33, 29
	v_writelane_b32 v253, s34, 30
	v_writelane_b32 v253, s35, 31
	v_writelane_b32 v253, s36, 32
	v_writelane_b32 v253, s37, 33
	v_writelane_b32 v253, s38, 34
	v_writelane_b32 v253, s39, 35
	v_writelane_b32 v253, s40, 36
	v_writelane_b32 v253, s41, 37
	v_writelane_b32 v253, s42, 38
	v_writelane_b32 v253, s43, 39
	v_writelane_b32 v253, s44, 40
	v_writelane_b32 v253, s45, 41
	v_writelane_b32 v253, s46, 42
	v_writelane_b32 v253, s47, 43
	v_writelane_b32 v253, s48, 44
	v_writelane_b32 v253, s49, 45
	v_writelane_b32 v253, s50, 46
	v_writelane_b32 v253, s51, 47
	v_writelane_b32 v253, s52, 48
	v_writelane_b32 v253, s53, 49
	v_writelane_b32 v253, s54, 50
	v_writelane_b32 v253, s55, 51
	v_writelane_b32 v253, s56, 52
	v_writelane_b32 v253, s57, 53
	v_writelane_b32 v253, s58, 54
	v_writelane_b32 v253, s59, 55
	s_mov_b32 s40, vcc_lo
	s_mov_b32 s41, vcc_hi
	v_writelane_b32 v253, s40, 60
	v_writelane_b32 v253, s41, 61
	v_lshrrev_b32_e32 v254, 6, v185
	v_readlane_b32 s14, v244, 4
	v_readfirstlane_b32 s36, v254
	s_nop 3
	s_lshr_b32 s37, s36, 2
	s_and_b32 s38, s36, 3
	s_lshl_b32 s35, s36, 10
	s_add_u32 s10, s76, 0x6800000
	s_addc_u32 s11, s77, 0
	s_add_u32 s12, s76, 0x2500000
	s_addc_u32 s13, s77, 0
	s_mov_b32 s16, 0
	s_mul_i32 s40, s16, s14
	s_add_u32 s40, s40, s2
	s_cmp_lt_u32 s40, 2816
	s_cselect_b32 s44, 1, 0
	s_min_u32 s40, s40, 2815
	s_and_b32 s41, s40, 7
	s_lshr_b32 s42, s40, 3
	s_mul_i32 s41, s41, 352
	s_add_u32 s41, s41, s42
	s_mul_hi_u32 s42, s41, 0xba2e8c
	s_mul_i32 s43, s42, 352
	s_sub_u32 s43, s41, s43
	s_and_b32 s40, s43, 7
	s_lshl_b32 s42, s42, 3
	s_add_u32 s17, s42, s40
	s_lshr_b32 s18, s43, 3
	s_cmp_eq_u32 s44, 0
	s_cbranch_scc1 .Lp5_exit
	v_and_b32_e32 v254, 63, v185
	v_and_b32_e32 v255, 15, v254
	v_lshrrev_b32_e32 v186, 1, v255
	v_lshrrev_b32_e32 v187, 4, v254
	v_xor_b32_e32 v186, v186, v187
	v_lshlrev_b32_e32 v255, 7, v255
	v_lshl_or_b32 v255, v186, 4, v255
	s_lshl_b32 s40, s37, 13
	s_lshl_b32 s41, s38, 12
	s_add_u32 s41, s41, 0x10000
	v_add_u32_e32 v245, s40, v255
	v_add_u32_e32 v247, s41, v255
	v_xor_b32_e32 v246, 64, v245
	v_xor_b32_e32 v248, 64, v247
	v_lshrrev_b32_e32 v255, 3, v254
	v_and_b32_e32 v186, 7, v254
	s_and_b32 s40, s36, 1
	s_lshl_b32 s40, s40, 2
	v_lshrrev_b32_e32 v187, 1, v255
	v_add_u32_e32 v187, s40, v187
	v_xor_b32_e32 v186, v186, v187
	v_lshlrev_b32_e32 v186, 4, v186
	s_lshl_b32 s40, s36, 3
	v_add_u32_e32 v187, s40, v255
	v_mul_u32_u24_e32 v187, 0x1000, v187
	v_add_u32_e32 v249, v187, v186
	v_add_u32_e32 v250, 0x40000, v249
	s_and_b32 s40, s36, 3
	s_lshl_b32 s40, s40, 3
	v_add_u32_e32 v187, s40, v255
	v_lshrrev_b32_e32 v254, 4, v187
	v_lshlrev_b32_e32 v254, 2, v254
	v_and_b32_e32 v255, 3, v187
	v_add_u32_e32 v254, v254, v255
	v_and_b32_e32 v187, 12, v187
	v_lshl_add_u32 v254, v187, 1, v254
	s_lshr_b32 s40, s36, 2
	s_lshl_b32 s40, s40, 5
	v_add_u32_e32 v254, s40, v254
	v_mul_u32_u24_e32 v254, 0x1000, v254
	v_add_u32_e32 v251, v254, v186
	v_add_u32_e32 v252, 0x40000, v251
	s_mul_i32 s40, s17, 0x100000
	s_add_u32 s22, s10, s40
	s_addc_u32 s23, s11, 0
	s_mul_i32 s40, s18, 0x100000
	s_add_u32 s24, s12, s40
	s_addc_u32 s25, s13, 0
	s_and_b32 s40, s16, 1
	s_lshl_b32 s4, s40, 8
	s_sub_u32 s4, 128, s4
	s_sub_u32 s5, 0, s40
	s_mul_i32 s8, s40, 3968
	s_add_u32 s30, s22, s8
	s_addc_u32 s31, s23, 0
	s_add_u32 s32, s24, s8
	s_addc_u32 s33, s25, 0
	s_add_u32 s56, s30, 0x80000
	s_addc_u32 s57, s31, 0
	s_add_u32 s58, s32, 0x80000
	s_addc_u32 s59, s33, 0
	s_add_i32 m0, s35, 0x0
	s_nop 0
	global_load_lds_dwordx4 v249, s[30:31]
	s_add_i32 m0, s35, 0x2000
	s_nop 0
	global_load_lds_dwordx4 v250, s[30:31]
	s_add_i32 m0, s35, 0x10000
	s_nop 0
	global_load_lds_dwordx4 v251, s[32:33]
	s_add_i32 m0, s35, 0x12000
	s_nop 0
	global_load_lds_dwordx4 v252, s[32:33]
	s_add_i32 m0, s35, 0x4000
	s_nop 0
	global_load_lds_dwordx4 v249, s[56:57]
	s_add_i32 m0, s35, 0x6000
	s_nop 0
	global_load_lds_dwordx4 v250, s[56:57]
	s_add_i32 m0, s35, 0x14000
	s_nop 0
	global_load_lds_dwordx4 v251, s[58:59]
	s_add_i32 m0, s35, 0x16000
	s_nop 0
	global_load_lds_dwordx4 v252, s[58:59]
	s_add_u32 s30, s30, s4
	s_addc_u32 s31, s31, s5
	s_add_u32 s56, s56, s4
	s_addc_u32 s57, s57, s5
	s_add_u32 s32, s32, s4
	s_addc_u32 s33, s33, s5
	s_add_u32 s58, s58, s4
	s_addc_u32 s59, s59, s5
	s_add_i32 m0, s35, 0x8000
	s_nop 0
	global_load_lds_dwordx4 v249, s[30:31]
	s_add_i32 m0, s35, 0xa000
	s_nop 0
	global_load_lds_dwordx4 v250, s[30:31]
	s_add_i32 m0, s35, 0x1c000
	s_nop 0
	global_load_lds_dwordx4 v251, s[58:59]
	s_add_i32 m0, s35, 0x1e000
	s_nop 0
	global_load_lds_dwordx4 v252, s[58:59]
	s_add_i32 m0, s35, 0xc000
	s_nop 0
	global_load_lds_dwordx4 v249, s[56:57]
	s_add_i32 m0, s35, 0xe000
	s_nop 0
	global_load_lds_dwordx4 v250, s[56:57]
	s_add_i32 m0, s35, 0x18000
	s_nop 0
	global_load_lds_dwordx4 v251, s[32:33]
	s_add_i32 m0, s35, 0x1a000
	s_nop 0
	global_load_lds_dwordx4 v252, s[32:33]
	s_add_u32 s30, s30, s4
	s_addc_u32 s31, s31, s5
	s_add_u32 s56, s56, s4
	s_addc_u32 s57, s57, s5
	s_add_u32 s32, s32, s4
	s_addc_u32 s33, s33, s5
	s_add_u32 s58, s58, s4
	s_addc_u32 s59, s59, s5
	s_waitcnt vmcnt(12)
	s_barrier
; #define PG8_STAGE(bufoff, gbase, voff) do { _Pragma("unroll") for (int _i = 0; _i < 2; ++_i) \
;         __builtin_amdgcn_global_load_lds((const unsigned*)((const char*)(gbase) + (voff)[_i]), (PG8_LAS unsigned*)(lds + (bufoff) + ldsw + _i * 8192), 16, 0, 0); } while (0)
; #define PG8_LDA(dst, b, h) do { _Pragma("unroll") for (int m = 0; m < 4; ++m) _Pragma("unroll") for (int k = 0; k < 2; ++k) dst[m][k] = *(const PG8_LAS bf16x8*)(lds + PG8_SA(b, h) + aoff + m * 2048 + k * 1024); } while (0)
; #define PG8_LDB(dst, b, h) do { _Pragma("unroll") for (int n = 0; n < 2; ++n) _Pragma("unroll") for (int k = 0; k < 2; ++k) dst[n][k] = *(const PG8_LAS bf16x8*)(lds + PG8_SB(b, h) + boff + n * 2048 + k * 1024); } while (0)
; #define PG8_SCHED __builtin_amdgcn_sched_barrier(0)
; template <class Epi, class Sched, bool ALIGN_EPI = false, bool SP2 = false>
; __device__ __forceinline__ void gemm_phase(PG8_LAS unsigned char* lds, const Gemm g, const Sched& S, const Epi& E) {
;     ...
;         const bool has_next = S.next(ui + 1, nxt);
;         const char* nA = has_next ? (const char*)g.A + (size_t)nxt.pm * tstep : cA; const char* nB = has_next ? (const char*)g.Bt + (size_t)nxt.pn * tstep : cB;
;         for (int t = 0; t < nt; t += 2) {
;             const bool last = (t == nt - 2);
;             const char* a1 = cA + (size_t)(t + 1) * kstep;
;             const char* a2 = last ? nA : cA + (size_t)(t + 2) * kstep; const char* b2 = last ? nB : cB + (size_t)(t + 2) * kstep;
;             const char* a3 = a2 + kstep; const char* b3 = b2 + kstep;
;             if (last && has_next) S.a_ready(nxt);
;             if constexpr (SP2) {
;             PG8_LDB(B0, 0, 0); PG8_LDB(B1, 0, 1); PG8_SCHED; PG8_LDA(At, 0, 0); PG8_STAGE(PG8_SA(1, 1), a1 + hstep, voffA);
;     ...
; #pragma unroll
;         for (int a = 0; a < 2; ++a)
; #pragma unroll
;             for (int b = 0; b < 2; ++b)
; #pragma unroll
;                 for (int m = 0; m < 4; ++m)
; #pragma unroll
;                     for (int n = 0; n < 2; ++n) acc[a][b][m][n] = (f32x4){0.f, 0.f, 0.f, 0.f};
;         cur = nxt; cA = nA; cB = nB; ++ui;
.Lp5_unit:
	s_add_u32 s45, s16, 1
	s_mul_i32 s40, s45, s14
	s_add_u32 s40, s40, s2
	s_cmp_lt_u32 s40, 2816
	s_cselect_b32 s19, 1, 0
	s_min_u32 s40, s40, 2815
	s_and_b32 s41, s40, 7
	s_lshr_b32 s42, s40, 3
	s_mul_i32 s41, s41, 352
	s_add_u32 s41, s41, s42
	s_mul_hi_u32 s42, s41, 0xba2e8c
	s_mul_i32 s43, s42, 352
	s_sub_u32 s43, s41, s43
	s_and_b32 s40, s43, 7
	s_lshl_b32 s42, s42, 3
	s_add_u32 s20, s42, s40
	s_lshr_b32 s21, s43, 3
	s_mul_i32 s40, s20, 0x100000
	s_add_u32 s26, s10, s40
	s_addc_u32 s27, s11, 0
	s_mul_i32 s40, s21, 0x100000
	s_add_u32 s28, s12, s40
	s_addc_u32 s29, s13, 0
	s_cmp_eq_u32 s19, 0
	s_cselect_b32 s26, s22, s26
	s_cselect_b32 s27, s23, s27
	s_cselect_b32 s28, s24, s28
	s_cselect_b32 s29, s25, s29
	s_add_u32 s30, s22, s8
	s_addc_u32 s31, s23, 0
	s_add_u32 s32, s24, s8
	s_addc_u32 s33, s25, 0
	s_add_u32 s30, s30, s4
	s_addc_u32 s31, s31, s5
	s_add_u32 s32, s32, s4
	s_addc_u32 s33, s33, s5
	s_add_u32 s30, s30, s4
	s_addc_u32 s31, s31, s5
	s_add_u32 s32, s32, s4
	s_addc_u32 s33, s33, s5
	s_add_u32 s56, s30, 0x80000
	s_addc_u32 s57, s31, 0
	s_add_u32 s58, s32, 0x80000
	s_addc_u32 s59, s33, 0
	s_movk_i32 s34, 16
	v_mov_b32_e32 v0, 0
	v_mov_b32_e32 v1, 0
	v_mov_b32_e32 v2, 0
	v_mov_b32_e32 v3, 0
	v_mov_b32_e32 v4, 0
	v_mov_b32_e32 v5, 0
	v_mov_b32_e32 v6, 0
	v_mov_b32_e32 v7, 0
	v_mov_b32_e32 v8, 0
	v_mov_b32_e32 v9, 0
	v_mov_b32_e32 v10, 0
	v_mov_b32_e32 v11, 0
	v_mov_b32_e32 v12, 0
	v_mov_b32_e32 v13, 0
	v_mov_b32_e32 v14, 0
	v_mov_b32_e32 v15, 0
	v_mov_b32_e32 v16, 0
	v_mov_b32_e32 v17, 0
	v_mov_b32_e32 v18, 0
	v_mov_b32_e32 v19, 0
	v_mov_b32_e32 v20, 0
	v_mov_b32_e32 v21, 0
	v_mov_b32_e32 v22, 0
	v_mov_b32_e32 v23, 0
	v_mov_b32_e32 v24, 0
	v_mov_b32_e32 v25, 0
	v_mov_b32_e32 v26, 0
	v_mov_b32_e32 v27, 0
	v_mov_b32_e32 v28, 0
	v_mov_b32_e32 v29, 0
	v_mov_b32_e32 v30, 0
	v_mov_b32_e32 v31, 0
	v_mov_b32_e32 v32, 0
	v_mov_b32_e32 v33, 0
	v_mov_b32_e32 v34, 0
	v_mov_b32_e32 v35, 0
	v_mov_b32_e32 v36, 0
	v_mov_b32_e32 v37, 0
	v_mov_b32_e32 v38, 0
	v_mov_b32_e32 v39, 0
	v_mov_b32_e32 v40, 0
	v_mov_b32_e32 v41, 0
	v_mov_b32_e32 v42, 0
	v_mov_b32_e32 v43, 0
	v_mov_b32_e32 v44, 0
	v_mov_b32_e32 v45, 0
	v_mov_b32_e32 v46, 0
	v_mov_b32_e32 v47, 0
	v_mov_b32_e32 v48, 0
	v_mov_b32_e32 v49, 0
	v_mov_b32_e32 v50, 0
	v_mov_b32_e32 v51, 0
	v_mov_b32_e32 v52, 0
	v_mov_b32_e32 v53, 0
	v_mov_b32_e32 v54, 0
	v_mov_b32_e32 v55, 0
	v_mov_b32_e32 v56, 0
	v_mov_b32_e32 v57, 0
	v_mov_b32_e32 v58, 0
	v_mov_b32_e32 v59, 0
	v_mov_b32_e32 v60, 0
	v_mov_b32_e32 v61, 0
	v_mov_b32_e32 v62, 0
	v_mov_b32_e32 v63, 0
	v_mov_b32_e32 v64, 0
	v_mov_b32_e32 v65, 0
	v_mov_b32_e32 v66, 0
	v_mov_b32_e32 v67, 0
	v_mov_b32_e32 v68, 0
	v_mov_b32_e32 v69, 0
	v_mov_b32_e32 v70, 0
	v_mov_b32_e32 v71, 0
	v_mov_b32_e32 v72, 0
	v_mov_b32_e32 v73, 0
	v_mov_b32_e32 v74, 0
	v_mov_b32_e32 v75, 0
	v_mov_b32_e32 v76, 0
	v_mov_b32_e32 v77, 0
	v_mov_b32_e32 v78, 0
	v_mov_b32_e32 v79, 0
	v_mov_b32_e32 v80, 0
	v_mov_b32_e32 v81, 0
	v_mov_b32_e32 v82, 0
	v_mov_b32_e32 v83, 0
	v_mov_b32_e32 v84, 0
	v_mov_b32_e32 v85, 0
	v_mov_b32_e32 v86, 0
	v_mov_b32_e32 v87, 0
	v_mov_b32_e32 v88, 0
	v_mov_b32_e32 v89, 0
	v_mov_b32_e32 v90, 0
	v_mov_b32_e32 v91, 0
	v_mov_b32_e32 v92, 0
	v_mov_b32_e32 v93, 0
	v_mov_b32_e32 v94, 0
	v_mov_b32_e32 v95, 0
	v_mov_b32_e32 v96, 0
	v_mov_b32_e32 v97, 0
	v_mov_b32_e32 v98, 0
	v_mov_b32_e32 v99, 0
	v_mov_b32_e32 v100, 0
	v_mov_b32_e32 v101, 0
	v_mov_b32_e32 v102, 0
	v_mov_b32_e32 v103, 0
	v_mov_b32_e32 v104, 0
	v_mov_b32_e32 v105, 0
	v_mov_b32_e32 v106, 0
	v_mov_b32_e32 v107, 0
	v_mov_b32_e32 v108, 0
	v_mov_b32_e32 v109, 0
	v_mov_b32_e32 v110, 0
	v_mov_b32_e32 v111, 0
	v_mov_b32_e32 v112, 0
	v_mov_b32_e32 v113, 0
	v_mov_b32_e32 v114, 0
	v_mov_b32_e32 v115, 0
	v_mov_b32_e32 v116, 0
	v_mov_b32_e32 v117, 0
	v_mov_b32_e32 v118, 0
	v_mov_b32_e32 v119, 0
	v_mov_b32_e32 v120, 0
	v_mov_b32_e32 v121, 0
	v_mov_b32_e32 v122, 0
	v_mov_b32_e32 v123, 0
	v_mov_b32_e32 v124, 0
	v_mov_b32_e32 v125, 0
	v_mov_b32_e32 v126, 0
	v_mov_b32_e32 v127, 0
	ds_read_b128 v[196:199], v247 offset:0
	ds_read_b128 v[200:203], v248 offset:0
	ds_read_b128 v[204:207], v247 offset:2048
	ds_read_b128 v[208:211], v248 offset:2048
	ds_read_b128 v[128:131], v245 offset:0
	ds_read_b128 v[132:135], v246 offset:0
	ds_read_b128 v[136:139], v245 offset:2048
	ds_read_b128 v[140:143], v246 offset:2048
	ds_read_b128 v[144:147], v245 offset:4096
	ds_read_b128 v[148:151], v246 offset:4096
	ds_read_b128 v[152:155], v245 offset:6144
	ds_read_b128 v[156:159], v246 offset:6144
	s_cmp_ge_u32 s36, 4
	s_cbranch_scc1 .Lp5_kloop1
; #define PG8_STAGE(bufoff, gbase, voff) do { _Pragma("unroll") for (int _i = 0; _i < 2; ++_i) \
;         __builtin_amdgcn_global_load_lds((const unsigned*)((const char*)(gbase) + (voff)[_i]), (PG8_LAS unsigned*)(lds + (bufoff) + ldsw + _i * 8192), 16, 0, 0); } while (0)
; #define PG8_LDA(dst, b, h) do { _Pragma("unroll") for (int m = 0; m < 4; ++m) _Pragma("unroll") for (int k = 0; k < 2; ++k) dst[m][k] = *(const PG8_LAS bf16x8*)(lds + PG8_SA(b, h) + aoff + m * 2048 + k * 1024); } while (0)
; #define PG8_LDB(dst, b, h) do { _Pragma("unroll") for (int n = 0; n < 2; ++n) _Pragma("unroll") for (int k = 0; k < 2; ++k) dst[n][k] = *(const PG8_LAS bf16x8*)(lds + PG8_SB(b, h) + boff + n * 2048 + k * 1024); } while (0)
; #define PG8_MMA(ai, bj, At, Bt) do { __builtin_amdgcn_s_setprio(1); _Pragma("unroll") for (int m = 0; m < 4; ++m) _Pragma("unroll") for (int n = 0; n < 2; ++n) _Pragma("unroll") for (int k = 0; k < 2; ++k) \
;         acc[ai][bj][m][n] = __builtin_amdgcn_mfma_f32_16x16x32_bf16(Bt[n][k], At[m][k], acc[ai][bj][m][n], 0, 0, 0); __builtin_amdgcn_s_setprio(0); } while (0)
; #define PG8_WAIT_V(n) asm volatile("s_waitcnt vmcnt(" #n ")" ::: "memory")
; #define PG8_WAIT_L(n) asm volatile("s_waitcnt lgkmcnt(" #n ")" ::: "memory")
; #define PG8_BAR __builtin_amdgcn_s_barrier()
; #define PG8_SCHED __builtin_amdgcn_sched_barrier(0)
; template <class Epi, class Sched, bool ALIGN_EPI = false, bool SP2 = false>
; __device__ __forceinline__ void gemm_phase(PG8_LAS unsigned char* lds, const Gemm g, const Sched& S, const Epi& E) {
;     ...
;             PG8_LDB(B0, 0, 0); PG8_LDB(B1, 0, 1); PG8_SCHED; PG8_LDA(At, 0, 0); PG8_STAGE(PG8_SA(1, 1), a1 + hstep, voffA);
;             PG8_WAIT_V(8); PG8_WAIT_L(0); PG8_BAR; PG8_MMA(0, 0, At, B0); PG8_MMA(0, 1, At, B1); PG8_BAR; PG8_SCHED;
;             PG8_LDA(At, 0, 1); PG8_STAGE(PG8_SB(0, 0), b2, voffB); PG8_STAGE(PG8_SB(0, 1), b2 + hstep, voffB); PG8_STAGE(PG8_SA(0, 0), a2, voffA);
;             PG8_WAIT_V(8); PG8_WAIT_L(0); PG8_BAR; PG8_MMA(1, 0, At, B0); PG8_MMA(1, 1, At, B1); PG8_BAR; PG8_SCHED;
;             PG8_LDB(B0, 1, 0); PG8_LDB(B1, 1, 1); PG8_SCHED; PG8_LDA(At, 1, 0); PG8_STAGE(PG8_SA(0, 1), a2 + hstep, voffA);
;             PG8_WAIT_V(8); PG8_WAIT_L(0); PG8_BAR; PG8_MMA(0, 0, At, B0); PG8_MMA(0, 1, At, B1); PG8_BAR; PG8_SCHED;
.Lp5_kloop0:
	s_waitcnt vmcnt(8)
	s_waitcnt lgkmcnt(0)
	s_barrier
	v_mfma_f32_16x16x32_bf16 v[0:3], v[196:199], v[128:131], v[0:3]
	ds_read_b128 v[212:215], v247 offset:16384
	v_mfma_f32_16x16x32_bf16 v[0:3], v[200:203], v[132:135], v[0:3]
	ds_read_b128 v[216:219], v248 offset:16384
	v_mfma_f32_16x16x32_bf16 v[4:7], v[208:211], v[132:135], v[4:7]
	ds_read_b128 v[220:223], v247 offset:18432
	v_mfma_f32_16x16x32_bf16 v[4:7], v[204:207], v[128:131], v[4:7]
	ds_read_b128 v[224:227], v248 offset:18432
	v_mfma_f32_16x16x32_bf16 v[12:15], v[204:207], v[136:139], v[12:15]
	s_add_i32 m0, s35, 0x0
	v_mfma_f32_16x16x32_bf16 v[12:15], v[208:211], v[140:143], v[12:15]
	global_load_lds_dwordx4 v249, s[30:31]
	v_mfma_f32_16x16x32_bf16 v[8:11], v[200:203], v[140:143], v[8:11]
	s_add_i32 m0, s35, 0x2000
	v_mfma_f32_16x16x32_bf16 v[8:11], v[196:199], v[136:139], v[8:11]
	global_load_lds_dwordx4 v250, s[30:31]
	v_mfma_f32_16x16x32_bf16 v[16:19], v[196:199], v[144:147], v[16:19]
	s_add_i32 m0, s35, 0x10000
	v_mfma_f32_16x16x32_bf16 v[16:19], v[200:203], v[148:151], v[16:19]
	global_load_lds_dwordx4 v251, s[32:33]
	v_mfma_f32_16x16x32_bf16 v[20:23], v[208:211], v[148:151], v[20:23]
	s_add_i32 m0, s35, 0x12000
	v_mfma_f32_16x16x32_bf16 v[20:23], v[204:207], v[144:147], v[20:23]
	global_load_lds_dwordx4 v252, s[32:33]
	v_mfma_f32_16x16x32_bf16 v[28:31], v[204:207], v[152:155], v[28:31]
	ds_read_b128 v[160:163], v245 offset:16384
	v_mfma_f32_16x16x32_bf16 v[28:31], v[208:211], v[156:159], v[28:31]
	ds_read_b128 v[164:167], v246 offset:16384
	v_mfma_f32_16x16x32_bf16 v[24:27], v[200:203], v[156:159], v[24:27]
	ds_read_b128 v[168:171], v245 offset:18432
	v_mfma_f32_16x16x32_bf16 v[24:27], v[196:199], v[152:155], v[24:27]
	ds_read_b128 v[172:175], v246 offset:18432
	s_waitcnt lgkmcnt(4)
	v_mfma_f32_16x16x32_bf16 v[32:35], v[212:215], v[128:131], v[32:35]
	ds_read_b128 v[176:179], v245 offset:20480
	v_mfma_f32_16x16x32_bf16 v[32:35], v[216:219], v[132:135], v[32:35]
	ds_read_b128 v[180:183], v246 offset:20480
	v_mfma_f32_16x16x32_bf16 v[36:39], v[224:227], v[132:135], v[36:39]
	ds_read_b128 v[188:191], v245 offset:22528
	v_mfma_f32_16x16x32_bf16 v[36:39], v[220:223], v[128:131], v[36:39]
	ds_read_b128 v[192:195], v246 offset:22528
	v_mfma_f32_16x16x32_bf16 v[44:47], v[220:223], v[136:139], v[44:47]
	v_mfma_f32_16x16x32_bf16 v[44:47], v[224:227], v[140:143], v[44:47]
	v_mfma_f32_16x16x32_bf16 v[40:43], v[216:219], v[140:143], v[40:43]
	v_mfma_f32_16x16x32_bf16 v[40:43], v[212:215], v[136:139], v[40:43]
	v_mfma_f32_16x16x32_bf16 v[48:51], v[212:215], v[144:147], v[48:51]
	v_mfma_f32_16x16x32_bf16 v[48:51], v[216:219], v[148:151], v[48:51]
	v_mfma_f32_16x16x32_bf16 v[52:55], v[224:227], v[148:151], v[52:55]
	v_mfma_f32_16x16x32_bf16 v[52:55], v[220:223], v[144:147], v[52:55]
	v_mfma_f32_16x16x32_bf16 v[60:63], v[220:223], v[152:155], v[60:63]
	v_mfma_f32_16x16x32_bf16 v[60:63], v[224:227], v[156:159], v[60:63]
	v_mfma_f32_16x16x32_bf16 v[56:59], v[216:219], v[156:159], v[56:59]
	v_mfma_f32_16x16x32_bf16 v[56:59], v[212:215], v[152:155], v[56:59]
	s_waitcnt vmcnt(8)
	s_waitcnt lgkmcnt(0)
	s_barrier
	v_mfma_f32_16x16x32_bf16 v[96:99], v[212:215], v[160:163], v[96:99]
	s_add_i32 m0, s35, 0x4000
	v_mfma_f32_16x16x32_bf16 v[96:99], v[216:219], v[164:167], v[96:99]
	global_load_lds_dwordx4 v249, s[56:57]
	v_mfma_f32_16x16x32_bf16 v[100:103], v[224:227], v[164:167], v[100:103]
	s_add_i32 m0, s35, 0x6000
	v_mfma_f32_16x16x32_bf16 v[100:103], v[220:223], v[160:163], v[100:103]
	global_load_lds_dwordx4 v250, s[56:57]
	v_mfma_f32_16x16x32_bf16 v[108:111], v[220:223], v[168:171], v[108:111]
	s_add_i32 m0, s35, 0x14000
	v_mfma_f32_16x16x32_bf16 v[108:111], v[224:227], v[172:175], v[108:111]
	global_load_lds_dwordx4 v251, s[58:59]
	v_mfma_f32_16x16x32_bf16 v[104:107], v[216:219], v[172:175], v[104:107]
	s_add_i32 m0, s35, 0x16000
	v_mfma_f32_16x16x32_bf16 v[104:107], v[212:215], v[168:171], v[104:107]
	global_load_lds_dwordx4 v252, s[58:59]
	v_mfma_f32_16x16x32_bf16 v[112:115], v[212:215], v[176:179], v[112:115]
	ds_read_b128 v[128:131], v245 offset:32768
	v_mfma_f32_16x16x32_bf16 v[112:115], v[216:219], v[180:183], v[112:115]
	ds_read_b128 v[132:135], v246 offset:32768
	v_mfma_f32_16x16x32_bf16 v[116:119], v[224:227], v[180:183], v[116:119]
	ds_read_b128 v[136:139], v245 offset:34816
	v_mfma_f32_16x16x32_bf16 v[116:119], v[220:223], v[176:179], v[116:119]
	ds_read_b128 v[140:143], v246 offset:34816
	v_mfma_f32_16x16x32_bf16 v[124:127], v[220:223], v[188:191], v[124:127]
	ds_read_b128 v[144:147], v245 offset:36864
	v_mfma_f32_16x16x32_bf16 v[124:127], v[224:227], v[192:195], v[124:127]
	ds_read_b128 v[148:151], v246 offset:36864
	v_mfma_f32_16x16x32_bf16 v[120:123], v[216:219], v[192:195], v[120:123]
	ds_read_b128 v[152:155], v245 offset:38912
	v_mfma_f32_16x16x32_bf16 v[120:123], v[212:215], v[188:191], v[120:123]
	ds_read_b128 v[156:159], v246 offset:38912
	v_mfma_f32_16x16x32_bf16 v[64:67], v[196:199], v[160:163], v[64:67]
	ds_read_b128 v[212:215], v247 offset:49152
	v_mfma_f32_16x16x32_bf16 v[64:67], v[200:203], v[164:167], v[64:67]
	ds_read_b128 v[216:219], v248 offset:49152
	v_mfma_f32_16x16x32_bf16 v[68:71], v[208:211], v[164:167], v[68:71]
	ds_read_b128 v[220:223], v247 offset:51200
	v_mfma_f32_16x16x32_bf16 v[68:71], v[204:207], v[160:163], v[68:71]
	ds_read_b128 v[224:227], v248 offset:51200
	v_mfma_f32_16x16x32_bf16 v[76:79], v[204:207], v[168:171], v[76:79]
	s_add_u32 s30, s30, s4
	s_addc_u32 s31, s31, s5
	v_mfma_f32_16x16x32_bf16 v[76:79], v[208:211], v[172:175], v[76:79]
	s_add_u32 s56, s56, s4
	s_addc_u32 s57, s57, s5
	v_mfma_f32_16x16x32_bf16 v[72:75], v[200:203], v[172:175], v[72:75]
	s_add_u32 s32, s32, s4
	s_addc_u32 s33, s33, s5
	v_mfma_f32_16x16x32_bf16 v[72:75], v[196:199], v[168:171], v[72:75]
	s_add_u32 s58, s58, s4
	s_addc_u32 s59, s59, s5
	v_mfma_f32_16x16x32_bf16 v[80:83], v[196:199], v[176:179], v[80:83]
	v_mfma_f32_16x16x32_bf16 v[80:83], v[200:203], v[180:183], v[80:83]
	v_mfma_f32_16x16x32_bf16 v[84:87], v[208:211], v[180:183], v[84:87]
	v_mfma_f32_16x16x32_bf16 v[84:87], v[204:207], v[176:179], v[84:87]
	v_mfma_f32_16x16x32_bf16 v[92:95], v[204:207], v[188:191], v[92:95]
	v_mfma_f32_16x16x32_bf16 v[92:95], v[208:211], v[192:195], v[92:95]
	v_mfma_f32_16x16x32_bf16 v[88:91], v[200:203], v[192:195], v[88:91]
	v_mfma_f32_16x16x32_bf16 v[88:91], v[196:199], v[188:191], v[88:91]
	s_waitcnt vmcnt(8)
	s_waitcnt lgkmcnt(0)
	s_barrier
; #define PG8_STAGE(bufoff, gbase, voff) do { _Pragma("unroll") for (int _i = 0; _i < 2; ++_i) \
;         __builtin_amdgcn_global_load_lds((const unsigned*)((const char*)(gbase) + (voff)[_i]), (PG8_LAS unsigned*)(lds + (bufoff) + ldsw + _i * 8192), 16, 0, 0); } while (0)
; #define PG8_LDA(dst, b, h) do { _Pragma("unroll") for (int m = 0; m < 4; ++m) _Pragma("unroll") for (int k = 0; k < 2; ++k) dst[m][k] = *(const PG8_LAS bf16x8*)(lds + PG8_SA(b, h) + aoff + m * 2048 + k * 1024); } while (0)
; #define PG8_LDB(dst, b, h) do { _Pragma("unroll") for (int n = 0; n < 2; ++n) _Pragma("unroll") for (int k = 0; k < 2; ++k) dst[n][k] = *(const PG8_LAS bf16x8*)(lds + PG8_SB(b, h) + boff + n * 2048 + k * 1024); } while (0)
; #define PG8_MMA(ai, bj, At, Bt) do { __builtin_amdgcn_s_setprio(1); _Pragma("unroll") for (int m = 0; m < 4; ++m) _Pragma("unroll") for (int n = 0; n < 2; ++n) _Pragma("unroll") for (int k = 0; k < 2; ++k) \
;         acc[ai][bj][m][n] = __builtin_amdgcn_mfma_f32_16x16x32_bf16(Bt[n][k], At[m][k], acc[ai][bj][m][n], 0, 0, 0); __builtin_amdgcn_s_setprio(0); } while (0)
; #define PG8_WAIT_V(n) asm volatile("s_waitcnt vmcnt(" #n ")" ::: "memory")
; #define PG8_WAIT_L(n) asm volatile("s_waitcnt lgkmcnt(" #n ")" ::: "memory")
; #define PG8_BAR __builtin_amdgcn_s_barrier()
; #define PG8_SCHED __builtin_amdgcn_sched_barrier(0)
; template <class Epi, class Sched, bool ALIGN_EPI = false, bool SP2 = false>
; __device__ __forceinline__ void gemm_phase(PG8_LAS unsigned char* lds, const Gemm g, const Sched& S, const Epi& E) {
;     ...
;             const char* a2 = last ? nA : cA + (size_t)(t + 2) * kstep; const char* b2 = last ? nB : cB + (size_t)(t + 2) * kstep;
;     ...
;             PG8_LDB(B0, 1, 0); PG8_LDB(B1, 1, 1); PG8_SCHED; PG8_LDA(At, 1, 0); PG8_STAGE(PG8_SA(0, 1), a2 + hstep, voffA);
;             PG8_WAIT_V(8); PG8_WAIT_L(0); PG8_BAR; PG8_MMA(0, 0, At, B0); PG8_MMA(0, 1, At, B1); PG8_BAR; PG8_SCHED;
;             PG8_LDA(At, 1, 1); PG8_STAGE(PG8_SB(1, 0), b3, voffB); PG8_STAGE(PG8_SB(1, 1), b3 + hstep, voffB); PG8_STAGE(PG8_SA(1, 0), a3, voffA);
;             PG8_WAIT_V(8); PG8_WAIT_L(0); PG8_BAR; PG8_MMA(1, 0, At, B0); PG8_MMA(1, 1, At, B1); PG8_BAR; PG8_SCHED;
	v_mfma_f32_16x16x32_bf16 v[32:35], v[212:215], v[128:131], v[32:35]
	ds_read_b128 v[196:199], v247 offset:32768
	v_mfma_f32_16x16x32_bf16 v[32:35], v[216:219], v[132:135], v[32:35]
	ds_read_b128 v[200:203], v248 offset:32768
	v_mfma_f32_16x16x32_bf16 v[36:39], v[224:227], v[132:135], v[36:39]
	ds_read_b128 v[204:207], v247 offset:34816
	v_mfma_f32_16x16x32_bf16 v[36:39], v[220:223], v[128:131], v[36:39]
	ds_read_b128 v[208:211], v248 offset:34816
	v_mfma_f32_16x16x32_bf16 v[44:47], v[220:223], v[136:139], v[44:47]
	s_add_i32 m0, s35, 0x8000
	v_mfma_f32_16x16x32_bf16 v[44:47], v[224:227], v[140:143], v[44:47]
	global_load_lds_dwordx4 v249, s[30:31]
	v_mfma_f32_16x16x32_bf16 v[40:43], v[216:219], v[140:143], v[40:43]
	s_add_i32 m0, s35, 0xa000
	v_mfma_f32_16x16x32_bf16 v[40:43], v[212:215], v[136:139], v[40:43]
	global_load_lds_dwordx4 v250, s[30:31]
	v_mfma_f32_16x16x32_bf16 v[48:51], v[212:215], v[144:147], v[48:51]
	s_add_i32 m0, s35, 0x1c000
	v_mfma_f32_16x16x32_bf16 v[48:51], v[216:219], v[148:151], v[48:51]
	global_load_lds_dwordx4 v251, s[58:59]
	v_mfma_f32_16x16x32_bf16 v[52:55], v[224:227], v[148:151], v[52:55]
	s_add_i32 m0, s35, 0x1e000
	v_mfma_f32_16x16x32_bf16 v[52:55], v[220:223], v[144:147], v[52:55]
	global_load_lds_dwordx4 v252, s[58:59]
	v_mfma_f32_16x16x32_bf16 v[60:63], v[220:223], v[152:155], v[60:63]
	ds_read_b128 v[160:163], v245 offset:49152
	v_mfma_f32_16x16x32_bf16 v[60:63], v[224:227], v[156:159], v[60:63]
	ds_read_b128 v[164:167], v246 offset:49152
	v_mfma_f32_16x16x32_bf16 v[56:59], v[216:219], v[156:159], v[56:59]
	ds_read_b128 v[168:171], v245 offset:51200
	v_mfma_f32_16x16x32_bf16 v[56:59], v[212:215], v[152:155], v[56:59]
	ds_read_b128 v[172:175], v246 offset:51200
	s_waitcnt lgkmcnt(4)
	v_mfma_f32_16x16x32_bf16 v[0:3], v[196:199], v[128:131], v[0:3]
	ds_read_b128 v[176:179], v245 offset:53248
	v_mfma_f32_16x16x32_bf16 v[0:3], v[200:203], v[132:135], v[0:3]
	ds_read_b128 v[180:183], v246 offset:53248
	v_mfma_f32_16x16x32_bf16 v[4:7], v[208:211], v[132:135], v[4:7]
	ds_read_b128 v[188:191], v245 offset:55296
	v_mfma_f32_16x16x32_bf16 v[4:7], v[204:207], v[128:131], v[4:7]
	ds_read_b128 v[192:195], v246 offset:55296
	v_mfma_f32_16x16x32_bf16 v[12:15], v[204:207], v[136:139], v[12:15]
	v_mfma_f32_16x16x32_bf16 v[12:15], v[208:211], v[140:143], v[12:15]
	v_mfma_f32_16x16x32_bf16 v[8:11], v[200:203], v[140:143], v[8:11]
	v_mfma_f32_16x16x32_bf16 v[8:11], v[196:199], v[136:139], v[8:11]
	v_mfma_f32_16x16x32_bf16 v[16:19], v[196:199], v[144:147], v[16:19]
	v_mfma_f32_16x16x32_bf16 v[16:19], v[200:203], v[148:151], v[16:19]
	v_mfma_f32_16x16x32_bf16 v[20:23], v[208:211], v[148:151], v[20:23]
	v_mfma_f32_16x16x32_bf16 v[20:23], v[204:207], v[144:147], v[20:23]
	v_mfma_f32_16x16x32_bf16 v[28:31], v[204:207], v[152:155], v[28:31]
	v_mfma_f32_16x16x32_bf16 v[28:31], v[208:211], v[156:159], v[28:31]
	v_mfma_f32_16x16x32_bf16 v[24:27], v[200:203], v[156:159], v[24:27]
	v_mfma_f32_16x16x32_bf16 v[24:27], v[196:199], v[152:155], v[24:27]
	s_waitcnt vmcnt(8)
	s_waitcnt lgkmcnt(0)
	s_barrier
	v_mfma_f32_16x16x32_bf16 v[64:67], v[196:199], v[160:163], v[64:67]
	s_add_i32 m0, s35, 0xc000
	v_mfma_f32_16x16x32_bf16 v[64:67], v[200:203], v[164:167], v[64:67]
	global_load_lds_dwordx4 v249, s[56:57]
	v_mfma_f32_16x16x32_bf16 v[68:71], v[208:211], v[164:167], v[68:71]
	s_add_i32 m0, s35, 0xe000
	v_mfma_f32_16x16x32_bf16 v[68:71], v[204:207], v[160:163], v[68:71]
	global_load_lds_dwordx4 v250, s[56:57]
	v_mfma_f32_16x16x32_bf16 v[76:79], v[204:207], v[168:171], v[76:79]
	s_add_i32 m0, s35, 0x18000
	v_mfma_f32_16x16x32_bf16 v[76:79], v[208:211], v[172:175], v[76:79]
	global_load_lds_dwordx4 v251, s[32:33]
	v_mfma_f32_16x16x32_bf16 v[72:75], v[200:203], v[172:175], v[72:75]
	s_add_i32 m0, s35, 0x1a000
	v_mfma_f32_16x16x32_bf16 v[72:75], v[196:199], v[168:171], v[72:75]
	global_load_lds_dwordx4 v252, s[32:33]
	v_mfma_f32_16x16x32_bf16 v[80:83], v[196:199], v[176:179], v[80:83]
	ds_read_b128 v[128:131], v245 offset:0
	v_mfma_f32_16x16x32_bf16 v[80:83], v[200:203], v[180:183], v[80:83]
	ds_read_b128 v[132:135], v246 offset:0
	v_mfma_f32_16x16x32_bf16 v[84:87], v[208:211], v[180:183], v[84:87]
	ds_read_b128 v[136:139], v245 offset:2048
	v_mfma_f32_16x16x32_bf16 v[84:87], v[204:207], v[176:179], v[84:87]
	ds_read_b128 v[140:143], v246 offset:2048
	v_mfma_f32_16x16x32_bf16 v[92:95], v[204:207], v[188:191], v[92:95]
	ds_read_b128 v[144:147], v245 offset:4096
	v_mfma_f32_16x16x32_bf16 v[92:95], v[208:211], v[192:195], v[92:95]
	ds_read_b128 v[148:151], v246 offset:4096
	v_mfma_f32_16x16x32_bf16 v[88:91], v[200:203], v[192:195], v[88:91]
	ds_read_b128 v[152:155], v245 offset:6144
	v_mfma_f32_16x16x32_bf16 v[88:91], v[196:199], v[188:191], v[88:91]
	ds_read_b128 v[156:159], v246 offset:6144
	v_mfma_f32_16x16x32_bf16 v[96:99], v[212:215], v[160:163], v[96:99]
	ds_read_b128 v[196:199], v247 offset:0
	v_mfma_f32_16x16x32_bf16 v[96:99], v[216:219], v[164:167], v[96:99]
	ds_read_b128 v[200:203], v248 offset:0
	v_mfma_f32_16x16x32_bf16 v[100:103], v[224:227], v[164:167], v[100:103]
	ds_read_b128 v[204:207], v247 offset:2048
	v_mfma_f32_16x16x32_bf16 v[100:103], v[220:223], v[160:163], v[100:103]
	ds_read_b128 v[208:211], v248 offset:2048
	v_mfma_f32_16x16x32_bf16 v[108:111], v[220:223], v[168:171], v[108:111]
	s_add_u32 s30, s30, s4
	s_addc_u32 s31, s31, s5
	v_mfma_f32_16x16x32_bf16 v[108:111], v[224:227], v[172:175], v[108:111]
	s_add_u32 s56, s56, s4
	s_addc_u32 s57, s57, s5
	v_mfma_f32_16x16x32_bf16 v[104:107], v[216:219], v[172:175], v[104:107]
	s_add_u32 s32, s32, s4
	s_addc_u32 s33, s33, s5
	v_mfma_f32_16x16x32_bf16 v[104:107], v[212:215], v[168:171], v[104:107]
	s_add_u32 s58, s58, s4
	s_addc_u32 s59, s59, s5
	v_mfma_f32_16x16x32_bf16 v[112:115], v[212:215], v[176:179], v[112:115]
	v_mfma_f32_16x16x32_bf16 v[112:115], v[216:219], v[180:183], v[112:115]
	v_mfma_f32_16x16x32_bf16 v[116:119], v[224:227], v[180:183], v[116:119]
	v_mfma_f32_16x16x32_bf16 v[116:119], v[220:223], v[176:179], v[116:119]
	v_mfma_f32_16x16x32_bf16 v[124:127], v[220:223], v[188:191], v[124:127]
	v_mfma_f32_16x16x32_bf16 v[124:127], v[224:227], v[192:195], v[124:127]
	v_mfma_f32_16x16x32_bf16 v[120:123], v[216:219], v[192:195], v[120:123]
	v_mfma_f32_16x16x32_bf16 v[120:123], v[212:215], v[188:191], v[120:123]
	s_add_i32 s34, s34, -1
	s_cmp_lg_u32 s34, 1
	s_cbranch_scc1 .Lp5_nosw0
	s_add_u32 s45, s16, 1
	s_and_b32 s40, s45, 1
	s_lshl_b32 s4, s40, 8
	s_sub_u32 s4, 128, s4
	s_sub_u32 s5, 0, s40
	s_mul_i32 s8, s40, 3968
	s_add_u32 s30, s26, s8
	s_addc_u32 s31, s27, 0
	s_add_u32 s32, s28, s8
	s_addc_u32 s33, s29, 0
	s_add_u32 s56, s30, 0x80000
	s_addc_u32 s57, s31, 0
	s_add_u32 s58, s32, 0x80000
	s_addc_u32 s59, s33, 0

; #define PG8_STAGE(bufoff, gbase, voff) do { _Pragma("unroll") for (int _i = 0; _i < 2; ++_i) \
;         __builtin_amdgcn_global_load_lds((const unsigned*)((const char*)(gbase) + (voff)[_i]), (PG8_LAS unsigned*)(lds + (bufoff) + ldsw + _i * 8192), 16, 0, 0); } while (0)
; #define PG8_LDA(dst, b, h) do { _Pragma("unroll") for (int m = 0; m < 4; ++m) _Pragma("unroll") for (int k = 0; k < 2; ++k) dst[m][k] = *(const PG8_LAS bf16x8*)(lds + PG8_SA(b, h) + aoff + m * 2048 + k * 1024); } while (0)
; #define PG8_LDB(dst, b, h) do { _Pragma("unroll") for (int n = 0; n < 2; ++n) _Pragma("unroll") for (int k = 0; k < 2; ++k) dst[n][k] = *(const PG8_LAS bf16x8*)(lds + PG8_SB(b, h) + boff + n * 2048 + k * 1024); } while (0)
; #define PG8_MMA(ai, bj, At, Bt) do { __builtin_amdgcn_s_setprio(1); _Pragma("unroll") for (int m = 0; m < 4; ++m) _Pragma("unroll") for (int n = 0; n < 2; ++n) _Pragma("unroll") for (int k = 0; k < 2; ++k) \
;         acc[ai][bj][m][n] = __builtin_amdgcn_mfma_f32_16x16x32_bf16(Bt[n][k], At[m][k], acc[ai][bj][m][n], 0, 0, 0); __builtin_amdgcn_s_setprio(0); } while (0)
; #define PG8_WAIT_V(n) asm volatile("s_waitcnt vmcnt(" #n ")" ::: "memory")
; #define PG8_WAIT_L(n) asm volatile("s_waitcnt lgkmcnt(" #n ")" ::: "memory")
; #define PG8_BAR __builtin_amdgcn_s_barrier()
; #define PG8_SCHED __builtin_amdgcn_sched_barrier(0)
; template <class Epi, class Sched, bool ALIGN_EPI = false, bool SP2 = false>
; __device__ __forceinline__ void gemm_phase(PG8_LAS unsigned char* lds, const Gemm g, const Sched& S, const Epi& E) {
;     ...
;             PG8_LDB(B0, 0, 0); PG8_LDB(B1, 0, 1); PG8_SCHED; PG8_LDA(At, 0, 0); PG8_STAGE(PG8_SA(1, 1), a1 + hstep, voffA);
;             PG8_WAIT_V(8); PG8_WAIT_L(0); PG8_BAR; PG8_MMA(0, 0, At, B0); PG8_MMA(0, 1, At, B1); PG8_BAR; PG8_SCHED;
;             PG8_LDA(At, 0, 1); PG8_STAGE(PG8_SB(0, 0), b2, voffB); PG8_STAGE(PG8_SB(0, 1), b2 + hstep, voffB); PG8_STAGE(PG8_SA(0, 0), a2, voffA);
;             PG8_WAIT_V(8); PG8_WAIT_L(0); PG8_BAR; PG8_MMA(1, 0, At, B0); PG8_MMA(1, 1, At, B1); PG8_BAR; PG8_SCHED;
;             PG8_LDB(B0, 1, 0); PG8_LDB(B1, 1, 1); PG8_SCHED; PG8_LDA(At, 1, 0); PG8_STAGE(PG8_SA(0, 1), a2 + hstep, voffA);
;             PG8_WAIT_V(8); PG8_WAIT_L(0); PG8_BAR; PG8_MMA(0, 0, At, B0); PG8_MMA(0, 1, At, B1); PG8_BAR; PG8_SCHED;
.Lp5_kloop1:
	s_waitcnt vmcnt(8)
	s_waitcnt lgkmcnt(0)
	s_barrier
	v_mfma_f32_16x16x32_bf16 v[0:3], v[196:199], v[128:131], v[0:3]
	ds_read_b128 v[212:215], v247 offset:16384
	v_mfma_f32_16x16x32_bf16 v[0:3], v[200:203], v[132:135], v[0:3]
	ds_read_b128 v[216:219], v248 offset:16384
	v_mfma_f32_16x16x32_bf16 v[4:7], v[208:211], v[132:135], v[4:7]
	ds_read_b128 v[220:223], v247 offset:18432
	v_mfma_f32_16x16x32_bf16 v[4:7], v[204:207], v[128:131], v[4:7]
	ds_read_b128 v[224:227], v248 offset:18432
	v_mfma_f32_16x16x32_bf16 v[12:15], v[204:207], v[136:139], v[12:15]
	ds_read_b128 v[160:163], v245 offset:16384
	v_mfma_f32_16x16x32_bf16 v[12:15], v[208:211], v[140:143], v[12:15]
	ds_read_b128 v[164:167], v246 offset:16384
	v_mfma_f32_16x16x32_bf16 v[8:11], v[200:203], v[140:143], v[8:11]
	ds_read_b128 v[168:171], v245 offset:18432
	v_mfma_f32_16x16x32_bf16 v[8:11], v[196:199], v[136:139], v[8:11]
	ds_read_b128 v[172:175], v246 offset:18432
	v_mfma_f32_16x16x32_bf16 v[16:19], v[196:199], v[144:147], v[16:19]
	ds_read_b128 v[176:179], v245 offset:20480
	v_mfma_f32_16x16x32_bf16 v[16:19], v[200:203], v[148:151], v[16:19]
	ds_read_b128 v[180:183], v246 offset:20480
	v_mfma_f32_16x16x32_bf16 v[20:23], v[208:211], v[148:151], v[20:23]
	ds_read_b128 v[188:191], v245 offset:22528
	v_mfma_f32_16x16x32_bf16 v[20:23], v[204:207], v[144:147], v[20:23]
	ds_read_b128 v[192:195], v246 offset:22528
	v_mfma_f32_16x16x32_bf16 v[28:31], v[204:207], v[152:155], v[28:31]
	v_mfma_f32_16x16x32_bf16 v[28:31], v[208:211], v[156:159], v[28:31]
	v_mfma_f32_16x16x32_bf16 v[24:27], v[200:203], v[156:159], v[24:27]
	v_mfma_f32_16x16x32_bf16 v[24:27], v[196:199], v[152:155], v[24:27]
	s_waitcnt lgkmcnt(8)
	v_mfma_f32_16x16x32_bf16 v[32:35], v[212:215], v[128:131], v[32:35]
	v_mfma_f32_16x16x32_bf16 v[32:35], v[216:219], v[132:135], v[32:35]
	s_add_i32 m0, s35, 0x0
	v_mfma_f32_16x16x32_bf16 v[36:39], v[224:227], v[132:135], v[36:39]
	global_load_lds_dwordx4 v249, s[30:31]
	v_mfma_f32_16x16x32_bf16 v[36:39], v[220:223], v[128:131], v[36:39]
	v_mfma_f32_16x16x32_bf16 v[44:47], v[220:223], v[136:139], v[44:47]
	s_add_i32 m0, s35, 0x2000
	v_mfma_f32_16x16x32_bf16 v[44:47], v[224:227], v[140:143], v[44:47]
	global_load_lds_dwordx4 v250, s[30:31]
	v_mfma_f32_16x16x32_bf16 v[40:43], v[216:219], v[140:143], v[40:43]
	v_mfma_f32_16x16x32_bf16 v[40:43], v[212:215], v[136:139], v[40:43]
	s_add_i32 m0, s35, 0x10000
	v_mfma_f32_16x16x32_bf16 v[48:51], v[212:215], v[144:147], v[48:51]
	global_load_lds_dwordx4 v251, s[32:33]
	v_mfma_f32_16x16x32_bf16 v[48:51], v[216:219], v[148:151], v[48:51]
	v_mfma_f32_16x16x32_bf16 v[52:55], v[224:227], v[148:151], v[52:55]
	s_add_i32 m0, s35, 0x12000
	v_mfma_f32_16x16x32_bf16 v[52:55], v[220:223], v[144:147], v[52:55]
	global_load_lds_dwordx4 v252, s[32:33]
	v_mfma_f32_16x16x32_bf16 v[60:63], v[220:223], v[152:155], v[60:63]
	v_mfma_f32_16x16x32_bf16 v[60:63], v[224:227], v[156:159], v[60:63]
	v_mfma_f32_16x16x32_bf16 v[56:59], v[216:219], v[156:159], v[56:59]
	v_mfma_f32_16x16x32_bf16 v[56:59], v[212:215], v[152:155], v[56:59]
	s_waitcnt vmcnt(8)
	s_waitcnt lgkmcnt(0)
	s_barrier
	v_mfma_f32_16x16x32_bf16 v[96:99], v[212:215], v[160:163], v[96:99]
	ds_read_b128 v[128:131], v245 offset:32768
	v_mfma_f32_16x16x32_bf16 v[96:99], v[216:219], v[164:167], v[96:99]
	ds_read_b128 v[132:135], v246 offset:32768
	v_mfma_f32_16x16x32_bf16 v[100:103], v[224:227], v[164:167], v[100:103]
	ds_read_b128 v[136:139], v245 offset:34816
	v_mfma_f32_16x16x32_bf16 v[100:103], v[220:223], v[160:163], v[100:103]
	ds_read_b128 v[140:143], v246 offset:34816
	v_mfma_f32_16x16x32_bf16 v[108:111], v[220:223], v[168:171], v[108:111]
	ds_read_b128 v[144:147], v245 offset:36864
	v_mfma_f32_16x16x32_bf16 v[108:111], v[224:227], v[172:175], v[108:111]
	ds_read_b128 v[148:151], v246 offset:36864
	v_mfma_f32_16x16x32_bf16 v[104:107], v[216:219], v[172:175], v[104:107]
	ds_read_b128 v[152:155], v245 offset:38912
	v_mfma_f32_16x16x32_bf16 v[104:107], v[212:215], v[168:171], v[104:107]
	ds_read_b128 v[156:159], v246 offset:38912
	v_mfma_f32_16x16x32_bf16 v[112:115], v[212:215], v[176:179], v[112:115]
	v_mfma_f32_16x16x32_bf16 v[112:115], v[216:219], v[180:183], v[112:115]
	v_mfma_f32_16x16x32_bf16 v[116:119], v[224:227], v[180:183], v[116:119]
	v_mfma_f32_16x16x32_bf16 v[116:119], v[220:223], v[176:179], v[116:119]
	v_mfma_f32_16x16x32_bf16 v[124:127], v[220:223], v[188:191], v[124:127]
	v_mfma_f32_16x16x32_bf16 v[124:127], v[224:227], v[192:195], v[124:127]
	v_mfma_f32_16x16x32_bf16 v[120:123], v[216:219], v[192:195], v[120:123]
	v_mfma_f32_16x16x32_bf16 v[120:123], v[212:215], v[188:191], v[120:123]
	v_mfma_f32_16x16x32_bf16 v[64:67], v[196:199], v[160:163], v[64:67]
	ds_read_b128 v[212:215], v247 offset:49152
	v_mfma_f32_16x16x32_bf16 v[64:67], v[200:203], v[164:167], v[64:67]
	ds_read_b128 v[216:219], v248 offset:49152
	v_mfma_f32_16x16x32_bf16 v[68:71], v[208:211], v[164:167], v[68:71]
	ds_read_b128 v[220:223], v247 offset:51200
	v_mfma_f32_16x16x32_bf16 v[68:71], v[204:207], v[160:163], v[68:71]
	ds_read_b128 v[224:227], v248 offset:51200
	v_mfma_f32_16x16x32_bf16 v[76:79], v[204:207], v[168:171], v[76:79]
	s_add_i32 m0, s35, 0x4000
	v_mfma_f32_16x16x32_bf16 v[76:79], v[208:211], v[172:175], v[76:79]
	global_load_lds_dwordx4 v249, s[56:57]
	v_mfma_f32_16x16x32_bf16 v[72:75], v[200:203], v[172:175], v[72:75]
	s_add_i32 m0, s35, 0x6000
	v_mfma_f32_16x16x32_bf16 v[72:75], v[196:199], v[168:171], v[72:75]
	global_load_lds_dwordx4 v250, s[56:57]
	v_mfma_f32_16x16x32_bf16 v[80:83], v[196:199], v[176:179], v[80:83]
	s_add_i32 m0, s35, 0x14000
	v_mfma_f32_16x16x32_bf16 v[80:83], v[200:203], v[180:183], v[80:83]
	global_load_lds_dwordx4 v251, s[58:59]
	v_mfma_f32_16x16x32_bf16 v[84:87], v[208:211], v[180:183], v[84:87]
	s_add_i32 m0, s35, 0x16000
	v_mfma_f32_16x16x32_bf16 v[84:87], v[204:207], v[176:179], v[84:87]
	global_load_lds_dwordx4 v252, s[58:59]
	v_mfma_f32_16x16x32_bf16 v[92:95], v[204:207], v[188:191], v[92:95]
	s_add_u32 s30, s30, s4
	s_addc_u32 s31, s31, s5
	v_mfma_f32_16x16x32_bf16 v[92:95], v[208:211], v[192:195], v[92:95]
	s_add_u32 s56, s56, s4
	s_addc_u32 s57, s57, s5
	v_mfma_f32_16x16x32_bf16 v[88:91], v[200:203], v[192:195], v[88:91]
	s_add_u32 s32, s32, s4
	s_addc_u32 s33, s33, s5
	v_mfma_f32_16x16x32_bf16 v[88:91], v[196:199], v[188:191], v[88:91]
	s_add_u32 s58, s58, s4
	s_addc_u32 s59, s59, s5
	s_waitcnt vmcnt(8)
	s_waitcnt lgkmcnt(0)
	s_barrier
; #define PG8_STAGE(bufoff, gbase, voff) do { _Pragma("unroll") for (int _i = 0; _i < 2; ++_i) \
;         __builtin_amdgcn_global_load_lds((const unsigned*)((const char*)(gbase) + (voff)[_i]), (PG8_LAS unsigned*)(lds + (bufoff) + ldsw + _i * 8192), 16, 0, 0); } while (0)
; #define PG8_LDA(dst, b, h) do { _Pragma("unroll") for (int m = 0; m < 4; ++m) _Pragma("unroll") for (int k = 0; k < 2; ++k) dst[m][k] = *(const PG8_LAS bf16x8*)(lds + PG8_SA(b, h) + aoff + m * 2048 + k * 1024); } while (0)
; #define PG8_LDB(dst, b, h) do { _Pragma("unroll") for (int n = 0; n < 2; ++n) _Pragma("unroll") for (int k = 0; k < 2; ++k) dst[n][k] = *(const PG8_LAS bf16x8*)(lds + PG8_SB(b, h) + boff + n * 2048 + k * 1024); } while (0)
; #define PG8_MMA(ai, bj, At, Bt) do { __builtin_amdgcn_s_setprio(1); _Pragma("unroll") for (int m = 0; m < 4; ++m) _Pragma("unroll") for (int n = 0; n < 2; ++n) _Pragma("unroll") for (int k = 0; k < 2; ++k) \
;         acc[ai][bj][m][n] = __builtin_amdgcn_mfma_f32_16x16x32_bf16(Bt[n][k], At[m][k], acc[ai][bj][m][n], 0, 0, 0); __builtin_amdgcn_s_setprio(0); } while (0)
; #define PG8_WAIT_V(n) asm volatile("s_waitcnt vmcnt(" #n ")" ::: "memory")
; #define PG8_WAIT_L(n) asm volatile("s_waitcnt lgkmcnt(" #n ")" ::: "memory")
; #define PG8_BAR __builtin_amdgcn_s_barrier()
; #define PG8_SCHED __builtin_amdgcn_sched_barrier(0)
; template <class Epi, class Sched, bool ALIGN_EPI = false, bool SP2 = false>
; __device__ __forceinline__ void gemm_phase(PG8_LAS unsigned char* lds, const Gemm g, const Sched& S, const Epi& E) {
;     ...
;             PG8_LDB(B0, 1, 0); PG8_LDB(B1, 1, 1); PG8_SCHED; PG8_LDA(At, 1, 0); PG8_STAGE(PG8_SA(0, 1), a2 + hstep, voffA);
;             PG8_WAIT_V(8); PG8_WAIT_L(0); PG8_BAR; PG8_MMA(0, 0, At, B0); PG8_MMA(0, 1, At, B1); PG8_BAR; PG8_SCHED;
;             PG8_LDA(At, 1, 1); PG8_STAGE(PG8_SB(1, 0), b3, voffB); PG8_STAGE(PG8_SB(1, 1), b3 + hstep, voffB); PG8_STAGE(PG8_SA(1, 0), a3, voffA);
;             PG8_WAIT_V(8); PG8_WAIT_L(0); PG8_BAR; PG8_MMA(1, 0, At, B0); PG8_MMA(1, 1, At, B1); PG8_BAR; PG8_SCHED;
	v_mfma_f32_16x16x32_bf16 v[32:35], v[212:215], v[128:131], v[32:35]
	ds_read_b128 v[196:199], v247 offset:32768
	v_mfma_f32_16x16x32_bf16 v[32:35], v[216:219], v[132:135], v[32:35]
	ds_read_b128 v[200:203], v248 offset:32768
	v_mfma_f32_16x16x32_bf16 v[36:39], v[224:227], v[132:135], v[36:39]
	ds_read_b128 v[204:207], v247 offset:34816
	v_mfma_f32_16x16x32_bf16 v[36:39], v[220:223], v[128:131], v[36:39]
	ds_read_b128 v[208:211], v248 offset:34816
	v_mfma_f32_16x16x32_bf16 v[44:47], v[220:223], v[136:139], v[44:47]
	ds_read_b128 v[160:163], v245 offset:49152
	v_mfma_f32_16x16x32_bf16 v[44:47], v[224:227], v[140:143], v[44:47]
	ds_read_b128 v[164:167], v246 offset:49152
	v_mfma_f32_16x16x32_bf16 v[40:43], v[216:219], v[140:143], v[40:43]
	ds_read_b128 v[168:171], v245 offset:51200
	v_mfma_f32_16x16x32_bf16 v[40:43], v[212:215], v[136:139], v[40:43]
	ds_read_b128 v[172:175], v246 offset:51200
	v_mfma_f32_16x16x32_bf16 v[48:51], v[212:215], v[144:147], v[48:51]
	ds_read_b128 v[176:179], v245 offset:53248
	v_mfma_f32_16x16x32_bf16 v[48:51], v[216:219], v[148:151], v[48:51]
	ds_read_b128 v[180:183], v246 offset:53248
	v_mfma_f32_16x16x32_bf16 v[52:55], v[224:227], v[148:151], v[52:55]
	ds_read_b128 v[188:191], v245 offset:55296
	v_mfma_f32_16x16x32_bf16 v[52:55], v[220:223], v[144:147], v[52:55]
	ds_read_b128 v[192:195], v246 offset:55296
	v_mfma_f32_16x16x32_bf16 v[60:63], v[220:223], v[152:155], v[60:63]
	v_mfma_f32_16x16x32_bf16 v[60:63], v[224:227], v[156:159], v[60:63]
	v_mfma_f32_16x16x32_bf16 v[56:59], v[216:219], v[156:159], v[56:59]
	v_mfma_f32_16x16x32_bf16 v[56:59], v[212:215], v[152:155], v[56:59]
	s_waitcnt lgkmcnt(8)
	v_mfma_f32_16x16x32_bf16 v[0:3], v[196:199], v[128:131], v[0:3]
	v_mfma_f32_16x16x32_bf16 v[0:3], v[200:203], v[132:135], v[0:3]
	s_add_i32 m0, s35, 0x8000
	v_mfma_f32_16x16x32_bf16 v[4:7], v[208:211], v[132:135], v[4:7]
	global_load_lds_dwordx4 v249, s[30:31]
	v_mfma_f32_16x16x32_bf16 v[4:7], v[204:207], v[128:131], v[4:7]
	v_mfma_f32_16x16x32_bf16 v[12:15], v[204:207], v[136:139], v[12:15]
	s_add_i32 m0, s35, 0xa000
	v_mfma_f32_16x16x32_bf16 v[12:15], v[208:211], v[140:143], v[12:15]
	global_load_lds_dwordx4 v250, s[30:31]
	v_mfma_f32_16x16x32_bf16 v[8:11], v[200:203], v[140:143], v[8:11]
	v_mfma_f32_16x16x32_bf16 v[8:11], v[196:199], v[136:139], v[8:11]
	s_add_i32 m0, s35, 0x1c000
	v_mfma_f32_16x16x32_bf16 v[16:19], v[196:199], v[144:147], v[16:19]
	global_load_lds_dwordx4 v251, s[58:59]
	v_mfma_f32_16x16x32_bf16 v[16:19], v[200:203], v[148:151], v[16:19]
	v_mfma_f32_16x16x32_bf16 v[20:23], v[208:211], v[148:151], v[20:23]
	s_add_i32 m0, s35, 0x1e000
	v_mfma_f32_16x16x32_bf16 v[20:23], v[204:207], v[144:147], v[20:23]
	global_load_lds_dwordx4 v252, s[58:59]
	v_mfma_f32_16x16x32_bf16 v[28:31], v[204:207], v[152:155], v[28:31]
	v_mfma_f32_16x16x32_bf16 v[28:31], v[208:211], v[156:159], v[28:31]
	v_mfma_f32_16x16x32_bf16 v[24:27], v[200:203], v[156:159], v[24:27]
	v_mfma_f32_16x16x32_bf16 v[24:27], v[196:199], v[152:155], v[24:27]
	s_waitcnt vmcnt(8)
	s_waitcnt lgkmcnt(0)
	s_barrier
	v_mfma_f32_16x16x32_bf16 v[64:67], v[196:199], v[160:163], v[64:67]
	ds_read_b128 v[128:131], v245 offset:0
	v_mfma_f32_16x16x32_bf16 v[64:67], v[200:203], v[164:167], v[64:67]
	ds_read_b128 v[132:135], v246 offset:0
	v_mfma_f32_16x16x32_bf16 v[68:71], v[208:211], v[164:167], v[68:71]
	ds_read_b128 v[136:139], v245 offset:2048
	v_mfma_f32_16x16x32_bf16 v[68:71], v[204:207], v[160:163], v[68:71]
	ds_read_b128 v[140:143], v246 offset:2048
	v_mfma_f32_16x16x32_bf16 v[76:79], v[204:207], v[168:171], v[76:79]
	ds_read_b128 v[144:147], v245 offset:4096
	v_mfma_f32_16x16x32_bf16 v[76:79], v[208:211], v[172:175], v[76:79]
	ds_read_b128 v[148:151], v246 offset:4096
	v_mfma_f32_16x16x32_bf16 v[72:75], v[200:203], v[172:175], v[72:75]
	ds_read_b128 v[152:155], v245 offset:6144
	v_mfma_f32_16x16x32_bf16 v[72:75], v[196:199], v[168:171], v[72:75]
	ds_read_b128 v[156:159], v246 offset:6144
	v_mfma_f32_16x16x32_bf16 v[80:83], v[196:199], v[176:179], v[80:83]
	v_mfma_f32_16x16x32_bf16 v[80:83], v[200:203], v[180:183], v[80:83]
	v_mfma_f32_16x16x32_bf16 v[84:87], v[208:211], v[180:183], v[84:87]
	v_mfma_f32_16x16x32_bf16 v[84:87], v[204:207], v[176:179], v[84:87]
	v_mfma_f32_16x16x32_bf16 v[92:95], v[204:207], v[188:191], v[92:95]
	v_mfma_f32_16x16x32_bf16 v[92:95], v[208:211], v[192:195], v[92:95]
	v_mfma_f32_16x16x32_bf16 v[88:91], v[200:203], v[192:195], v[88:91]
	v_mfma_f32_16x16x32_bf16 v[88:91], v[196:199], v[188:191], v[88:91]
	v_mfma_f32_16x16x32_bf16 v[96:99], v[212:215], v[160:163], v[96:99]
	ds_read_b128 v[196:199], v247 offset:0
	v_mfma_f32_16x16x32_bf16 v[96:99], v[216:219], v[164:167], v[96:99]
	ds_read_b128 v[200:203], v248 offset:0
	v_mfma_f32_16x16x32_bf16 v[100:103], v[224:227], v[164:167], v[100:103]
	ds_read_b128 v[204:207], v247 offset:2048
	v_mfma_f32_16x16x32_bf16 v[100:103], v[220:223], v[160:163], v[100:103]
	ds_read_b128 v[208:211], v248 offset:2048
	v_mfma_f32_16x16x32_bf16 v[108:111], v[220:223], v[168:171], v[108:111]
	s_add_i32 m0, s35, 0xc000
	v_mfma_f32_16x16x32_bf16 v[108:111], v[224:227], v[172:175], v[108:111]
	global_load_lds_dwordx4 v249, s[56:57]
	v_mfma_f32_16x16x32_bf16 v[104:107], v[216:219], v[172:175], v[104:107]
	s_add_i32 m0, s35, 0xe000
	v_mfma_f32_16x16x32_bf16 v[104:107], v[212:215], v[168:171], v[104:107]
	global_load_lds_dwordx4 v250, s[56:57]
	v_mfma_f32_16x16x32_bf16 v[112:115], v[212:215], v[176:179], v[112:115]
	s_add_i32 m0, s35, 0x18000
	v_mfma_f32_16x16x32_bf16 v[112:115], v[216:219], v[180:183], v[112:115]
	global_load_lds_dwordx4 v251, s[32:33]
	v_mfma_f32_16x16x32_bf16 v[116:119], v[224:227], v[180:183], v[116:119]
	s_add_i32 m0, s35, 0x1a000
	v_mfma_f32_16x16x32_bf16 v[116:119], v[220:223], v[176:179], v[116:119]
	global_load_lds_dwordx4 v252, s[32:33]
	v_mfma_f32_16x16x32_bf16 v[124:127], v[220:223], v[188:191], v[124:127]
	s_add_u32 s30, s30, s4
	s_addc_u32 s31, s31, s5
	v_mfma_f32_16x16x32_bf16 v[124:127], v[224:227], v[192:195], v[124:127]
	s_add_u32 s56, s56, s4
	s_addc_u32 s57, s57, s5
	v_mfma_f32_16x16x32_bf16 v[120:123], v[216:219], v[192:195], v[120:123]
	s_add_u32 s32, s32, s4
	s_addc_u32 s33, s33, s5
	v_mfma_f32_16x16x32_bf16 v[120:123], v[212:215], v[188:191], v[120:123]
	s_add_u32 s58, s58, s4
	s_addc_u32 s59, s59, s5
	s_add_i32 s34, s34, -1
	s_cmp_lg_u32 s34, 1
	s_cbranch_scc1 .Lp5_nosw1
	s_add_u32 s45, s16, 1
	s_and_b32 s40, s45, 1
	s_lshl_b32 s4, s40, 8
	s_sub_u32 s4, 128, s4
	s_sub_u32 s5, 0, s40
	s_mul_i32 s8, s40, 3968
	s_add_u32 s30, s26, s8
	s_addc_u32 s31, s27, 0
	s_add_u32 s32, s28, s8
	s_addc_u32 s33, s29, 0
	s_add_u32 s56, s30, 0x80000
	s_addc_u32 s57, s31, 0
	s_add_u32 s58, s32, 0x80000
	s_addc_u32 s59, s33, 0

; __device__ __forceinline__ unsigned cvt_pk_bf16(float lo, float hi) { unsigned r; asm volatile("v_cvt_pk_bf16_f32 %0, %1, %2" : "=v"(r) : "v"(lo), "v"(hi)); return r; }
;     __device__ __forceinline__ void operator()(const f32x4 (&acc)[2][2][4][2], const Unit& u, int wr, int wc, int fr, int fq) const {
;         const int row0 = u.pm * BM + wr * 64 + fr, col0 = u.pn * HALF + wc * 32 + 8 * fq;
;         float rsv[2][4];
; #pragma unroll
;         for (int ai = 0; ai < 2; ++ai)
; #pragma unroll
;             for (int m = 0; m < 4; ++m) rsv[ai][m] = ss[row0 + ai * HALF + m * 16];
;         asm volatile("" ::: "memory");
; #pragma unroll
;         for (int ai = 0; ai < 2; ++ai)
; #pragma unroll
;             for (int m = 0; m < 4; ++m) { const int row = row0 + ai * HALF + m * 16; const float rs = __builtin_amdgcn_rsqf(rsv[ai][m] * inv_n + eps);
;                 float a[8];
; #pragma unroll
;                 for (int n = 0; n < 2; ++n)
; #pragma unroll
;                     for (int i = 0; i < 4; ++i) { const float g = acc[ai][0][m][n][i] * rs, up = acc[ai][1][m][n][i] * rs;
;                         a[n * 4 + i] = g * __builtin_amdgcn_rcpf(1.0f + __builtin_amdgcn_exp2f(-1.4426950408889634f * g)) * up; }
;                 u32x4 w; w.x = cvt_pk_bf16(a[0], a[1]); w.y = cvt_pk_bf16(a[2], a[3]); w.z = cvt_pk_bf16(a[4], a[5]); w.w = cvt_pk_bf16(a[6], a[7]);
;                 *(u32x4*)(O + (size_t)row * ldc + col0) = w; }
.Lp5_kdone:
	s_waitcnt lgkmcnt(0)
	s_nop 7
	s_nop 7
	v_and_b32_e32 v254, 63, v185
	v_and_b32_e32 v255, 15, v254
	v_lshrrev_b32_e32 v186, 4, v254
	s_lshl_b32 s40, s37, 6
	v_add_u32_e32 v255, s40, v255
	v_lshlrev_b32_e32 v128, 2, v255
	v_mul_u32_u24_e32 v129, 0x2c00, v255
	s_lshl_b32 s41, s38, 6
	v_lshl_add_u32 v129, v186, 4, v129
	v_add_u32_e32 v129, s41, v129
	v_mov_b32_e32 v130, 0x358637bd
	s_lshl_b32 s40, s17, 10
	s_add_u32 s48, s76, s40
	s_addc_u32 s49, s77, 0
	s_mul_i32 s40, s17, 0x2c0000
	s_lshl_b32 s41, s18, 8
	s_add_u32 s40, s40, s41
	s_add_u32 s50, s76, 0xa800000
	s_addc_u32 s51, s77, 0
	s_add_u32 s50, s50, s40
	s_addc_u32 s51, s51, 0
	global_load_dword v134, v128, s[48:49] offset:0
	global_load_dword v135, v128, s[48:49] offset:64
	global_load_dword v136, v128, s[48:49] offset:128
	global_load_dword v137, v128, s[48:49] offset:192
	global_load_dword v138, v128, s[48:49] offset:512
	global_load_dword v139, v128, s[48:49] offset:576
	global_load_dword v140, v128, s[48:49] offset:640
	global_load_dword v141, v128, s[48:49] offset:704
	s_waitcnt vmcnt(0)
	v_fmamk_f32 v131, v134, 0x3a000000, v130
	v_add_u32_e32 v132, 0x0, v129
	v_rsq_f32_e32 v131, v131
	s_nop 0
	v_mul_f32_e32 v0, v0, v131
	v_mul_f32_e32 v1, v1, v131
	v_mul_f32_e32 v2, v2, v131
	v_mul_f32_e32 v3, v3, v131
	v_mul_f32_e32 v4, v4, v131
	v_mul_f32_e32 v5, v5, v131
	v_mul_f32_e32 v6, v6, v131
	v_mul_f32_e32 v7, v7, v131
	v_mul_f32_e32 v32, v32, v131
	v_mul_f32_e32 v33, v33, v131
	v_mul_f32_e32 v34, v34, v131
	v_mul_f32_e32 v35, v35, v131
	v_mul_f32_e32 v36, v36, v131
	v_mul_f32_e32 v37, v37, v131
	v_mul_f32_e32 v38, v38, v131
	v_mul_f32_e32 v39, v39, v131
	v_mul_f32_e32 v144, 0xbfb8aa3b, v0
	v_mul_f32_e32 v145, 0xbfb8aa3b, v1
	v_mul_f32_e32 v146, 0xbfb8aa3b, v2
	v_mul_f32_e32 v147, 0xbfb8aa3b, v3
	v_mul_f32_e32 v148, 0xbfb8aa3b, v4
	v_mul_f32_e32 v149, 0xbfb8aa3b, v5
	v_mul_f32_e32 v150, 0xbfb8aa3b, v6
	v_mul_f32_e32 v151, 0xbfb8aa3b, v7
	v_exp_f32_e32 v144, v144
	v_exp_f32_e32 v145, v145
	v_exp_f32_e32 v146, v146
	v_exp_f32_e32 v147, v147
	v_exp_f32_e32 v148, v148
	v_exp_f32_e32 v149, v149
	v_exp_f32_e32 v150, v150
	v_exp_f32_e32 v151, v151
	v_add_f32_e32 v144, 1.0, v144
	v_add_f32_e32 v145, 1.0, v145
	v_add_f32_e32 v146, 1.0, v146
	v_add_f32_e32 v147, 1.0, v147
	v_add_f32_e32 v148, 1.0, v148
	v_add_f32_e32 v149, 1.0, v149
	v_add_f32_e32 v150, 1.0, v150
	v_add_f32_e32 v151, 1.0, v151
	v_rcp_f32_e32 v144, v144
	v_rcp_f32_e32 v145, v145
	v_rcp_f32_e32 v146, v146
	v_rcp_f32_e32 v147, v147
	v_rcp_f32_e32 v148, v148
	v_rcp_f32_e32 v149, v149
	v_rcp_f32_e32 v150, v150
	v_rcp_f32_e32 v151, v151
	v_mul_f32_e32 v0, v0, v144
	v_mul_f32_e32 v1, v1, v145
	v_mul_f32_e32 v2, v2, v146
	v_mul_f32_e32 v3, v3, v147
	v_mul_f32_e32 v4, v4, v148
	v_mul_f32_e32 v5, v5, v149
	v_mul_f32_e32 v6, v6, v150
	v_mul_f32_e32 v7, v7, v151
	v_mul_f32_e32 v0, v32, v0
	v_mul_f32_e32 v1, v33, v1
	v_mul_f32_e32 v2, v34, v2
	v_mul_f32_e32 v3, v35, v3
	v_mul_f32_e32 v4, v36, v4
	v_mul_f32_e32 v5, v37, v5
	v_mul_f32_e32 v6, v38, v6
	v_mul_f32_e32 v7, v39, v7
	v_cvt_pk_bf16_f32 v152, v0, v1
	v_cvt_pk_bf16_f32 v153, v2, v3
	v_cvt_pk_bf16_f32 v154, v4, v5
	v_cvt_pk_bf16_f32 v155, v6, v7
	s_nop 1
	global_store_dwordx4 v132, v[152:155], s[50:51]
	s_nop 1
	v_fmamk_f32 v131, v135, 0x3a000000, v130
	v_add_u32_e32 v132, 0x2c000, v129
	v_rsq_f32_e32 v131, v131
	s_nop 0
	v_mul_f32_e32 v8, v8, v131
	v_mul_f32_e32 v9, v9, v131
	v_mul_f32_e32 v10, v10, v131
	v_mul_f32_e32 v11, v11, v131
	v_mul_f32_e32 v12, v12, v131
	v_mul_f32_e32 v13, v13, v131
	v_mul_f32_e32 v14, v14, v131
	v_mul_f32_e32 v15, v15, v131
	v_mul_f32_e32 v40, v40, v131
	v_mul_f32_e32 v41, v41, v131
	v_mul_f32_e32 v42, v42, v131
	v_mul_f32_e32 v43, v43, v131
	v_mul_f32_e32 v44, v44, v131
	v_mul_f32_e32 v45, v45, v131
	v_mul_f32_e32 v46, v46, v131
	v_mul_f32_e32 v47, v47, v131
	v_mul_f32_e32 v144, 0xbfb8aa3b, v8
	v_mul_f32_e32 v145, 0xbfb8aa3b, v9
	v_mul_f32_e32 v146, 0xbfb8aa3b, v10
	v_mul_f32_e32 v147, 0xbfb8aa3b, v11
	v_mul_f32_e32 v148, 0xbfb8aa3b, v12
	v_mul_f32_e32 v149, 0xbfb8aa3b, v13
	v_mul_f32_e32 v150, 0xbfb8aa3b, v14
	v_mul_f32_e32 v151, 0xbfb8aa3b, v15
	v_exp_f32_e32 v144, v144
	v_exp_f32_e32 v145, v145
	v_exp_f32_e32 v146, v146
	v_exp_f32_e32 v147, v147
	v_exp_f32_e32 v148, v148
	v_exp_f32_e32 v149, v149
	v_exp_f32_e32 v150, v150
	v_exp_f32_e32 v151, v151
	v_add_f32_e32 v144, 1.0, v144
	v_add_f32_e32 v145, 1.0, v145
	v_add_f32_e32 v146, 1.0, v146
	v_add_f32_e32 v147, 1.0, v147
	v_add_f32_e32 v148, 1.0, v148
	v_add_f32_e32 v149, 1.0, v149
	v_add_f32_e32 v150, 1.0, v150
	v_add_f32_e32 v151, 1.0, v151
	v_rcp_f32_e32 v144, v144
	v_rcp_f32_e32 v145, v145
	v_rcp_f32_e32 v146, v146
	v_rcp_f32_e32 v147, v147
	v_rcp_f32_e32 v148, v148
	v_rcp_f32_e32 v149, v149
	v_rcp_f32_e32 v150, v150
	v_rcp_f32_e32 v151, v151
	v_mul_f32_e32 v8, v8, v144
	v_mul_f32_e32 v9, v9, v145
	v_mul_f32_e32 v10, v10, v146
	v_mul_f32_e32 v11, v11, v147
	v_mul_f32_e32 v12, v12, v148
	v_mul_f32_e32 v13, v13, v149
	v_mul_f32_e32 v14, v14, v150
	v_mul_f32_e32 v15, v15, v151
	v_mul_f32_e32 v8, v40, v8
	v_mul_f32_e32 v9, v41, v9
	v_mul_f32_e32 v10, v42, v10
	v_mul_f32_e32 v11, v43, v11
	v_mul_f32_e32 v12, v44, v12
	v_mul_f32_e32 v13, v45, v13
	v_mul_f32_e32 v14, v46, v14
	v_mul_f32_e32 v15, v47, v15
	v_cvt_pk_bf16_f32 v152, v8, v9
	v_cvt_pk_bf16_f32 v153, v10, v11
	v_cvt_pk_bf16_f32 v154, v12, v13
	v_cvt_pk_bf16_f32 v155, v14, v15
	s_nop 1
	global_store_dwordx4 v132, v[152:155], s[50:51]
	s_nop 1
	v_fmamk_f32 v131, v136, 0x3a000000, v130
	v_add_u32_e32 v132, 0x58000, v129
	v_rsq_f32_e32 v131, v131
	s_nop 0
	v_mul_f32_e32 v16, v16, v131
	v_mul_f32_e32 v17, v17, v131
	v_mul_f32_e32 v18, v18, v131
; __device__ __forceinline__ unsigned cvt_pk_bf16(float lo, float hi) { unsigned r; asm volatile("v_cvt_pk_bf16_f32 %0, %1, %2" : "=v"(r) : "v"(lo), "v"(hi)); return r; }
;     __device__ __forceinline__ void operator()(const f32x4 (&acc)[2][2][4][2], const Unit& u, int wr, int wc, int fr, int fq) const {
;     ...
; #pragma unroll
;         for (int ai = 0; ai < 2; ++ai)
; #pragma unroll
;             for (int m = 0; m < 4; ++m) { const int row = row0 + ai * HALF + m * 16; const float rs = __builtin_amdgcn_rsqf(rsv[ai][m] * inv_n + eps);
;                 float a[8];
; #pragma unroll
;                 for (int n = 0; n < 2; ++n)
; #pragma unroll
;                     for (int i = 0; i < 4; ++i) { const float g = acc[ai][0][m][n][i] * rs, up = acc[ai][1][m][n][i] * rs;
;                         a[n * 4 + i] = g * __builtin_amdgcn_rcpf(1.0f + __builtin_amdgcn_exp2f(-1.4426950408889634f * g)) * up; }
;                 u32x4 w; w.x = cvt_pk_bf16(a[0], a[1]); w.y = cvt_pk_bf16(a[2], a[3]); w.z = cvt_pk_bf16(a[4], a[5]); w.w = cvt_pk_bf16(a[6], a[7]);
;                 *(u32x4*)(O + (size_t)row * ldc + col0) = w; }
	v_mul_f32_e32 v19, v19, v131
	v_mul_f32_e32 v20, v20, v131
	v_mul_f32_e32 v21, v21, v131
	v_mul_f32_e32 v22, v22, v131
	v_mul_f32_e32 v23, v23, v131
	v_mul_f32_e32 v48, v48, v131
	v_mul_f32_e32 v49, v49, v131
	v_mul_f32_e32 v50, v50, v131
	v_mul_f32_e32 v51, v51, v131
	v_mul_f32_e32 v52, v52, v131
	v_mul_f32_e32 v53, v53, v131
	v_mul_f32_e32 v54, v54, v131
	v_mul_f32_e32 v55, v55, v131
	v_mul_f32_e32 v144, 0xbfb8aa3b, v16
	v_mul_f32_e32 v145, 0xbfb8aa3b, v17
	v_mul_f32_e32 v146, 0xbfb8aa3b, v18
	v_mul_f32_e32 v147, 0xbfb8aa3b, v19
	v_mul_f32_e32 v148, 0xbfb8aa3b, v20
	v_mul_f32_e32 v149, 0xbfb8aa3b, v21
	v_mul_f32_e32 v150, 0xbfb8aa3b, v22
	v_mul_f32_e32 v151, 0xbfb8aa3b, v23
	v_exp_f32_e32 v144, v144
	v_exp_f32_e32 v145, v145
	v_exp_f32_e32 v146, v146
	v_exp_f32_e32 v147, v147
	v_exp_f32_e32 v148, v148
	v_exp_f32_e32 v149, v149
	v_exp_f32_e32 v150, v150
	v_exp_f32_e32 v151, v151
	v_add_f32_e32 v144, 1.0, v144
	v_add_f32_e32 v145, 1.0, v145
	v_add_f32_e32 v146, 1.0, v146
	v_add_f32_e32 v147, 1.0, v147
	v_add_f32_e32 v148, 1.0, v148
	v_add_f32_e32 v149, 1.0, v149
	v_add_f32_e32 v150, 1.0, v150
	v_add_f32_e32 v151, 1.0, v151
	v_rcp_f32_e32 v144, v144
	v_rcp_f32_e32 v145, v145
	v_rcp_f32_e32 v146, v146
	v_rcp_f32_e32 v147, v147
	v_rcp_f32_e32 v148, v148
	v_rcp_f32_e32 v149, v149
	v_rcp_f32_e32 v150, v150
	v_rcp_f32_e32 v151, v151
	v_mul_f32_e32 v16, v16, v144
	v_mul_f32_e32 v17, v17, v145
	v_mul_f32_e32 v18, v18, v146
	v_mul_f32_e32 v19, v19, v147
	v_mul_f32_e32 v20, v20, v148
	v_mul_f32_e32 v21, v21, v149
	v_mul_f32_e32 v22, v22, v150
	v_mul_f32_e32 v23, v23, v151
	v_mul_f32_e32 v16, v48, v16
	v_mul_f32_e32 v17, v49, v17
	v_mul_f32_e32 v18, v50, v18
	v_mul_f32_e32 v19, v51, v19
	v_mul_f32_e32 v20, v52, v20
	v_mul_f32_e32 v21, v53, v21
	v_mul_f32_e32 v22, v54, v22
	v_mul_f32_e32 v23, v55, v23
	v_cvt_pk_bf16_f32 v152, v16, v17
	v_cvt_pk_bf16_f32 v153, v18, v19
	v_cvt_pk_bf16_f32 v154, v20, v21
	v_cvt_pk_bf16_f32 v155, v22, v23
	s_nop 1
	global_store_dwordx4 v132, v[152:155], s[50:51]
	s_nop 1
	v_fmamk_f32 v131, v137, 0x3a000000, v130
	v_add_u32_e32 v132, 0x84000, v129
	v_rsq_f32_e32 v131, v131
	s_nop 0
	v_mul_f32_e32 v24, v24, v131
	v_mul_f32_e32 v25, v25, v131
	v_mul_f32_e32 v26, v26, v131
	v_mul_f32_e32 v27, v27, v131
	v_mul_f32_e32 v28, v28, v131
	v_mul_f32_e32 v29, v29, v131
	v_mul_f32_e32 v30, v30, v131
	v_mul_f32_e32 v31, v31, v131
	v_mul_f32_e32 v56, v56, v131
	v_mul_f32_e32 v57, v57, v131
	v_mul_f32_e32 v58, v58, v131
	v_mul_f32_e32 v59, v59, v131
	v_mul_f32_e32 v60, v60, v131
	v_mul_f32_e32 v61, v61, v131
	v_mul_f32_e32 v62, v62, v131
	v_mul_f32_e32 v63, v63, v131
	v_mul_f32_e32 v144, 0xbfb8aa3b, v24
	v_mul_f32_e32 v145, 0xbfb8aa3b, v25
	v_mul_f32_e32 v146, 0xbfb8aa3b, v26
	v_mul_f32_e32 v147, 0xbfb8aa3b, v27
	v_mul_f32_e32 v148, 0xbfb8aa3b, v28
	v_mul_f32_e32 v149, 0xbfb8aa3b, v29
	v_mul_f32_e32 v150, 0xbfb8aa3b, v30
	v_mul_f32_e32 v151, 0xbfb8aa3b, v31
	v_exp_f32_e32 v144, v144
	v_exp_f32_e32 v145, v145
	v_exp_f32_e32 v146, v146
	v_exp_f32_e32 v147, v147
	v_exp_f32_e32 v148, v148
	v_exp_f32_e32 v149, v149
	v_exp_f32_e32 v150, v150
	v_exp_f32_e32 v151, v151
	v_add_f32_e32 v144, 1.0, v144
	v_add_f32_e32 v145, 1.0, v145
	v_add_f32_e32 v146, 1.0, v146
	v_add_f32_e32 v147, 1.0, v147
	v_add_f32_e32 v148, 1.0, v148
	v_add_f32_e32 v149, 1.0, v149
	v_add_f32_e32 v150, 1.0, v150
	v_add_f32_e32 v151, 1.0, v151
	v_rcp_f32_e32 v144, v144
	v_rcp_f32_e32 v145, v145
	v_rcp_f32_e32 v146, v146
	v_rcp_f32_e32 v147, v147
	v_rcp_f32_e32 v148, v148
	v_rcp_f32_e32 v149, v149
	v_rcp_f32_e32 v150, v150
	v_rcp_f32_e32 v151, v151
	v_mul_f32_e32 v24, v24, v144
	v_mul_f32_e32 v25, v25, v145
	v_mul_f32_e32 v26, v26, v146
	v_mul_f32_e32 v27, v27, v147
	v_mul_f32_e32 v28, v28, v148
	v_mul_f32_e32 v29, v29, v149
	v_mul_f32_e32 v30, v30, v150
	v_mul_f32_e32 v31, v31, v151
	v_mul_f32_e32 v24, v56, v24
	v_mul_f32_e32 v25, v57, v25
	v_mul_f32_e32 v26, v58, v26
	v_mul_f32_e32 v27, v59, v27
	v_mul_f32_e32 v28, v60, v28
	v_mul_f32_e32 v29, v61, v29
	v_mul_f32_e32 v30, v62, v30
	v_mul_f32_e32 v31, v63, v31
	v_cvt_pk_bf16_f32 v152, v24, v25
	v_cvt_pk_bf16_f32 v153, v26, v27
	v_cvt_pk_bf16_f32 v154, v28, v29
	v_cvt_pk_bf16_f32 v155, v30, v31
	s_nop 1
	global_store_dwordx4 v132, v[152:155], s[50:51]
	s_nop 1
	v_fmamk_f32 v131, v138, 0x3a000000, v130
	v_add_u32_e32 v132, 0x160000, v129
	v_rsq_f32_e32 v131, v131
	s_nop 0
	v_mul_f32_e32 v64, v64, v131
	v_mul_f32_e32 v65, v65, v131
	v_mul_f32_e32 v66, v66, v131
	v_mul_f32_e32 v67, v67, v131
	v_mul_f32_e32 v68, v68, v131
	v_mul_f32_e32 v69, v69, v131
	v_mul_f32_e32 v70, v70, v131
	v_mul_f32_e32 v71, v71, v131
	v_mul_f32_e32 v96, v96, v131
	v_mul_f32_e32 v97, v97, v131
	v_mul_f32_e32 v98, v98, v131
	v_mul_f32_e32 v99, v99, v131
	v_mul_f32_e32 v100, v100, v131
	v_mul_f32_e32 v101, v101, v131
	v_mul_f32_e32 v102, v102, v131
	v_mul_f32_e32 v103, v103, v131
	v_mul_f32_e32 v144, 0xbfb8aa3b, v64
	v_mul_f32_e32 v145, 0xbfb8aa3b, v65
	v_mul_f32_e32 v146, 0xbfb8aa3b, v66
	v_mul_f32_e32 v147, 0xbfb8aa3b, v67
	v_mul_f32_e32 v148, 0xbfb8aa3b, v68
	v_mul_f32_e32 v149, 0xbfb8aa3b, v69
	v_mul_f32_e32 v150, 0xbfb8aa3b, v70
	v_mul_f32_e32 v151, 0xbfb8aa3b, v71
	v_exp_f32_e32 v144, v144
	v_exp_f32_e32 v145, v145
	v_exp_f32_e32 v146, v146
	v_exp_f32_e32 v147, v147
	v_exp_f32_e32 v148, v148
	v_exp_f32_e32 v149, v149
	v_exp_f32_e32 v150, v150
	v_exp_f32_e32 v151, v151
	v_add_f32_e32 v144, 1.0, v144
	v_add_f32_e32 v145, 1.0, v145
	v_add_f32_e32 v146, 1.0, v146
	v_add_f32_e32 v147, 1.0, v147
	v_add_f32_e32 v148, 1.0, v148
	v_add_f32_e32 v149, 1.0, v149
	v_add_f32_e32 v150, 1.0, v150
	v_add_f32_e32 v151, 1.0, v151
	v_rcp_f32_e32 v144, v144
; __device__ __forceinline__ unsigned cvt_pk_bf16(float lo, float hi) { unsigned r; asm volatile("v_cvt_pk_bf16_f32 %0, %1, %2" : "=v"(r) : "v"(lo), "v"(hi)); return r; }
;     __device__ __forceinline__ void operator()(const f32x4 (&acc)[2][2][4][2], const Unit& u, int wr, int wc, int fr, int fq) const {
;     ...
; #pragma unroll
;         for (int ai = 0; ai < 2; ++ai)
; #pragma unroll
;             for (int m = 0; m < 4; ++m) { const int row = row0 + ai * HALF + m * 16; const float rs = __builtin_amdgcn_rsqf(rsv[ai][m] * inv_n + eps);
;                 float a[8];
; #pragma unroll
;                 for (int n = 0; n < 2; ++n)
; #pragma unroll
;                     for (int i = 0; i < 4; ++i) { const float g = acc[ai][0][m][n][i] * rs, up = acc[ai][1][m][n][i] * rs;
;                         a[n * 4 + i] = g * __builtin_amdgcn_rcpf(1.0f + __builtin_amdgcn_exp2f(-1.4426950408889634f * g)) * up; }
;                 u32x4 w; w.x = cvt_pk_bf16(a[0], a[1]); w.y = cvt_pk_bf16(a[2], a[3]); w.z = cvt_pk_bf16(a[4], a[5]); w.w = cvt_pk_bf16(a[6], a[7]);
;                 *(u32x4*)(O + (size_t)row * ldc + col0) = w; }
	v_rcp_f32_e32 v145, v145
	v_rcp_f32_e32 v146, v146
	v_rcp_f32_e32 v147, v147
	v_rcp_f32_e32 v148, v148
	v_rcp_f32_e32 v149, v149
	v_rcp_f32_e32 v150, v150
	v_rcp_f32_e32 v151, v151
	v_mul_f32_e32 v64, v64, v144
	v_mul_f32_e32 v65, v65, v145
	v_mul_f32_e32 v66, v66, v146
	v_mul_f32_e32 v67, v67, v147
	v_mul_f32_e32 v68, v68, v148
	v_mul_f32_e32 v69, v69, v149
	v_mul_f32_e32 v70, v70, v150
	v_mul_f32_e32 v71, v71, v151
	v_mul_f32_e32 v64, v96, v64
	v_mul_f32_e32 v65, v97, v65
	v_mul_f32_e32 v66, v98, v66
	v_mul_f32_e32 v67, v99, v67
	v_mul_f32_e32 v68, v100, v68
	v_mul_f32_e32 v69, v101, v69
	v_mul_f32_e32 v70, v102, v70
	v_mul_f32_e32 v71, v103, v71
	v_cvt_pk_bf16_f32 v152, v64, v65
	v_cvt_pk_bf16_f32 v153, v66, v67
	v_cvt_pk_bf16_f32 v154, v68, v69
	v_cvt_pk_bf16_f32 v155, v70, v71
	s_nop 1
	global_store_dwordx4 v132, v[152:155], s[50:51]
	s_nop 1
	v_fmamk_f32 v131, v139, 0x3a000000, v130
	v_add_u32_e32 v132, 0x18c000, v129
	v_rsq_f32_e32 v131, v131
	s_nop 0
	v_mul_f32_e32 v72, v72, v131
	v_mul_f32_e32 v73, v73, v131
	v_mul_f32_e32 v74, v74, v131
	v_mul_f32_e32 v75, v75, v131
	v_mul_f32_e32 v76, v76, v131
	v_mul_f32_e32 v77, v77, v131
	v_mul_f32_e32 v78, v78, v131
	v_mul_f32_e32 v79, v79, v131
	v_mul_f32_e32 v104, v104, v131
	v_mul_f32_e32 v105, v105, v131
	v_mul_f32_e32 v106, v106, v131
	v_mul_f32_e32 v107, v107, v131
	v_mul_f32_e32 v108, v108, v131
	v_mul_f32_e32 v109, v109, v131
	v_mul_f32_e32 v110, v110, v131
	v_mul_f32_e32 v111, v111, v131
	v_mul_f32_e32 v144, 0xbfb8aa3b, v72
	v_mul_f32_e32 v145, 0xbfb8aa3b, v73
	v_mul_f32_e32 v146, 0xbfb8aa3b, v74
	v_mul_f32_e32 v147, 0xbfb8aa3b, v75
	v_mul_f32_e32 v148, 0xbfb8aa3b, v76
	v_mul_f32_e32 v149, 0xbfb8aa3b, v77
	v_mul_f32_e32 v150, 0xbfb8aa3b, v78
	v_mul_f32_e32 v151, 0xbfb8aa3b, v79
	v_exp_f32_e32 v144, v144
	v_exp_f32_e32 v145, v145
	v_exp_f32_e32 v146, v146
	v_exp_f32_e32 v147, v147
	v_exp_f32_e32 v148, v148
	v_exp_f32_e32 v149, v149
	v_exp_f32_e32 v150, v150
	v_exp_f32_e32 v151, v151
	v_add_f32_e32 v144, 1.0, v144
	v_add_f32_e32 v145, 1.0, v145
	v_add_f32_e32 v146, 1.0, v146
	v_add_f32_e32 v147, 1.0, v147
	v_add_f32_e32 v148, 1.0, v148
	v_add_f32_e32 v149, 1.0, v149
	v_add_f32_e32 v150, 1.0, v150
	v_add_f32_e32 v151, 1.0, v151
	v_rcp_f32_e32 v144, v144
	v_rcp_f32_e32 v145, v145
	v_rcp_f32_e32 v146, v146
	v_rcp_f32_e32 v147, v147
	v_rcp_f32_e32 v148, v148
	v_rcp_f32_e32 v149, v149
	v_rcp_f32_e32 v150, v150
	v_rcp_f32_e32 v151, v151
	v_mul_f32_e32 v72, v72, v144
	v_mul_f32_e32 v73, v73, v145
	v_mul_f32_e32 v74, v74, v146
	v_mul_f32_e32 v75, v75, v147
	v_mul_f32_e32 v76, v76, v148
	v_mul_f32_e32 v77, v77, v149
	v_mul_f32_e32 v78, v78, v150
	v_mul_f32_e32 v79, v79, v151
	v_mul_f32_e32 v72, v104, v72
	v_mul_f32_e32 v73, v105, v73
	v_mul_f32_e32 v74, v106, v74
	v_mul_f32_e32 v75, v107, v75
	v_mul_f32_e32 v76, v108, v76
	v_mul_f32_e32 v77, v109, v77
	v_mul_f32_e32 v78, v110, v78
	v_mul_f32_e32 v79, v111, v79
	v_cvt_pk_bf16_f32 v152, v72, v73
	v_cvt_pk_bf16_f32 v153, v74, v75
	v_cvt_pk_bf16_f32 v154, v76, v77
	v_cvt_pk_bf16_f32 v155, v78, v79
	s_nop 1
	global_store_dwordx4 v132, v[152:155], s[50:51]
	s_nop 1
	v_fmamk_f32 v131, v140, 0x3a000000, v130
	v_add_u32_e32 v132, 0x1b8000, v129
	v_rsq_f32_e32 v131, v131
	s_nop 0
	v_mul_f32_e32 v80, v80, v131
	v_mul_f32_e32 v81, v81, v131
	v_mul_f32_e32 v82, v82, v131
	v_mul_f32_e32 v83, v83, v131
	v_mul_f32_e32 v84, v84, v131
	v_mul_f32_e32 v85, v85, v131
	v_mul_f32_e32 v86, v86, v131
	v_mul_f32_e32 v87, v87, v131
	v_mul_f32_e32 v112, v112, v131
	v_mul_f32_e32 v113, v113, v131
	v_mul_f32_e32 v114, v114, v131
	v_mul_f32_e32 v115, v115, v131
	v_mul_f32_e32 v116, v116, v131
	v_mul_f32_e32 v117, v117, v131
	v_mul_f32_e32 v118, v118, v131
	v_mul_f32_e32 v119, v119, v131
	v_mul_f32_e32 v144, 0xbfb8aa3b, v80
	v_mul_f32_e32 v145, 0xbfb8aa3b, v81
	v_mul_f32_e32 v146, 0xbfb8aa3b, v82
	v_mul_f32_e32 v147, 0xbfb8aa3b, v83
	v_mul_f32_e32 v148, 0xbfb8aa3b, v84
; __device__ __forceinline__ unsigned cvt_pk_bf16(float lo, float hi) { unsigned r; asm volatile("v_cvt_pk_bf16_f32 %0, %1, %2" : "=v"(r) : "v"(lo), "v"(hi)); return r; }
;     __device__ __forceinline__ void operator()(const f32x4 (&acc)[2][2][4][2], const Unit& u, int wr, int wc, int fr, int fq) const {
;     ...
;             for (int m = 0; m < 4; ++m) { const int row = row0 + ai * HALF + m * 16; const float rs = __builtin_amdgcn_rsqf(rsv[ai][m] * inv_n + eps);
;                 float a[8];
; #pragma unroll
;                 for (int n = 0; n < 2; ++n)
; #pragma unroll
;                     for (int i = 0; i < 4; ++i) { const float g = acc[ai][0][m][n][i] * rs, up = acc[ai][1][m][n][i] * rs;
;                         a[n * 4 + i] = g * __builtin_amdgcn_rcpf(1.0f + __builtin_amdgcn_exp2f(-1.4426950408889634f * g)) * up; }
;                 u32x4 w; w.x = cvt_pk_bf16(a[0], a[1]); w.y = cvt_pk_bf16(a[2], a[3]); w.z = cvt_pk_bf16(a[4], a[5]); w.w = cvt_pk_bf16(a[6], a[7]);
;                 *(u32x4*)(O + (size_t)row * ldc + col0) = w; }
; template <class Epi, class Sched, bool ALIGN_EPI = false, bool SP2 = false>
; __device__ __forceinline__ void gemm_phase(PG8_LAS unsigned char* lds, const Gemm g, const Sched& S, const Epi& E) {
;     ...
;         if (!has_next) break;
; #pragma unroll
;         for (int a = 0; a < 2; ++a)
; #pragma unroll
;             for (int b = 0; b < 2; ++b)
; #pragma unroll
;                 for (int m = 0; m < 4; ++m)
; #pragma unroll
;                     for (int n = 0; n < 2; ++n) acc[a][b][m][n] = (f32x4){0.f, 0.f, 0.f, 0.f};
;         cur = nxt; cA = nA; cB = nB; ++ui;
	v_mul_f32_e32 v149, 0xbfb8aa3b, v85
	v_mul_f32_e32 v150, 0xbfb8aa3b, v86
	v_mul_f32_e32 v151, 0xbfb8aa3b, v87
	v_exp_f32_e32 v144, v144
	v_exp_f32_e32 v145, v145
	v_exp_f32_e32 v146, v146
	v_exp_f32_e32 v147, v147
	v_exp_f32_e32 v148, v148
	v_exp_f32_e32 v149, v149
	v_exp_f32_e32 v150, v150
	v_exp_f32_e32 v151, v151
	v_add_f32_e32 v144, 1.0, v144
	v_add_f32_e32 v145, 1.0, v145
	v_add_f32_e32 v146, 1.0, v146
	v_add_f32_e32 v147, 1.0, v147
	v_add_f32_e32 v148, 1.0, v148
	v_add_f32_e32 v149, 1.0, v149
	v_add_f32_e32 v150, 1.0, v150
	v_add_f32_e32 v151, 1.0, v151
	v_rcp_f32_e32 v144, v144
	v_rcp_f32_e32 v145, v145
	v_rcp_f32_e32 v146, v146
	v_rcp_f32_e32 v147, v147
	v_rcp_f32_e32 v148, v148
	v_rcp_f32_e32 v149, v149
	v_rcp_f32_e32 v150, v150
	v_rcp_f32_e32 v151, v151
	v_mul_f32_e32 v80, v80, v144
	v_mul_f32_e32 v81, v81, v145
	v_mul_f32_e32 v82, v82, v146
	v_mul_f32_e32 v83, v83, v147
	v_mul_f32_e32 v84, v84, v148
	v_mul_f32_e32 v85, v85, v149
	v_mul_f32_e32 v86, v86, v150
	v_mul_f32_e32 v87, v87, v151
	v_mul_f32_e32 v80, v112, v80
	v_mul_f32_e32 v81, v113, v81
	v_mul_f32_e32 v82, v114, v82
	v_mul_f32_e32 v83, v115, v83
	v_mul_f32_e32 v84, v116, v84
	v_mul_f32_e32 v85, v117, v85
	v_mul_f32_e32 v86, v118, v86
	v_mul_f32_e32 v87, v119, v87
	v_cvt_pk_bf16_f32 v152, v80, v81
	v_cvt_pk_bf16_f32 v153, v82, v83
	v_cvt_pk_bf16_f32 v154, v84, v85
	v_cvt_pk_bf16_f32 v155, v86, v87
	s_nop 1
	global_store_dwordx4 v132, v[152:155], s[50:51]
	s_nop 1
	v_fmamk_f32 v131, v141, 0x3a000000, v130
	v_add_u32_e32 v132, 0x1e4000, v129
	v_rsq_f32_e32 v131, v131
	s_nop 0
	v_mul_f32_e32 v88, v88, v131
	v_mul_f32_e32 v89, v89, v131
	v_mul_f32_e32 v90, v90, v131
	v_mul_f32_e32 v91, v91, v131
	v_mul_f32_e32 v92, v92, v131
	v_mul_f32_e32 v93, v93, v131
	v_mul_f32_e32 v94, v94, v131
	v_mul_f32_e32 v95, v95, v131
	v_mul_f32_e32 v120, v120, v131
	v_mul_f32_e32 v121, v121, v131
	v_mul_f32_e32 v122, v122, v131
	v_mul_f32_e32 v123, v123, v131
	v_mul_f32_e32 v124, v124, v131
	v_mul_f32_e32 v125, v125, v131
	v_mul_f32_e32 v126, v126, v131
	v_mul_f32_e32 v127, v127, v131
	v_mul_f32_e32 v144, 0xbfb8aa3b, v88
	v_mul_f32_e32 v145, 0xbfb8aa3b, v89
	v_mul_f32_e32 v146, 0xbfb8aa3b, v90
	v_mul_f32_e32 v147, 0xbfb8aa3b, v91
	v_mul_f32_e32 v148, 0xbfb8aa3b, v92
	v_mul_f32_e32 v149, 0xbfb8aa3b, v93
	v_mul_f32_e32 v150, 0xbfb8aa3b, v94
	v_mul_f32_e32 v151, 0xbfb8aa3b, v95
	v_exp_f32_e32 v144, v144
	v_exp_f32_e32 v145, v145
	v_exp_f32_e32 v146, v146
	v_exp_f32_e32 v147, v147
	v_exp_f32_e32 v148, v148
	v_exp_f32_e32 v149, v149
	v_exp_f32_e32 v150, v150
	v_exp_f32_e32 v151, v151
	v_add_f32_e32 v144, 1.0, v144
	v_add_f32_e32 v145, 1.0, v145
	v_add_f32_e32 v146, 1.0, v146
	v_add_f32_e32 v147, 1.0, v147
	v_add_f32_e32 v148, 1.0, v148
	v_add_f32_e32 v149, 1.0, v149
	v_add_f32_e32 v150, 1.0, v150
	v_add_f32_e32 v151, 1.0, v151
	v_rcp_f32_e32 v144, v144
	v_rcp_f32_e32 v145, v145
	v_rcp_f32_e32 v146, v146
	v_rcp_f32_e32 v147, v147
	v_rcp_f32_e32 v148, v148
	v_rcp_f32_e32 v149, v149
	v_rcp_f32_e32 v150, v150
	v_rcp_f32_e32 v151, v151
	v_mul_f32_e32 v88, v88, v144
	v_mul_f32_e32 v89, v89, v145
	v_mul_f32_e32 v90, v90, v146
	v_mul_f32_e32 v91, v91, v147
	v_mul_f32_e32 v92, v92, v148
	v_mul_f32_e32 v93, v93, v149
	v_mul_f32_e32 v94, v94, v150
	v_mul_f32_e32 v95, v95, v151
	v_mul_f32_e32 v88, v120, v88
	v_mul_f32_e32 v89, v121, v89
	v_mul_f32_e32 v90, v122, v90
	v_mul_f32_e32 v91, v123, v91
	v_mul_f32_e32 v92, v124, v92
	v_mul_f32_e32 v93, v125, v93
	v_mul_f32_e32 v94, v126, v94
	v_mul_f32_e32 v95, v127, v95
	v_cvt_pk_bf16_f32 v152, v88, v89
	v_cvt_pk_bf16_f32 v153, v90, v91
	v_cvt_pk_bf16_f32 v154, v92, v93
	v_cvt_pk_bf16_f32 v155, v94, v95
	s_nop 1
	global_store_dwordx4 v132, v[152:155], s[50:51]
	s_nop 1
	s_cmp_eq_u32 s19, 0
	s_cbranch_scc1 .Lp5_done
	s_mov_b32 s17, s20
	s_mov_b32 s18, s21
	s_mov_b64 s[22:23], s[26:27]
	s_mov_b64 s[24:25], s[28:29]
	s_add_u32 s16, s16, 1
	s_branch .Lp5_unit

; template <class Epi, class Sched, bool ALIGN_EPI = false, bool SP2 = false>
; __device__ __forceinline__ void gemm_phase(PG8_LAS unsigned char* lds, const Gemm g, const Sched& S, const Epi& E) {
;     ...
;     const int tid = tid_, wid = __builtin_amdgcn_readfirstlane(tid >> 6), lane = tid & 63, wr = wid >> 2, wc = wid & 3, fr = lane & 15, fq = lane >> 4;
;     const int K = g.K, nt = K / BK;
;     unsigned voffA[2], voffB[2];
; #pragma unroll
;     for (int i = 0; i < 2; ++i) { int R, C; stage_rc(tid * 16 + i * 8192, R, C); const int Rb = Epi::PERM ? ((R & ~31) + perm32(R & 31)) : R;
;         voffA[i] = (unsigned)(R * K + C) * 2u; voffB[i] = (unsigned)(Rb * K + C) * 2u; }
;     const size_t kstep = (size_t)(BK * 2);
;     const size_t hstep = (size_t)HALF * K * 2;
;     const size_t tstep = 2 * hstep;
;     const unsigned ldsw = (unsigned)wid * 1024u;
;     const int aoff = lds_byte(wr * 64 + fr, fq * 8), boff = lds_byte(wc * 32 + fr, fq * 8);
;     ...
;     Unit cur, nxt; int ui = 0;
;     if (!S.next(0, cur)) return;
;     f32x4 acc[2][2][4][2];
; #pragma unroll
;     for (int a = 0; a < 2; ++a)
; #pragma unroll
;         for (int b = 0; b < 2; ++b)
; #pragma unroll
;             for (int m = 0; m < 4; ++m)
; #pragma unroll
;                 for (int n = 0; n < 2; ++n) acc[a][b][m][n] = (f32x4){0.f, 0.f, 0.f, 0.f};
;     bf16x8 At[4][2], B0[2][2], B1[2][2];
;     const char* cA = (const char*)g.A + (size_t)cur.pm * tstep; const char* cB = (const char*)g.Bt + (size_t)cur.pn * tstep;
;     S.a_ready(cur);
;     if constexpr (SP2) {
;         PG8_STAGE(PG8_SB(0, 0), cB, voffB); PG8_STAGE(PG8_SB(0, 1), cB + hstep, voffB); PG8_STAGE(PG8_SA(0, 0), cA, voffA); PG8_STAGE(PG8_SA(0, 1), cA + hstep, voffA);
;         if (wr == 1) PG8_BAR;
;         PG8_WAIT_V(2); PG8_BAR;
;         PG8_STAGE(PG8_SB(1, 0), cB + kstep, voffB); PG8_STAGE(PG8_SA(1, 0), cA + kstep, voffA); PG8_STAGE(PG8_SB(1, 1), cB + hstep + kstep, voffB);
;         PG8_WAIT_V(6); PG8_BAR;
;     } else {
;         PG8_STAGE(PG8_SB(0, 0), cB, voffB); PG8_STAGE(PG8_SA(0, 0), cA, voffA); PG8_STAGE(PG8_SB(0, 1), cB + hstep, voffB); PG8_STAGE(PG8_SA(0, 1), cA + hstep, voffA);
;         if (wr == 1) PG8_BAR;
;         PG8_WAIT_V(4); PG8_BAR;
;         PG8_STAGE(PG8_SB(1, 0), cB + kstep, voffB); PG8_STAGE(PG8_SA(1, 0), cA + kstep, voffA); PG8_STAGE(PG8_SB(1, 1), cB + hstep + kstep, voffB);
;         PG8_WAIT_V(6); PG8_BAR;
.LBB0_840:
	s_cmp_lt_i32 s70, 7
	s_cselect_b64 s[4:5], -1, 0
	s_and_b64 s[8:9], s[4:5], s[0:1]
	s_andn2_b64 vcc, exec, s[8:9]
	s_cbranch_vccnz .LBB0_887
	v_readlane_b32 s100, v244, 4
	s_nop 3
	s_cmp_lg_u32 s100, 0x100
	s_cbranch_scc1 .Lp6_base
	v_writelane_b32 v253, s4, 0
	v_writelane_b32 v253, s5, 1
	v_writelane_b32 v253, s6, 2
	v_writelane_b32 v253, s7, 3
	v_writelane_b32 v253, s8, 4
	v_writelane_b32 v253, s9, 5
	v_writelane_b32 v253, s10, 6
	v_writelane_b32 v253, s11, 7
	v_writelane_b32 v253, s12, 8
	v_writelane_b32 v253, s13, 9
	v_writelane_b32 v253, s14, 10
	v_writelane_b32 v253, s15, 11
	v_writelane_b32 v253, s16, 12
	v_writelane_b32 v253, s17, 13
	v_writelane_b32 v253, s18, 14
	v_writelane_b32 v253, s19, 15
	v_writelane_b32 v253, s20, 16
	v_writelane_b32 v253, s21, 17
	v_writelane_b32 v253, s22, 18
	v_writelane_b32 v253, s23, 19
	v_writelane_b32 v253, s24, 20
	v_writelane_b32 v253, s25, 21
	v_writelane_b32 v253, s26, 22
	v_writelane_b32 v253, s27, 23
	v_writelane_b32 v253, s28, 24
	v_writelane_b32 v253, s29, 25
	v_writelane_b32 v253, s30, 26
	v_writelane_b32 v253, s31, 27
	v_writelane_b32 v253, s32, 28
	v_writelane_b32 v253, s33, 29
	v_writelane_b32 v253, s34, 30
	v_writelane_b32 v253, s35, 31
	v_writelane_b32 v253, s36, 32
	v_writelane_b32 v253, s37, 33
	v_writelane_b32 v253, s38, 34
	v_writelane_b32 v253, s39, 35
	v_writelane_b32 v253, s40, 36
	v_writelane_b32 v253, s41, 37
	v_writelane_b32 v253, s42, 38
	v_writelane_b32 v253, s43, 39
	v_writelane_b32 v253, s44, 40
	v_writelane_b32 v253, s45, 41
	v_writelane_b32 v253, s46, 42
	v_writelane_b32 v253, s47, 43
	v_writelane_b32 v253, s48, 44
	v_writelane_b32 v253, s49, 45
	v_writelane_b32 v253, s50, 46
	v_writelane_b32 v253, s51, 47
	v_writelane_b32 v253, s52, 48
	v_writelane_b32 v253, s53, 49
	v_writelane_b32 v253, s54, 50
	v_writelane_b32 v253, s55, 51
	v_writelane_b32 v253, s56, 52
	v_writelane_b32 v253, s57, 53
	v_writelane_b32 v253, s58, 54
	v_writelane_b32 v253, s59, 55
	s_mov_b32 s40, vcc_lo
	s_mov_b32 s41, vcc_hi
	v_writelane_b32 v253, s40, 60
	v_writelane_b32 v253, s41, 61
	v_lshrrev_b32_e32 v254, 6, v185
	v_readlane_b32 s14, v244, 4
	v_readfirstlane_b32 s36, v254
	s_nop 3
	s_lshr_b32 s37, s36, 2
	s_and_b32 s38, s36, 3
	s_lshl_b32 s35, s36, 10
	s_add_u32 s10, s76, 0xa800000
	s_addc_u32 s11, s77, 0
	s_add_u32 s12, s76, 0x5100000
	s_addc_u32 s13, s77, 0
	s_mov_b32 s16, 0
	s_mul_i32 s40, s16, s14
	s_add_u32 s40, s40, s2
	s_cmp_lt_u32 s40, 512
	s_cselect_b32 s44, 1, 0
	s_min_u32 s40, s40, 511
	s_and_b32 s41, s40, 7
	s_lshr_b32 s42, s40, 3
	s_mul_i32 s41, s41, 64
	s_add_u32 s41, s41, s42
	s_lshr_b32 s42, s41, 5
	s_and_b32 s43, s41, 31
	s_and_b32 s40, s43, 3
	s_lshl_b32 s42, s42, 2
	s_add_u32 s17, s42, s40
	s_lshr_b32 s18, s43, 2
	s_cmp_eq_u32 s44, 0
	s_cbranch_scc1 .Lp6_exit
	v_and_b32_e32 v254, 63, v185
	v_and_b32_e32 v255, 15, v254
	v_lshrrev_b32_e32 v186, 1, v255
	v_lshrrev_b32_e32 v187, 4, v254
	v_xor_b32_e32 v186, v186, v187
	v_lshlrev_b32_e32 v255, 7, v255
	v_lshl_or_b32 v255, v186, 4, v255
	s_lshl_b32 s40, s37, 13
	s_lshl_b32 s41, s38, 12
	s_add_u32 s41, s41, 0x10000
	v_add_u32_e32 v245, s40, v255
	v_add_u32_e32 v247, s41, v255
	v_xor_b32_e32 v246, 64, v245
	v_xor_b32_e32 v248, 64, v247
	v_lshrrev_b32_e32 v255, 3, v254
	v_and_b32_e32 v186, 7, v254
	s_and_b32 s40, s36, 1
	s_lshl_b32 s40, s40, 2
	v_lshrrev_b32_e32 v187, 1, v255
	v_add_u32_e32 v187, s40, v187
	v_xor_b32_e32 v186, v186, v187
	v_lshlrev_b32_e32 v186, 4, v186
	s_lshl_b32 s40, s36, 3
	v_add_u32_e32 v187, s40, v255
	v_mul_u32_u24_e32 v187, 0x2c00, v187
	v_add_u32_e32 v249, v187, v186
	v_add_u32_e32 v250, 0xb0000, v249
	s_and_b32 s40, s36, 3
	s_lshl_b32 s40, s40, 3
	v_add_u32_e32 v187, s40, v255
	v_lshrrev_b32_e32 v254, 4, v187
	v_lshlrev_b32_e32 v254, 2, v254
	v_and_b32_e32 v255, 3, v187
	v_add_u32_e32 v254, v254, v255
	v_and_b32_e32 v187, 12, v187
	v_lshl_add_u32 v254, v187, 1, v254
	s_lshr_b32 s40, s36, 2
	s_lshl_b32 s40, s40, 5
	v_add_u32_e32 v254, s40, v254
	v_mul_u32_u24_e32 v254, 0x2c00, v254
	v_add_u32_e32 v251, v254, v186
	v_add_u32_e32 v252, 0xb0000, v251
	s_mul_i32 s40, s17, 0x2c0000
	s_add_u32 s22, s10, s40
	s_addc_u32 s23, s11, 0
	s_mul_i32 s40, s18, 0x2c0000
	s_add_u32 s24, s12, s40
	s_addc_u32 s25, s13, 0
	s_and_b32 s40, s16, 1
	s_lshl_b32 s4, s40, 8
	s_sub_u32 s4, 128, s4
	s_sub_u32 s5, 0, s40
	s_mul_i32 s8, s40, 11136
	s_add_u32 s30, s22, s8
	s_addc_u32 s31, s23, 0
	s_add_u32 s32, s24, s8
	s_addc_u32 s33, s25, 0
	s_add_u32 s56, s30, 0x160000
	s_addc_u32 s57, s31, 0
	s_add_u32 s58, s32, 0x160000
	s_addc_u32 s59, s33, 0
	s_add_i32 m0, s35, 0x0
	s_nop 0
	global_load_lds_dwordx4 v249, s[30:31]
	s_add_i32 m0, s35, 0x2000
	s_nop 0
	global_load_lds_dwordx4 v250, s[30:31]
	s_add_i32 m0, s35, 0x10000
	s_nop 0
	global_load_lds_dwordx4 v251, s[32:33]
	s_add_i32 m0, s35, 0x12000
	s_nop 0
	global_load_lds_dwordx4 v252, s[32:33]
	s_add_i32 m0, s35, 0x4000
	s_nop 0
	global_load_lds_dwordx4 v249, s[56:57]
	s_add_i32 m0, s35, 0x6000
	s_nop 0
	global_load_lds_dwordx4 v250, s[56:57]
	s_add_i32 m0, s35, 0x14000
	s_nop 0
	global_load_lds_dwordx4 v251, s[58:59]
	s_add_i32 m0, s35, 0x16000
	s_nop 0
	global_load_lds_dwordx4 v252, s[58:59]
	s_add_u32 s30, s30, s4
	s_addc_u32 s31, s31, s5
	s_add_u32 s56, s56, s4
	s_addc_u32 s57, s57, s5
	s_add_u32 s32, s32, s4
	s_addc_u32 s33, s33, s5
	s_add_u32 s58, s58, s4
	s_addc_u32 s59, s59, s5
	s_add_i32 m0, s35, 0x8000
	s_nop 0
	global_load_lds_dwordx4 v249, s[30:31]
	s_add_i32 m0, s35, 0xa000
	s_nop 0
	global_load_lds_dwordx4 v250, s[30:31]
	s_add_i32 m0, s35, 0x1c000
	s_nop 0
	global_load_lds_dwordx4 v251, s[58:59]
	s_add_i32 m0, s35, 0x1e000
	s_nop 0
	global_load_lds_dwordx4 v252, s[58:59]
	s_add_i32 m0, s35, 0xc000
	s_nop 0
	global_load_lds_dwordx4 v249, s[56:57]
	s_add_i32 m0, s35, 0xe000
	s_nop 0
	global_load_lds_dwordx4 v250, s[56:57]
	s_add_i32 m0, s35, 0x18000
	s_nop 0
	global_load_lds_dwordx4 v251, s[32:33]
	s_add_i32 m0, s35, 0x1a000
	s_nop 0
	global_load_lds_dwordx4 v252, s[32:33]
	s_add_u32 s30, s30, s4
	s_addc_u32 s31, s31, s5
	s_add_u32 s56, s56, s4
	s_addc_u32 s57, s57, s5
	s_add_u32 s32, s32, s4
	s_addc_u32 s33, s33, s5
	s_add_u32 s58, s58, s4
	s_addc_u32 s59, s59, s5
	s_waitcnt vmcnt(12)
	s_barrier
; #define PG8_STAGE(bufoff, gbase, voff) do { _Pragma("unroll") for (int _i = 0; _i < 2; ++_i) \
;         __builtin_amdgcn_global_load_lds((const unsigned*)((const char*)(gbase) + (voff)[_i]), (PG8_LAS unsigned*)(lds + (bufoff) + ldsw + _i * 8192), 16, 0, 0); } while (0)
; #define PG8_LDA(dst, b, h) do { _Pragma("unroll") for (int m = 0; m < 4; ++m) _Pragma("unroll") for (int k = 0; k < 2; ++k) dst[m][k] = *(const PG8_LAS bf16x8*)(lds + PG8_SA(b, h) + aoff + m * 2048 + k * 1024); } while (0)
; #define PG8_LDB(dst, b, h) do { _Pragma("unroll") for (int n = 0; n < 2; ++n) _Pragma("unroll") for (int k = 0; k < 2; ++k) dst[n][k] = *(const PG8_LAS bf16x8*)(lds + PG8_SB(b, h) + boff + n * 2048 + k * 1024); } while (0)
; #define PG8_SCHED __builtin_amdgcn_sched_barrier(0)
; template <class Epi, class Sched, bool ALIGN_EPI = false, bool SP2 = false>
; __device__ __forceinline__ void gemm_phase(PG8_LAS unsigned char* lds, const Gemm g, const Sched& S, const Epi& E) {
;     ...
;         const bool has_next = S.next(ui + 1, nxt);
;         const char* nA = has_next ? (const char*)g.A + (size_t)nxt.pm * tstep : cA; const char* nB = has_next ? (const char*)g.Bt + (size_t)nxt.pn * tstep : cB;
;         for (int t = 0; t < nt; t += 2) {
;             const bool last = (t == nt - 2);
;             const char* a1 = cA + (size_t)(t + 1) * kstep;
;             const char* a2 = last ? nA : cA + (size_t)(t + 2) * kstep; const char* b2 = last ? nB : cB + (size_t)(t + 2) * kstep;
;             const char* a3 = a2 + kstep; const char* b3 = b2 + kstep;
;             if (last && has_next) S.a_ready(nxt);
;             if constexpr (SP2) {
;             PG8_LDB(B0, 0, 0); PG8_LDB(B1, 0, 1); PG8_SCHED; PG8_LDA(At, 0, 0); PG8_STAGE(PG8_SA(1, 1), a1 + hstep, voffA);
;     ...
; #pragma unroll
;         for (int a = 0; a < 2; ++a)
; #pragma unroll
;             for (int b = 0; b < 2; ++b)
; #pragma unroll
;                 for (int m = 0; m < 4; ++m)
; #pragma unroll
;                     for (int n = 0; n < 2; ++n) acc[a][b][m][n] = (f32x4){0.f, 0.f, 0.f, 0.f};
;         cur = nxt; cA = nA; cB = nB; ++ui;
.Lp6_unit:
	s_add_u32 s45, s16, 1
	s_mul_i32 s40, s45, s14
	s_add_u32 s40, s40, s2
	s_cmp_lt_u32 s40, 512
	s_cselect_b32 s19, 1, 0
	s_min_u32 s40, s40, 511
	s_and_b32 s41, s40, 7
	s_lshr_b32 s42, s40, 3
	s_mul_i32 s41, s41, 64
	s_add_u32 s41, s41, s42
	s_lshr_b32 s42, s41, 5
	s_and_b32 s43, s41, 31
	s_and_b32 s40, s43, 3
	s_lshl_b32 s42, s42, 2
	s_add_u32 s20, s42, s40
	s_lshr_b32 s21, s43, 2
	s_mul_i32 s40, s20, 0x2c0000
	s_add_u32 s26, s10, s40
	s_addc_u32 s27, s11, 0
	s_mul_i32 s40, s21, 0x2c0000
	s_add_u32 s28, s12, s40
	s_addc_u32 s29, s13, 0
	s_cmp_eq_u32 s19, 0
	s_cselect_b32 s26, s22, s26
	s_cselect_b32 s27, s23, s27
	s_cselect_b32 s28, s24, s28
	s_cselect_b32 s29, s25, s29
	s_add_u32 s30, s22, s8
	s_addc_u32 s31, s23, 0
	s_add_u32 s32, s24, s8
	s_addc_u32 s33, s25, 0
	s_add_u32 s30, s30, s4
	s_addc_u32 s31, s31, s5
	s_add_u32 s32, s32, s4
	s_addc_u32 s33, s33, s5
	s_add_u32 s30, s30, s4
	s_addc_u32 s31, s31, s5
	s_add_u32 s32, s32, s4
	s_addc_u32 s33, s33, s5
	s_add_u32 s56, s30, 0x160000
	s_addc_u32 s57, s31, 0
	s_add_u32 s58, s32, 0x160000
	s_addc_u32 s59, s33, 0
	s_movk_i32 s34, 44
	v_mov_b32_e32 v0, 0
	v_mov_b32_e32 v1, 0
	v_mov_b32_e32 v2, 0
	v_mov_b32_e32 v3, 0
	v_mov_b32_e32 v4, 0
	v_mov_b32_e32 v5, 0
	v_mov_b32_e32 v6, 0
	v_mov_b32_e32 v7, 0
	v_mov_b32_e32 v8, 0
	v_mov_b32_e32 v9, 0
	v_mov_b32_e32 v10, 0
	v_mov_b32_e32 v11, 0
	v_mov_b32_e32 v12, 0
	v_mov_b32_e32 v13, 0
	v_mov_b32_e32 v14, 0
	v_mov_b32_e32 v15, 0
	v_mov_b32_e32 v16, 0
	v_mov_b32_e32 v17, 0
	v_mov_b32_e32 v18, 0
	v_mov_b32_e32 v19, 0
	v_mov_b32_e32 v20, 0
	v_mov_b32_e32 v21, 0
	v_mov_b32_e32 v22, 0
	v_mov_b32_e32 v23, 0
	v_mov_b32_e32 v24, 0
	v_mov_b32_e32 v25, 0
	v_mov_b32_e32 v26, 0
	v_mov_b32_e32 v27, 0
	v_mov_b32_e32 v28, 0
	v_mov_b32_e32 v29, 0
	v_mov_b32_e32 v30, 0
	v_mov_b32_e32 v31, 0
	v_mov_b32_e32 v32, 0
	v_mov_b32_e32 v33, 0
	v_mov_b32_e32 v34, 0
	v_mov_b32_e32 v35, 0
	v_mov_b32_e32 v36, 0
	v_mov_b32_e32 v37, 0
	v_mov_b32_e32 v38, 0
	v_mov_b32_e32 v39, 0
	v_mov_b32_e32 v40, 0
	v_mov_b32_e32 v41, 0
	v_mov_b32_e32 v42, 0
	v_mov_b32_e32 v43, 0
	v_mov_b32_e32 v44, 0
	v_mov_b32_e32 v45, 0
	v_mov_b32_e32 v46, 0
	v_mov_b32_e32 v47, 0
	v_mov_b32_e32 v48, 0
	v_mov_b32_e32 v49, 0
	v_mov_b32_e32 v50, 0
	v_mov_b32_e32 v51, 0
	v_mov_b32_e32 v52, 0
	v_mov_b32_e32 v53, 0
	v_mov_b32_e32 v54, 0
	v_mov_b32_e32 v55, 0
	v_mov_b32_e32 v56, 0
	v_mov_b32_e32 v57, 0
	v_mov_b32_e32 v58, 0
	v_mov_b32_e32 v59, 0
	v_mov_b32_e32 v60, 0
	v_mov_b32_e32 v61, 0
	v_mov_b32_e32 v62, 0
	v_mov_b32_e32 v63, 0
	v_mov_b32_e32 v64, 0
	v_mov_b32_e32 v65, 0
	v_mov_b32_e32 v66, 0
	v_mov_b32_e32 v67, 0
	v_mov_b32_e32 v68, 0
	v_mov_b32_e32 v69, 0
	v_mov_b32_e32 v70, 0
	v_mov_b32_e32 v71, 0
	v_mov_b32_e32 v72, 0
	v_mov_b32_e32 v73, 0
	v_mov_b32_e32 v74, 0
	v_mov_b32_e32 v75, 0
	v_mov_b32_e32 v76, 0
	v_mov_b32_e32 v77, 0
	v_mov_b32_e32 v78, 0
	v_mov_b32_e32 v79, 0
	v_mov_b32_e32 v80, 0
	v_mov_b32_e32 v81, 0
	v_mov_b32_e32 v82, 0
	v_mov_b32_e32 v83, 0
	v_mov_b32_e32 v84, 0
	v_mov_b32_e32 v85, 0
	v_mov_b32_e32 v86, 0
	v_mov_b32_e32 v87, 0
	v_mov_b32_e32 v88, 0
	v_mov_b32_e32 v89, 0
	v_mov_b32_e32 v90, 0
	v_mov_b32_e32 v91, 0
	v_mov_b32_e32 v92, 0
	v_mov_b32_e32 v93, 0
	v_mov_b32_e32 v94, 0
	v_mov_b32_e32 v95, 0
	v_mov_b32_e32 v96, 0
	v_mov_b32_e32 v97, 0
	v_mov_b32_e32 v98, 0
	v_mov_b32_e32 v99, 0
	v_mov_b32_e32 v100, 0
	v_mov_b32_e32 v101, 0
	v_mov_b32_e32 v102, 0
	v_mov_b32_e32 v103, 0
	v_mov_b32_e32 v104, 0
	v_mov_b32_e32 v105, 0
	v_mov_b32_e32 v106, 0
	v_mov_b32_e32 v107, 0
	v_mov_b32_e32 v108, 0
	v_mov_b32_e32 v109, 0
	v_mov_b32_e32 v110, 0
	v_mov_b32_e32 v111, 0
	v_mov_b32_e32 v112, 0
	v_mov_b32_e32 v113, 0
	v_mov_b32_e32 v114, 0
	v_mov_b32_e32 v115, 0
	v_mov_b32_e32 v116, 0
	v_mov_b32_e32 v117, 0
	v_mov_b32_e32 v118, 0
	v_mov_b32_e32 v119, 0
	v_mov_b32_e32 v120, 0
	v_mov_b32_e32 v121, 0
	v_mov_b32_e32 v122, 0
	v_mov_b32_e32 v123, 0
	v_mov_b32_e32 v124, 0
	v_mov_b32_e32 v125, 0
	v_mov_b32_e32 v126, 0
	v_mov_b32_e32 v127, 0
	ds_read_b128 v[196:199], v247 offset:0
	ds_read_b128 v[200:203], v248 offset:0
	ds_read_b128 v[204:207], v247 offset:2048
	ds_read_b128 v[208:211], v248 offset:2048
	ds_read_b128 v[128:131], v245 offset:0
	ds_read_b128 v[132:135], v246 offset:0
	ds_read_b128 v[136:139], v245 offset:2048
	ds_read_b128 v[140:143], v246 offset:2048
	ds_read_b128 v[144:147], v245 offset:4096
	ds_read_b128 v[148:151], v246 offset:4096
	ds_read_b128 v[152:155], v245 offset:6144
	ds_read_b128 v[156:159], v246 offset:6144
	s_cmp_ge_u32 s36, 4
	s_cbranch_scc1 .Lp6_kloop1
; #define PG8_STAGE(bufoff, gbase, voff) do { _Pragma("unroll") for (int _i = 0; _i < 2; ++_i) \
;         __builtin_amdgcn_global_load_lds((const unsigned*)((const char*)(gbase) + (voff)[_i]), (PG8_LAS unsigned*)(lds + (bufoff) + ldsw + _i * 8192), 16, 0, 0); } while (0)
; #define PG8_LDA(dst, b, h) do { _Pragma("unroll") for (int m = 0; m < 4; ++m) _Pragma("unroll") for (int k = 0; k < 2; ++k) dst[m][k] = *(const PG8_LAS bf16x8*)(lds + PG8_SA(b, h) + aoff + m * 2048 + k * 1024); } while (0)
; #define PG8_LDB(dst, b, h) do { _Pragma("unroll") for (int n = 0; n < 2; ++n) _Pragma("unroll") for (int k = 0; k < 2; ++k) dst[n][k] = *(const PG8_LAS bf16x8*)(lds + PG8_SB(b, h) + boff + n * 2048 + k * 1024); } while (0)
; #define PG8_MMA(ai, bj, At, Bt) do { __builtin_amdgcn_s_setprio(1); _Pragma("unroll") for (int m = 0; m < 4; ++m) _Pragma("unroll") for (int n = 0; n < 2; ++n) _Pragma("unroll") for (int k = 0; k < 2; ++k) \
;         acc[ai][bj][m][n] = __builtin_amdgcn_mfma_f32_16x16x32_bf16(Bt[n][k], At[m][k], acc[ai][bj][m][n], 0, 0, 0); __builtin_amdgcn_s_setprio(0); } while (0)
; #define PG8_WAIT_V(n) asm volatile("s_waitcnt vmcnt(" #n ")" ::: "memory")
; template <class Epi, class Sched, bool ALIGN_EPI = false, bool SP2 = false>
; __device__ __forceinline__ void gemm_phase(PG8_LAS unsigned char* lds, const Gemm g, const Sched& S, const Epi& E) {
;     ...
;             PG8_LDB(B0, 0, 0); PG8_LDB(B1, 0, 1); PG8_SCHED; PG8_LDA(At, 0, 0); PG8_STAGE(PG8_SA(1, 1), a1 + hstep, voffA);
;             PG8_WAIT_V(8); PG8_WAIT_L(0); PG8_BAR; PG8_MMA(0, 0, At, B0); PG8_MMA(0, 1, At, B1); PG8_BAR; PG8_SCHED;
;             PG8_LDA(At, 0, 1); PG8_STAGE(PG8_SB(0, 0), b2, voffB); PG8_STAGE(PG8_SB(0, 1), b2 + hstep, voffB); PG8_STAGE(PG8_SA(0, 0), a2, voffA);
;             PG8_WAIT_V(8); PG8_WAIT_L(0); PG8_BAR; PG8_MMA(1, 0, At, B0); PG8_MMA(1, 1, At, B1); PG8_BAR; PG8_SCHED;
;             PG8_LDB(B0, 1, 0); PG8_LDB(B1, 1, 1); PG8_SCHED; PG8_LDA(At, 1, 0); PG8_STAGE(PG8_SA(0, 1), a2 + hstep, voffA);
;             PG8_WAIT_V(8); PG8_WAIT_L(0); PG8_BAR; PG8_MMA(0, 0, At, B0); PG8_MMA(0, 1, At, B1); PG8_BAR; PG8_SCHED;
;             PG8_LDA(At, 1, 1); PG8_STAGE(PG8_SB(1, 0), b3, voffB); PG8_STAGE(PG8_SB(1, 1), b3 + hstep, voffB); PG8_STAGE(PG8_SA(1, 0), a3, voffA);
;             PG8_WAIT_V(8); PG8_WAIT_L(0); PG8_BAR; PG8_MMA(1, 0, At, B0); PG8_MMA(1, 1, At, B1); PG8_BAR; PG8_SCHED;
.Lp6_kloop0:
	s_waitcnt vmcnt(8)
	s_waitcnt lgkmcnt(0)
	s_barrier
	v_mfma_f32_16x16x32_bf16 v[0:3], v[196:199], v[128:131], v[0:3]
	ds_read_b128 v[212:215], v247 offset:16384
	v_mfma_f32_16x16x32_bf16 v[0:3], v[200:203], v[132:135], v[0:3]
	ds_read_b128 v[216:219], v248 offset:16384
	v_mfma_f32_16x16x32_bf16 v[4:7], v[208:211], v[132:135], v[4:7]
	ds_read_b128 v[220:223], v247 offset:18432
	v_mfma_f32_16x16x32_bf16 v[4:7], v[204:207], v[128:131], v[4:7]
	ds_read_b128 v[224:227], v248 offset:18432
	v_mfma_f32_16x16x32_bf16 v[12:15], v[204:207], v[136:139], v[12:15]
	s_add_i32 m0, s35, 0x0
	v_mfma_f32_16x16x32_bf16 v[12:15], v[208:211], v[140:143], v[12:15]
	global_load_lds_dwordx4 v249, s[30:31]
	v_mfma_f32_16x16x32_bf16 v[8:11], v[200:203], v[140:143], v[8:11]
	s_add_i32 m0, s35, 0x2000
	v_mfma_f32_16x16x32_bf16 v[8:11], v[196:199], v[136:139], v[8:11]
	global_load_lds_dwordx4 v250, s[30:31]
	v_mfma_f32_16x16x32_bf16 v[16:19], v[196:199], v[144:147], v[16:19]
	s_add_i32 m0, s35, 0x10000
	v_mfma_f32_16x16x32_bf16 v[16:19], v[200:203], v[148:151], v[16:19]
	global_load_lds_dwordx4 v251, s[32:33]
	v_mfma_f32_16x16x32_bf16 v[20:23], v[208:211], v[148:151], v[20:23]
	s_add_i32 m0, s35, 0x12000
	v_mfma_f32_16x16x32_bf16 v[20:23], v[204:207], v[144:147], v[20:23]
	global_load_lds_dwordx4 v252, s[32:33]
	v_mfma_f32_16x16x32_bf16 v[28:31], v[204:207], v[152:155], v[28:31]
	ds_read_b128 v[160:163], v245 offset:16384
	v_mfma_f32_16x16x32_bf16 v[28:31], v[208:211], v[156:159], v[28:31]
	ds_read_b128 v[164:167], v246 offset:16384
	v_mfma_f32_16x16x32_bf16 v[24:27], v[200:203], v[156:159], v[24:27]
	ds_read_b128 v[168:171], v245 offset:18432
	v_mfma_f32_16x16x32_bf16 v[24:27], v[196:199], v[152:155], v[24:27]
	ds_read_b128 v[172:175], v246 offset:18432
	s_waitcnt lgkmcnt(4)
	v_mfma_f32_16x16x32_bf16 v[32:35], v[212:215], v[128:131], v[32:35]
	ds_read_b128 v[176:179], v245 offset:20480
	v_mfma_f32_16x16x32_bf16 v[32:35], v[216:219], v[132:135], v[32:35]
	ds_read_b128 v[180:183], v246 offset:20480
	v_mfma_f32_16x16x32_bf16 v[36:39], v[224:227], v[132:135], v[36:39]
	ds_read_b128 v[188:191], v245 offset:22528
	v_mfma_f32_16x16x32_bf16 v[36:39], v[220:223], v[128:131], v[36:39]
	ds_read_b128 v[192:195], v246 offset:22528
	v_mfma_f32_16x16x32_bf16 v[44:47], v[220:223], v[136:139], v[44:47]
	v_mfma_f32_16x16x32_bf16 v[44:47], v[224:227], v[140:143], v[44:47]
	v_mfma_f32_16x16x32_bf16 v[40:43], v[216:219], v[140:143], v[40:43]
	v_mfma_f32_16x16x32_bf16 v[40:43], v[212:215], v[136:139], v[40:43]
	v_mfma_f32_16x16x32_bf16 v[48:51], v[212:215], v[144:147], v[48:51]
	v_mfma_f32_16x16x32_bf16 v[48:51], v[216:219], v[148:151], v[48:51]
	v_mfma_f32_16x16x32_bf16 v[52:55], v[224:227], v[148:151], v[52:55]
	v_mfma_f32_16x16x32_bf16 v[52:55], v[220:223], v[144:147], v[52:55]
	v_mfma_f32_16x16x32_bf16 v[60:63], v[220:223], v[152:155], v[60:63]
	v_mfma_f32_16x16x32_bf16 v[60:63], v[224:227], v[156:159], v[60:63]
	v_mfma_f32_16x16x32_bf16 v[56:59], v[216:219], v[156:159], v[56:59]
	v_mfma_f32_16x16x32_bf16 v[56:59], v[212:215], v[152:155], v[56:59]
	s_waitcnt vmcnt(8)
	s_waitcnt lgkmcnt(0)
	s_barrier
	v_mfma_f32_16x16x32_bf16 v[96:99], v[212:215], v[160:163], v[96:99]
	s_add_i32 m0, s35, 0x4000
	v_mfma_f32_16x16x32_bf16 v[96:99], v[216:219], v[164:167], v[96:99]
	global_load_lds_dwordx4 v249, s[56:57]
	v_mfma_f32_16x16x32_bf16 v[100:103], v[224:227], v[164:167], v[100:103]
	s_add_i32 m0, s35, 0x6000
	v_mfma_f32_16x16x32_bf16 v[100:103], v[220:223], v[160:163], v[100:103]
	global_load_lds_dwordx4 v250, s[56:57]
	v_mfma_f32_16x16x32_bf16 v[108:111], v[220:223], v[168:171], v[108:111]
	s_add_i32 m0, s35, 0x14000
	v_mfma_f32_16x16x32_bf16 v[108:111], v[224:227], v[172:175], v[108:111]
	global_load_lds_dwordx4 v251, s[58:59]
	v_mfma_f32_16x16x32_bf16 v[104:107], v[216:219], v[172:175], v[104:107]
	s_add_i32 m0, s35, 0x16000
	v_mfma_f32_16x16x32_bf16 v[104:107], v[212:215], v[168:171], v[104:107]
	global_load_lds_dwordx4 v252, s[58:59]
	v_mfma_f32_16x16x32_bf16 v[112:115], v[212:215], v[176:179], v[112:115]
	ds_read_b128 v[128:131], v245 offset:32768
	v_mfma_f32_16x16x32_bf16 v[112:115], v[216:219], v[180:183], v[112:115]
	ds_read_b128 v[132:135], v246 offset:32768
	v_mfma_f32_16x16x32_bf16 v[116:119], v[224:227], v[180:183], v[116:119]
	ds_read_b128 v[136:139], v245 offset:34816
	v_mfma_f32_16x16x32_bf16 v[116:119], v[220:223], v[176:179], v[116:119]
	ds_read_b128 v[140:143], v246 offset:34816
	v_mfma_f32_16x16x32_bf16 v[124:127], v[220:223], v[188:191], v[124:127]
	ds_read_b128 v[144:147], v245 offset:36864
	v_mfma_f32_16x16x32_bf16 v[124:127], v[224:227], v[192:195], v[124:127]
	ds_read_b128 v[148:151], v246 offset:36864
	v_mfma_f32_16x16x32_bf16 v[120:123], v[216:219], v[192:195], v[120:123]
	ds_read_b128 v[152:155], v245 offset:38912
	v_mfma_f32_16x16x32_bf16 v[120:123], v[212:215], v[188:191], v[120:123]
	ds_read_b128 v[156:159], v246 offset:38912
	v_mfma_f32_16x16x32_bf16 v[64:67], v[196:199], v[160:163], v[64:67]
	ds_read_b128 v[212:215], v247 offset:49152
	v_mfma_f32_16x16x32_bf16 v[64:67], v[200:203], v[164:167], v[64:67]
	ds_read_b128 v[216:219], v248 offset:49152
	v_mfma_f32_16x16x32_bf16 v[68:71], v[208:211], v[164:167], v[68:71]
	ds_read_b128 v[220:223], v247 offset:51200
	v_mfma_f32_16x16x32_bf16 v[68:71], v[204:207], v[160:163], v[68:71]
	ds_read_b128 v[224:227], v248 offset:51200
	v_mfma_f32_16x16x32_bf16 v[76:79], v[204:207], v[168:171], v[76:79]
	s_add_u32 s30, s30, s4
	s_addc_u32 s31, s31, s5
	v_mfma_f32_16x16x32_bf16 v[76:79], v[208:211], v[172:175], v[76:79]
	s_add_u32 s56, s56, s4
	s_addc_u32 s57, s57, s5
	v_mfma_f32_16x16x32_bf16 v[72:75], v[200:203], v[172:175], v[72:75]
	s_add_u32 s32, s32, s4
	s_addc_u32 s33, s33, s5
	v_mfma_f32_16x16x32_bf16 v[72:75], v[196:199], v[168:171], v[72:75]
	s_add_u32 s58, s58, s4
	s_addc_u32 s59, s59, s5
	v_mfma_f32_16x16x32_bf16 v[80:83], v[196:199], v[176:179], v[80:83]
	v_mfma_f32_16x16x32_bf16 v[80:83], v[200:203], v[180:183], v[80:83]
	v_mfma_f32_16x16x32_bf16 v[84:87], v[208:211], v[180:183], v[84:87]
	v_mfma_f32_16x16x32_bf16 v[84:87], v[204:207], v[176:179], v[84:87]
	v_mfma_f32_16x16x32_bf16 v[92:95], v[204:207], v[188:191], v[92:95]
	v_mfma_f32_16x16x32_bf16 v[92:95], v[208:211], v[192:195], v[92:95]
	v_mfma_f32_16x16x32_bf16 v[88:91], v[200:203], v[192:195], v[88:91]
	v_mfma_f32_16x16x32_bf16 v[88:91], v[196:199], v[188:191], v[88:91]
	s_waitcnt vmcnt(8)
	s_waitcnt lgkmcnt(0)
	s_barrier
; #define PG8_STAGE(bufoff, gbase, voff) do { _Pragma("unroll") for (int _i = 0; _i < 2; ++_i) \
;         __builtin_amdgcn_global_load_lds((const unsigned*)((const char*)(gbase) + (voff)[_i]), (PG8_LAS unsigned*)(lds + (bufoff) + ldsw + _i * 8192), 16, 0, 0); } while (0)
; #define PG8_LDA(dst, b, h) do { _Pragma("unroll") for (int m = 0; m < 4; ++m) _Pragma("unroll") for (int k = 0; k < 2; ++k) dst[m][k] = *(const PG8_LAS bf16x8*)(lds + PG8_SA(b, h) + aoff + m * 2048 + k * 1024); } while (0)
; #define PG8_LDB(dst, b, h) do { _Pragma("unroll") for (int n = 0; n < 2; ++n) _Pragma("unroll") for (int k = 0; k < 2; ++k) dst[n][k] = *(const PG8_LAS bf16x8*)(lds + PG8_SB(b, h) + boff + n * 2048 + k * 1024); } while (0)
; #define PG8_WAIT_V(n) asm volatile("s_waitcnt vmcnt(" #n ")" ::: "memory")
; #define PG8_WAIT_L(n) asm volatile("s_waitcnt lgkmcnt(" #n ")" ::: "memory")
; template <class Epi, class Sched, bool ALIGN_EPI = false, bool SP2 = false>
; __device__ __forceinline__ void gemm_phase(PG8_LAS unsigned char* lds, const Gemm g, const Sched& S, const Epi& E) {
;     ...
;             const char* a1 = cA + (size_t)(t + 1) * kstep;
;             const char* a2 = last ? nA : cA + (size_t)(t + 2) * kstep; const char* b2 = last ? nB : cB + (size_t)(t + 2) * kstep;
;             const char* a3 = a2 + kstep; const char* b3 = b2 + kstep;
;     ...
;             PG8_LDB(B0, 0, 0); PG8_LDB(B1, 0, 1); PG8_SCHED; PG8_LDA(At, 0, 0); PG8_STAGE(PG8_SA(1, 1), a1 + hstep, voffA);
;             PG8_WAIT_V(8); PG8_WAIT_L(0); PG8_BAR; PG8_MMA(0, 0, At, B0); PG8_MMA(0, 1, At, B1); PG8_BAR; PG8_SCHED;
;             PG8_LDA(At, 0, 1); PG8_STAGE(PG8_SB(0, 0), b2, voffB); PG8_STAGE(PG8_SB(0, 1), b2 + hstep, voffB); PG8_STAGE(PG8_SA(0, 0), a2, voffA);
;             PG8_WAIT_V(8); PG8_WAIT_L(0); PG8_BAR; PG8_MMA(1, 0, At, B0); PG8_MMA(1, 1, At, B1); PG8_BAR; PG8_SCHED;
;             PG8_LDB(B0, 1, 0); PG8_LDB(B1, 1, 1); PG8_SCHED; PG8_LDA(At, 1, 0); PG8_STAGE(PG8_SA(0, 1), a2 + hstep, voffA);
;             PG8_WAIT_V(8); PG8_WAIT_L(0); PG8_BAR; PG8_MMA(0, 0, At, B0); PG8_MMA(0, 1, At, B1); PG8_BAR; PG8_SCHED;
;             PG8_LDA(At, 1, 1); PG8_STAGE(PG8_SB(1, 0), b3, voffB); PG8_STAGE(PG8_SB(1, 1), b3 + hstep, voffB); PG8_STAGE(PG8_SA(1, 0), a3, voffA);
;             PG8_WAIT_V(8); PG8_WAIT_L(0); PG8_BAR; PG8_MMA(1, 0, At, B0); PG8_MMA(1, 1, At, B1); PG8_BAR; PG8_SCHED;
	v_mfma_f32_16x16x32_bf16 v[32:35], v[212:215], v[128:131], v[32:35]
	ds_read_b128 v[196:199], v247 offset:32768
	v_mfma_f32_16x16x32_bf16 v[32:35], v[216:219], v[132:135], v[32:35]
	ds_read_b128 v[200:203], v248 offset:32768
	v_mfma_f32_16x16x32_bf16 v[36:39], v[224:227], v[132:135], v[36:39]
	ds_read_b128 v[204:207], v247 offset:34816
	v_mfma_f32_16x16x32_bf16 v[36:39], v[220:223], v[128:131], v[36:39]
	ds_read_b128 v[208:211], v248 offset:34816
	v_mfma_f32_16x16x32_bf16 v[44:47], v[220:223], v[136:139], v[44:47]
	s_add_i32 m0, s35, 0x8000
	v_mfma_f32_16x16x32_bf16 v[44:47], v[224:227], v[140:143], v[44:47]
	global_load_lds_dwordx4 v249, s[30:31]
	v_mfma_f32_16x16x32_bf16 v[40:43], v[216:219], v[140:143], v[40:43]
	s_add_i32 m0, s35, 0xa000
	v_mfma_f32_16x16x32_bf16 v[40:43], v[212:215], v[136:139], v[40:43]
	global_load_lds_dwordx4 v250, s[30:31]
	v_mfma_f32_16x16x32_bf16 v[48:51], v[212:215], v[144:147], v[48:51]
	s_add_i32 m0, s35, 0x1c000
	v_mfma_f32_16x16x32_bf16 v[48:51], v[216:219], v[148:151], v[48:51]
	global_load_lds_dwordx4 v251, s[58:59]
	v_mfma_f32_16x16x32_bf16 v[52:55], v[224:227], v[148:151], v[52:55]
	s_add_i32 m0, s35, 0x1e000
	v_mfma_f32_16x16x32_bf16 v[52:55], v[220:223], v[144:147], v[52:55]
	global_load_lds_dwordx4 v252, s[58:59]
	v_mfma_f32_16x16x32_bf16 v[60:63], v[220:223], v[152:155], v[60:63]
	ds_read_b128 v[160:163], v245 offset:49152
	v_mfma_f32_16x16x32_bf16 v[60:63], v[224:227], v[156:159], v[60:63]
	ds_read_b128 v[164:167], v246 offset:49152
	v_mfma_f32_16x16x32_bf16 v[56:59], v[216:219], v[156:159], v[56:59]
	ds_read_b128 v[168:171], v245 offset:51200
	v_mfma_f32_16x16x32_bf16 v[56:59], v[212:215], v[152:155], v[56:59]
	ds_read_b128 v[172:175], v246 offset:51200
	s_waitcnt lgkmcnt(4)
	v_mfma_f32_16x16x32_bf16 v[0:3], v[196:199], v[128:131], v[0:3]
	ds_read_b128 v[176:179], v245 offset:53248
	v_mfma_f32_16x16x32_bf16 v[0:3], v[200:203], v[132:135], v[0:3]
	ds_read_b128 v[180:183], v246 offset:53248
	v_mfma_f32_16x16x32_bf16 v[4:7], v[208:211], v[132:135], v[4:7]
	ds_read_b128 v[188:191], v245 offset:55296
	v_mfma_f32_16x16x32_bf16 v[4:7], v[204:207], v[128:131], v[4:7]
	ds_read_b128 v[192:195], v246 offset:55296
	v_mfma_f32_16x16x32_bf16 v[12:15], v[204:207], v[136:139], v[12:15]
	v_mfma_f32_16x16x32_bf16 v[12:15], v[208:211], v[140:143], v[12:15]
	v_mfma_f32_16x16x32_bf16 v[8:11], v[200:203], v[140:143], v[8:11]
	v_mfma_f32_16x16x32_bf16 v[8:11], v[196:199], v[136:139], v[8:11]
	v_mfma_f32_16x16x32_bf16 v[16:19], v[196:199], v[144:147], v[16:19]
	v_mfma_f32_16x16x32_bf16 v[16:19], v[200:203], v[148:151], v[16:19]
	v_mfma_f32_16x16x32_bf16 v[20:23], v[208:211], v[148:151], v[20:23]
	v_mfma_f32_16x16x32_bf16 v[20:23], v[204:207], v[144:147], v[20:23]
	v_mfma_f32_16x16x32_bf16 v[28:31], v[204:207], v[152:155], v[28:31]
	v_mfma_f32_16x16x32_bf16 v[28:31], v[208:211], v[156:159], v[28:31]
	v_mfma_f32_16x16x32_bf16 v[24:27], v[200:203], v[156:159], v[24:27]
	v_mfma_f32_16x16x32_bf16 v[24:27], v[196:199], v[152:155], v[24:27]
	s_waitcnt vmcnt(8)
	s_waitcnt lgkmcnt(0)
	s_barrier
	v_mfma_f32_16x16x32_bf16 v[64:67], v[196:199], v[160:163], v[64:67]
	s_add_i32 m0, s35, 0xc000
	v_mfma_f32_16x16x32_bf16 v[64:67], v[200:203], v[164:167], v[64:67]
	global_load_lds_dwordx4 v249, s[56:57]
	v_mfma_f32_16x16x32_bf16 v[68:71], v[208:211], v[164:167], v[68:71]
	s_add_i32 m0, s35, 0xe000
	v_mfma_f32_16x16x32_bf16 v[68:71], v[204:207], v[160:163], v[68:71]
	global_load_lds_dwordx4 v250, s[56:57]
	v_mfma_f32_16x16x32_bf16 v[76:79], v[204:207], v[168:171], v[76:79]
	s_add_i32 m0, s35, 0x18000
	v_mfma_f32_16x16x32_bf16 v[76:79], v[208:211], v[172:175], v[76:79]
	global_load_lds_dwordx4 v251, s[32:33]
	v_mfma_f32_16x16x32_bf16 v[72:75], v[200:203], v[172:175], v[72:75]
	s_add_i32 m0, s35, 0x1a000
	v_mfma_f32_16x16x32_bf16 v[72:75], v[196:199], v[168:171], v[72:75]
	global_load_lds_dwordx4 v252, s[32:33]
	v_mfma_f32_16x16x32_bf16 v[80:83], v[196:199], v[176:179], v[80:83]
	ds_read_b128 v[128:131], v245 offset:0
	v_mfma_f32_16x16x32_bf16 v[80:83], v[200:203], v[180:183], v[80:83]
	ds_read_b128 v[132:135], v246 offset:0
	v_mfma_f32_16x16x32_bf16 v[84:87], v[208:211], v[180:183], v[84:87]
	ds_read_b128 v[136:139], v245 offset:2048
	v_mfma_f32_16x16x32_bf16 v[84:87], v[204:207], v[176:179], v[84:87]
	ds_read_b128 v[140:143], v246 offset:2048
	v_mfma_f32_16x16x32_bf16 v[92:95], v[204:207], v[188:191], v[92:95]
	ds_read_b128 v[144:147], v245 offset:4096
	v_mfma_f32_16x16x32_bf16 v[92:95], v[208:211], v[192:195], v[92:95]
	ds_read_b128 v[148:151], v246 offset:4096
	v_mfma_f32_16x16x32_bf16 v[88:91], v[200:203], v[192:195], v[88:91]
	ds_read_b128 v[152:155], v245 offset:6144
	v_mfma_f32_16x16x32_bf16 v[88:91], v[196:199], v[188:191], v[88:91]
	ds_read_b128 v[156:159], v246 offset:6144
	v_mfma_f32_16x16x32_bf16 v[96:99], v[212:215], v[160:163], v[96:99]
	ds_read_b128 v[196:199], v247 offset:0
	v_mfma_f32_16x16x32_bf16 v[96:99], v[216:219], v[164:167], v[96:99]
	ds_read_b128 v[200:203], v248 offset:0
	v_mfma_f32_16x16x32_bf16 v[100:103], v[224:227], v[164:167], v[100:103]
	ds_read_b128 v[204:207], v247 offset:2048
	v_mfma_f32_16x16x32_bf16 v[100:103], v[220:223], v[160:163], v[100:103]
	ds_read_b128 v[208:211], v248 offset:2048
	v_mfma_f32_16x16x32_bf16 v[108:111], v[220:223], v[168:171], v[108:111]
	s_add_u32 s30, s30, s4
	s_addc_u32 s31, s31, s5
	v_mfma_f32_16x16x32_bf16 v[108:111], v[224:227], v[172:175], v[108:111]
	s_add_u32 s56, s56, s4
	s_addc_u32 s57, s57, s5
	v_mfma_f32_16x16x32_bf16 v[104:107], v[216:219], v[172:175], v[104:107]
	s_add_u32 s32, s32, s4
	s_addc_u32 s33, s33, s5
	v_mfma_f32_16x16x32_bf16 v[104:107], v[212:215], v[168:171], v[104:107]
	s_add_u32 s58, s58, s4
	s_addc_u32 s59, s59, s5
	v_mfma_f32_16x16x32_bf16 v[112:115], v[212:215], v[176:179], v[112:115]
	v_mfma_f32_16x16x32_bf16 v[112:115], v[216:219], v[180:183], v[112:115]
	v_mfma_f32_16x16x32_bf16 v[116:119], v[224:227], v[180:183], v[116:119]
	v_mfma_f32_16x16x32_bf16 v[116:119], v[220:223], v[176:179], v[116:119]
	v_mfma_f32_16x16x32_bf16 v[124:127], v[220:223], v[188:191], v[124:127]
	v_mfma_f32_16x16x32_bf16 v[124:127], v[224:227], v[192:195], v[124:127]
	v_mfma_f32_16x16x32_bf16 v[120:123], v[216:219], v[192:195], v[120:123]
	v_mfma_f32_16x16x32_bf16 v[120:123], v[212:215], v[188:191], v[120:123]
	s_add_i32 s34, s34, -1
	s_cmp_lg_u32 s34, 1
	s_cbranch_scc1 .Lp6_nosw0
	s_add_u32 s45, s16, 1
	s_and_b32 s40, s45, 1
	s_lshl_b32 s4, s40, 8
	s_sub_u32 s4, 128, s4
	s_sub_u32 s5, 0, s40
	s_mul_i32 s8, s40, 11136
	s_add_u32 s30, s26, s8
	s_addc_u32 s31, s27, 0
	s_add_u32 s32, s28, s8
	s_addc_u32 s33, s29, 0
	s_add_u32 s56, s30, 0x160000
	s_addc_u32 s57, s31, 0
	s_add_u32 s58, s32, 0x160000
	s_addc_u32 s59, s33, 0

; #define PG8_STAGE(bufoff, gbase, voff) do { _Pragma("unroll") for (int _i = 0; _i < 2; ++_i) \
;         __builtin_amdgcn_global_load_lds((const unsigned*)((const char*)(gbase) + (voff)[_i]), (PG8_LAS unsigned*)(lds + (bufoff) + ldsw + _i * 8192), 16, 0, 0); } while (0)
; #define PG8_LDA(dst, b, h) do { _Pragma("unroll") for (int m = 0; m < 4; ++m) _Pragma("unroll") for (int k = 0; k < 2; ++k) dst[m][k] = *(const PG8_LAS bf16x8*)(lds + PG8_SA(b, h) + aoff + m * 2048 + k * 1024); } while (0)
; #define PG8_LDB(dst, b, h) do { _Pragma("unroll") for (int n = 0; n < 2; ++n) _Pragma("unroll") for (int k = 0; k < 2; ++k) dst[n][k] = *(const PG8_LAS bf16x8*)(lds + PG8_SB(b, h) + boff + n * 2048 + k * 1024); } while (0)
; #define PG8_MMA(ai, bj, At, Bt) do { __builtin_amdgcn_s_setprio(1); _Pragma("unroll") for (int m = 0; m < 4; ++m) _Pragma("unroll") for (int n = 0; n < 2; ++n) _Pragma("unroll") for (int k = 0; k < 2; ++k) \
;         acc[ai][bj][m][n] = __builtin_amdgcn_mfma_f32_16x16x32_bf16(Bt[n][k], At[m][k], acc[ai][bj][m][n], 0, 0, 0); __builtin_amdgcn_s_setprio(0); } while (0)
; #define PG8_WAIT_V(n) asm volatile("s_waitcnt vmcnt(" #n ")" ::: "memory")
; template <class Epi, class Sched, bool ALIGN_EPI = false, bool SP2 = false>
; __device__ __forceinline__ void gemm_phase(PG8_LAS unsigned char* lds, const Gemm g, const Sched& S, const Epi& E) {
;     ...
;             PG8_LDB(B0, 0, 0); PG8_LDB(B1, 0, 1); PG8_SCHED; PG8_LDA(At, 0, 0); PG8_STAGE(PG8_SA(1, 1), a1 + hstep, voffA);
;             PG8_WAIT_V(8); PG8_WAIT_L(0); PG8_BAR; PG8_MMA(0, 0, At, B0); PG8_MMA(0, 1, At, B1); PG8_BAR; PG8_SCHED;
;             PG8_LDA(At, 0, 1); PG8_STAGE(PG8_SB(0, 0), b2, voffB); PG8_STAGE(PG8_SB(0, 1), b2 + hstep, voffB); PG8_STAGE(PG8_SA(0, 0), a2, voffA);
;             PG8_WAIT_V(8); PG8_WAIT_L(0); PG8_BAR; PG8_MMA(1, 0, At, B0); PG8_MMA(1, 1, At, B1); PG8_BAR; PG8_SCHED;
;             PG8_LDB(B0, 1, 0); PG8_LDB(B1, 1, 1); PG8_SCHED; PG8_LDA(At, 1, 0); PG8_STAGE(PG8_SA(0, 1), a2 + hstep, voffA);
;             PG8_WAIT_V(8); PG8_WAIT_L(0); PG8_BAR; PG8_MMA(0, 0, At, B0); PG8_MMA(0, 1, At, B1); PG8_BAR; PG8_SCHED;
;             PG8_LDA(At, 1, 1); PG8_STAGE(PG8_SB(1, 0), b3, voffB); PG8_STAGE(PG8_SB(1, 1), b3 + hstep, voffB); PG8_STAGE(PG8_SA(1, 0), a3, voffA);
;             PG8_WAIT_V(8); PG8_WAIT_L(0); PG8_BAR; PG8_MMA(1, 0, At, B0); PG8_MMA(1, 1, At, B1); PG8_BAR; PG8_SCHED;
.Lp6_kloop1:
	s_waitcnt vmcnt(8)
	s_waitcnt lgkmcnt(0)
	s_barrier
	v_mfma_f32_16x16x32_bf16 v[0:3], v[196:199], v[128:131], v[0:3]
	ds_read_b128 v[212:215], v247 offset:16384
	v_mfma_f32_16x16x32_bf16 v[0:3], v[200:203], v[132:135], v[0:3]
	ds_read_b128 v[216:219], v248 offset:16384
	v_mfma_f32_16x16x32_bf16 v[4:7], v[208:211], v[132:135], v[4:7]
	ds_read_b128 v[220:223], v247 offset:18432
	v_mfma_f32_16x16x32_bf16 v[4:7], v[204:207], v[128:131], v[4:7]
	ds_read_b128 v[224:227], v248 offset:18432
	v_mfma_f32_16x16x32_bf16 v[12:15], v[204:207], v[136:139], v[12:15]
	ds_read_b128 v[160:163], v245 offset:16384
	v_mfma_f32_16x16x32_bf16 v[12:15], v[208:211], v[140:143], v[12:15]
	ds_read_b128 v[164:167], v246 offset:16384
	v_mfma_f32_16x16x32_bf16 v[8:11], v[200:203], v[140:143], v[8:11]
	ds_read_b128 v[168:171], v245 offset:18432
	v_mfma_f32_16x16x32_bf16 v[8:11], v[196:199], v[136:139], v[8:11]
	ds_read_b128 v[172:175], v246 offset:18432
	v_mfma_f32_16x16x32_bf16 v[16:19], v[196:199], v[144:147], v[16:19]
	ds_read_b128 v[176:179], v245 offset:20480
	v_mfma_f32_16x16x32_bf16 v[16:19], v[200:203], v[148:151], v[16:19]
	ds_read_b128 v[180:183], v246 offset:20480
	v_mfma_f32_16x16x32_bf16 v[20:23], v[208:211], v[148:151], v[20:23]
	ds_read_b128 v[188:191], v245 offset:22528
	v_mfma_f32_16x16x32_bf16 v[20:23], v[204:207], v[144:147], v[20:23]
	ds_read_b128 v[192:195], v246 offset:22528
	v_mfma_f32_16x16x32_bf16 v[28:31], v[204:207], v[152:155], v[28:31]
	v_mfma_f32_16x16x32_bf16 v[28:31], v[208:211], v[156:159], v[28:31]
	v_mfma_f32_16x16x32_bf16 v[24:27], v[200:203], v[156:159], v[24:27]
	v_mfma_f32_16x16x32_bf16 v[24:27], v[196:199], v[152:155], v[24:27]
	s_waitcnt lgkmcnt(8)
	v_mfma_f32_16x16x32_bf16 v[32:35], v[212:215], v[128:131], v[32:35]
	v_mfma_f32_16x16x32_bf16 v[32:35], v[216:219], v[132:135], v[32:35]
	s_add_i32 m0, s35, 0x0
	v_mfma_f32_16x16x32_bf16 v[36:39], v[224:227], v[132:135], v[36:39]
	global_load_lds_dwordx4 v249, s[30:31]
	v_mfma_f32_16x16x32_bf16 v[36:39], v[220:223], v[128:131], v[36:39]
	v_mfma_f32_16x16x32_bf16 v[44:47], v[220:223], v[136:139], v[44:47]
	s_add_i32 m0, s35, 0x2000
	v_mfma_f32_16x16x32_bf16 v[44:47], v[224:227], v[140:143], v[44:47]
	global_load_lds_dwordx4 v250, s[30:31]
	v_mfma_f32_16x16x32_bf16 v[40:43], v[216:219], v[140:143], v[40:43]
	v_mfma_f32_16x16x32_bf16 v[40:43], v[212:215], v[136:139], v[40:43]
	s_add_i32 m0, s35, 0x10000
	v_mfma_f32_16x16x32_bf16 v[48:51], v[212:215], v[144:147], v[48:51]
	global_load_lds_dwordx4 v251, s[32:33]
	v_mfma_f32_16x16x32_bf16 v[48:51], v[216:219], v[148:151], v[48:51]
	v_mfma_f32_16x16x32_bf16 v[52:55], v[224:227], v[148:151], v[52:55]
	s_add_i32 m0, s35, 0x12000
	v_mfma_f32_16x16x32_bf16 v[52:55], v[220:223], v[144:147], v[52:55]
	global_load_lds_dwordx4 v252, s[32:33]
	v_mfma_f32_16x16x32_bf16 v[60:63], v[220:223], v[152:155], v[60:63]
	v_mfma_f32_16x16x32_bf16 v[60:63], v[224:227], v[156:159], v[60:63]
	v_mfma_f32_16x16x32_bf16 v[56:59], v[216:219], v[156:159], v[56:59]
	v_mfma_f32_16x16x32_bf16 v[56:59], v[212:215], v[152:155], v[56:59]
	s_waitcnt vmcnt(8)
	s_waitcnt lgkmcnt(0)
	s_barrier
	v_mfma_f32_16x16x32_bf16 v[96:99], v[212:215], v[160:163], v[96:99]
	ds_read_b128 v[128:131], v245 offset:32768
	v_mfma_f32_16x16x32_bf16 v[96:99], v[216:219], v[164:167], v[96:99]
	ds_read_b128 v[132:135], v246 offset:32768
	v_mfma_f32_16x16x32_bf16 v[100:103], v[224:227], v[164:167], v[100:103]
	ds_read_b128 v[136:139], v245 offset:34816
	v_mfma_f32_16x16x32_bf16 v[100:103], v[220:223], v[160:163], v[100:103]
	ds_read_b128 v[140:143], v246 offset:34816
	v_mfma_f32_16x16x32_bf16 v[108:111], v[220:223], v[168:171], v[108:111]
	ds_read_b128 v[144:147], v245 offset:36864
	v_mfma_f32_16x16x32_bf16 v[108:111], v[224:227], v[172:175], v[108:111]
	ds_read_b128 v[148:151], v246 offset:36864
	v_mfma_f32_16x16x32_bf16 v[104:107], v[216:219], v[172:175], v[104:107]
	ds_read_b128 v[152:155], v245 offset:38912
	v_mfma_f32_16x16x32_bf16 v[104:107], v[212:215], v[168:171], v[104:107]
	ds_read_b128 v[156:159], v246 offset:38912
	v_mfma_f32_16x16x32_bf16 v[112:115], v[212:215], v[176:179], v[112:115]
	v_mfma_f32_16x16x32_bf16 v[112:115], v[216:219], v[180:183], v[112:115]
	v_mfma_f32_16x16x32_bf16 v[116:119], v[224:227], v[180:183], v[116:119]
	v_mfma_f32_16x16x32_bf16 v[116:119], v[220:223], v[176:179], v[116:119]
	v_mfma_f32_16x16x32_bf16 v[124:127], v[220:223], v[188:191], v[124:127]
	v_mfma_f32_16x16x32_bf16 v[124:127], v[224:227], v[192:195], v[124:127]
	v_mfma_f32_16x16x32_bf16 v[120:123], v[216:219], v[192:195], v[120:123]
	v_mfma_f32_16x16x32_bf16 v[120:123], v[212:215], v[188:191], v[120:123]
	v_mfma_f32_16x16x32_bf16 v[64:67], v[196:199], v[160:163], v[64:67]
	ds_read_b128 v[212:215], v247 offset:49152
	v_mfma_f32_16x16x32_bf16 v[64:67], v[200:203], v[164:167], v[64:67]
	ds_read_b128 v[216:219], v248 offset:49152
	v_mfma_f32_16x16x32_bf16 v[68:71], v[208:211], v[164:167], v[68:71]
	ds_read_b128 v[220:223], v247 offset:51200
	v_mfma_f32_16x16x32_bf16 v[68:71], v[204:207], v[160:163], v[68:71]
	ds_read_b128 v[224:227], v248 offset:51200
	v_mfma_f32_16x16x32_bf16 v[76:79], v[204:207], v[168:171], v[76:79]
	s_add_i32 m0, s35, 0x4000
	v_mfma_f32_16x16x32_bf16 v[76:79], v[208:211], v[172:175], v[76:79]
	global_load_lds_dwordx4 v249, s[56:57]
	v_mfma_f32_16x16x32_bf16 v[72:75], v[200:203], v[172:175], v[72:75]
	s_add_i32 m0, s35, 0x6000
	v_mfma_f32_16x16x32_bf16 v[72:75], v[196:199], v[168:171], v[72:75]
	global_load_lds_dwordx4 v250, s[56:57]
	v_mfma_f32_16x16x32_bf16 v[80:83], v[196:199], v[176:179], v[80:83]
	s_add_i32 m0, s35, 0x14000
	v_mfma_f32_16x16x32_bf16 v[80:83], v[200:203], v[180:183], v[80:83]
	global_load_lds_dwordx4 v251, s[58:59]
	v_mfma_f32_16x16x32_bf16 v[84:87], v[208:211], v[180:183], v[84:87]
	s_add_i32 m0, s35, 0x16000
	v_mfma_f32_16x16x32_bf16 v[84:87], v[204:207], v[176:179], v[84:87]
	global_load_lds_dwordx4 v252, s[58:59]
	v_mfma_f32_16x16x32_bf16 v[92:95], v[204:207], v[188:191], v[92:95]
	s_add_u32 s30, s30, s4
	s_addc_u32 s31, s31, s5
	v_mfma_f32_16x16x32_bf16 v[92:95], v[208:211], v[192:195], v[92:95]
	s_add_u32 s56, s56, s4
	s_addc_u32 s57, s57, s5
	v_mfma_f32_16x16x32_bf16 v[88:91], v[200:203], v[192:195], v[88:91]
	s_add_u32 s32, s32, s4
	s_addc_u32 s33, s33, s5
	v_mfma_f32_16x16x32_bf16 v[88:91], v[196:199], v[188:191], v[88:91]
	s_add_u32 s58, s58, s4
	s_addc_u32 s59, s59, s5
	s_waitcnt vmcnt(8)
	s_waitcnt lgkmcnt(0)
	s_barrier
; #define PG8_STAGE(bufoff, gbase, voff) do { _Pragma("unroll") for (int _i = 0; _i < 2; ++_i) \
;         __builtin_amdgcn_global_load_lds((const unsigned*)((const char*)(gbase) + (voff)[_i]), (PG8_LAS unsigned*)(lds + (bufoff) + ldsw + _i * 8192), 16, 0, 0); } while (0)
; #define PG8_LDA(dst, b, h) do { _Pragma("unroll") for (int m = 0; m < 4; ++m) _Pragma("unroll") for (int k = 0; k < 2; ++k) dst[m][k] = *(const PG8_LAS bf16x8*)(lds + PG8_SA(b, h) + aoff + m * 2048 + k * 1024); } while (0)
; #define PG8_LDB(dst, b, h) do { _Pragma("unroll") for (int n = 0; n < 2; ++n) _Pragma("unroll") for (int k = 0; k < 2; ++k) dst[n][k] = *(const PG8_LAS bf16x8*)(lds + PG8_SB(b, h) + boff + n * 2048 + k * 1024); } while (0)
; #define PG8_WAIT_V(n) asm volatile("s_waitcnt vmcnt(" #n ")" ::: "memory")
; #define PG8_WAIT_L(n) asm volatile("s_waitcnt lgkmcnt(" #n ")" ::: "memory")
; template <class Epi, class Sched, bool ALIGN_EPI = false, bool SP2 = false>
; __device__ __forceinline__ void gemm_phase(PG8_LAS unsigned char* lds, const Gemm g, const Sched& S, const Epi& E) {
;     ...
;             const char* a1 = cA + (size_t)(t + 1) * kstep;
;             const char* a2 = last ? nA : cA + (size_t)(t + 2) * kstep; const char* b2 = last ? nB : cB + (size_t)(t + 2) * kstep;
;             const char* a3 = a2 + kstep; const char* b3 = b2 + kstep;
;     ...
;             PG8_LDB(B0, 0, 0); PG8_LDB(B1, 0, 1); PG8_SCHED; PG8_LDA(At, 0, 0); PG8_STAGE(PG8_SA(1, 1), a1 + hstep, voffA);
;             PG8_WAIT_V(8); PG8_WAIT_L(0); PG8_BAR; PG8_MMA(0, 0, At, B0); PG8_MMA(0, 1, At, B1); PG8_BAR; PG8_SCHED;
;             PG8_LDA(At, 0, 1); PG8_STAGE(PG8_SB(0, 0), b2, voffB); PG8_STAGE(PG8_SB(0, 1), b2 + hstep, voffB); PG8_STAGE(PG8_SA(0, 0), a2, voffA);
;             PG8_WAIT_V(8); PG8_WAIT_L(0); PG8_BAR; PG8_MMA(1, 0, At, B0); PG8_MMA(1, 1, At, B1); PG8_BAR; PG8_SCHED;
;             PG8_LDB(B0, 1, 0); PG8_LDB(B1, 1, 1); PG8_SCHED; PG8_LDA(At, 1, 0); PG8_STAGE(PG8_SA(0, 1), a2 + hstep, voffA);
;             PG8_WAIT_V(8); PG8_WAIT_L(0); PG8_BAR; PG8_MMA(0, 0, At, B0); PG8_MMA(0, 1, At, B1); PG8_BAR; PG8_SCHED;
;             PG8_LDA(At, 1, 1); PG8_STAGE(PG8_SB(1, 0), b3, voffB); PG8_STAGE(PG8_SB(1, 1), b3 + hstep, voffB); PG8_STAGE(PG8_SA(1, 0), a3, voffA);
;             PG8_WAIT_V(8); PG8_WAIT_L(0); PG8_BAR; PG8_MMA(1, 0, At, B0); PG8_MMA(1, 1, At, B1); PG8_BAR; PG8_SCHED;
	v_mfma_f32_16x16x32_bf16 v[32:35], v[212:215], v[128:131], v[32:35]
	ds_read_b128 v[196:199], v247 offset:32768
	v_mfma_f32_16x16x32_bf16 v[32:35], v[216:219], v[132:135], v[32:35]
	ds_read_b128 v[200:203], v248 offset:32768
	v_mfma_f32_16x16x32_bf16 v[36:39], v[224:227], v[132:135], v[36:39]
	ds_read_b128 v[204:207], v247 offset:34816
	v_mfma_f32_16x16x32_bf16 v[36:39], v[220:223], v[128:131], v[36:39]
	ds_read_b128 v[208:211], v248 offset:34816
	v_mfma_f32_16x16x32_bf16 v[44:47], v[220:223], v[136:139], v[44:47]
	ds_read_b128 v[160:163], v245 offset:49152
	v_mfma_f32_16x16x32_bf16 v[44:47], v[224:227], v[140:143], v[44:47]
	ds_read_b128 v[164:167], v246 offset:49152
	v_mfma_f32_16x16x32_bf16 v[40:43], v[216:219], v[140:143], v[40:43]
	ds_read_b128 v[168:171], v245 offset:51200
	v_mfma_f32_16x16x32_bf16 v[40:43], v[212:215], v[136:139], v[40:43]
	ds_read_b128 v[172:175], v246 offset:51200
	v_mfma_f32_16x16x32_bf16 v[48:51], v[212:215], v[144:147], v[48:51]
	ds_read_b128 v[176:179], v245 offset:53248
	v_mfma_f32_16x16x32_bf16 v[48:51], v[216:219], v[148:151], v[48:51]
	ds_read_b128 v[180:183], v246 offset:53248
	v_mfma_f32_16x16x32_bf16 v[52:55], v[224:227], v[148:151], v[52:55]
	ds_read_b128 v[188:191], v245 offset:55296
	v_mfma_f32_16x16x32_bf16 v[52:55], v[220:223], v[144:147], v[52:55]
	ds_read_b128 v[192:195], v246 offset:55296
	v_mfma_f32_16x16x32_bf16 v[60:63], v[220:223], v[152:155], v[60:63]
	v_mfma_f32_16x16x32_bf16 v[60:63], v[224:227], v[156:159], v[60:63]
	v_mfma_f32_16x16x32_bf16 v[56:59], v[216:219], v[156:159], v[56:59]
	v_mfma_f32_16x16x32_bf16 v[56:59], v[212:215], v[152:155], v[56:59]
	s_waitcnt lgkmcnt(8)
	v_mfma_f32_16x16x32_bf16 v[0:3], v[196:199], v[128:131], v[0:3]
	v_mfma_f32_16x16x32_bf16 v[0:3], v[200:203], v[132:135], v[0:3]
	s_add_i32 m0, s35, 0x8000
	v_mfma_f32_16x16x32_bf16 v[4:7], v[208:211], v[132:135], v[4:7]
	global_load_lds_dwordx4 v249, s[30:31]
	v_mfma_f32_16x16x32_bf16 v[4:7], v[204:207], v[128:131], v[4:7]
	v_mfma_f32_16x16x32_bf16 v[12:15], v[204:207], v[136:139], v[12:15]
	s_add_i32 m0, s35, 0xa000
	v_mfma_f32_16x16x32_bf16 v[12:15], v[208:211], v[140:143], v[12:15]
	global_load_lds_dwordx4 v250, s[30:31]
	v_mfma_f32_16x16x32_bf16 v[8:11], v[200:203], v[140:143], v[8:11]
	v_mfma_f32_16x16x32_bf16 v[8:11], v[196:199], v[136:139], v[8:11]
	s_add_i32 m0, s35, 0x1c000
	v_mfma_f32_16x16x32_bf16 v[16:19], v[196:199], v[144:147], v[16:19]
	global_load_lds_dwordx4 v251, s[58:59]
	v_mfma_f32_16x16x32_bf16 v[16:19], v[200:203], v[148:151], v[16:19]
	v_mfma_f32_16x16x32_bf16 v[20:23], v[208:211], v[148:151], v[20:23]
	s_add_i32 m0, s35, 0x1e000
	v_mfma_f32_16x16x32_bf16 v[20:23], v[204:207], v[144:147], v[20:23]
	global_load_lds_dwordx4 v252, s[58:59]
	v_mfma_f32_16x16x32_bf16 v[28:31], v[204:207], v[152:155], v[28:31]
	v_mfma_f32_16x16x32_bf16 v[28:31], v[208:211], v[156:159], v[28:31]
	v_mfma_f32_16x16x32_bf16 v[24:27], v[200:203], v[156:159], v[24:27]
	v_mfma_f32_16x16x32_bf16 v[24:27], v[196:199], v[152:155], v[24:27]
	s_waitcnt vmcnt(8)
	s_waitcnt lgkmcnt(0)
	s_barrier
	v_mfma_f32_16x16x32_bf16 v[64:67], v[196:199], v[160:163], v[64:67]
	ds_read_b128 v[128:131], v245 offset:0
	v_mfma_f32_16x16x32_bf16 v[64:67], v[200:203], v[164:167], v[64:67]
	ds_read_b128 v[132:135], v246 offset:0
	v_mfma_f32_16x16x32_bf16 v[68:71], v[208:211], v[164:167], v[68:71]
	ds_read_b128 v[136:139], v245 offset:2048
	v_mfma_f32_16x16x32_bf16 v[68:71], v[204:207], v[160:163], v[68:71]
	ds_read_b128 v[140:143], v246 offset:2048
	v_mfma_f32_16x16x32_bf16 v[76:79], v[204:207], v[168:171], v[76:79]
	ds_read_b128 v[144:147], v245 offset:4096
	v_mfma_f32_16x16x32_bf16 v[76:79], v[208:211], v[172:175], v[76:79]
	ds_read_b128 v[148:151], v246 offset:4096
	v_mfma_f32_16x16x32_bf16 v[72:75], v[200:203], v[172:175], v[72:75]
	ds_read_b128 v[152:155], v245 offset:6144
	v_mfma_f32_16x16x32_bf16 v[72:75], v[196:199], v[168:171], v[72:75]
	ds_read_b128 v[156:159], v246 offset:6144
	v_mfma_f32_16x16x32_bf16 v[80:83], v[196:199], v[176:179], v[80:83]
	v_mfma_f32_16x16x32_bf16 v[80:83], v[200:203], v[180:183], v[80:83]
	v_mfma_f32_16x16x32_bf16 v[84:87], v[208:211], v[180:183], v[84:87]
	v_mfma_f32_16x16x32_bf16 v[84:87], v[204:207], v[176:179], v[84:87]
	v_mfma_f32_16x16x32_bf16 v[92:95], v[204:207], v[188:191], v[92:95]
	v_mfma_f32_16x16x32_bf16 v[92:95], v[208:211], v[192:195], v[92:95]
	v_mfma_f32_16x16x32_bf16 v[88:91], v[200:203], v[192:195], v[88:91]
	v_mfma_f32_16x16x32_bf16 v[88:91], v[196:199], v[188:191], v[88:91]
	v_mfma_f32_16x16x32_bf16 v[96:99], v[212:215], v[160:163], v[96:99]
	ds_read_b128 v[196:199], v247 offset:0
	v_mfma_f32_16x16x32_bf16 v[96:99], v[216:219], v[164:167], v[96:99]
	ds_read_b128 v[200:203], v248 offset:0
	v_mfma_f32_16x16x32_bf16 v[100:103], v[224:227], v[164:167], v[100:103]
	ds_read_b128 v[204:207], v247 offset:2048
	v_mfma_f32_16x16x32_bf16 v[100:103], v[220:223], v[160:163], v[100:103]
	ds_read_b128 v[208:211], v248 offset:2048
	v_mfma_f32_16x16x32_bf16 v[108:111], v[220:223], v[168:171], v[108:111]
	s_add_i32 m0, s35, 0xc000
	v_mfma_f32_16x16x32_bf16 v[108:111], v[224:227], v[172:175], v[108:111]
	global_load_lds_dwordx4 v249, s[56:57]
	v_mfma_f32_16x16x32_bf16 v[104:107], v[216:219], v[172:175], v[104:107]
	s_add_i32 m0, s35, 0xe000
	v_mfma_f32_16x16x32_bf16 v[104:107], v[212:215], v[168:171], v[104:107]
	global_load_lds_dwordx4 v250, s[56:57]
	v_mfma_f32_16x16x32_bf16 v[112:115], v[212:215], v[176:179], v[112:115]
	s_add_i32 m0, s35, 0x18000
	v_mfma_f32_16x16x32_bf16 v[112:115], v[216:219], v[180:183], v[112:115]
	global_load_lds_dwordx4 v251, s[32:33]
	v_mfma_f32_16x16x32_bf16 v[116:119], v[224:227], v[180:183], v[116:119]
	s_add_i32 m0, s35, 0x1a000
	v_mfma_f32_16x16x32_bf16 v[116:119], v[220:223], v[176:179], v[116:119]
	global_load_lds_dwordx4 v252, s[32:33]
	v_mfma_f32_16x16x32_bf16 v[124:127], v[220:223], v[188:191], v[124:127]
	s_add_u32 s30, s30, s4
	s_addc_u32 s31, s31, s5
	v_mfma_f32_16x16x32_bf16 v[124:127], v[224:227], v[192:195], v[124:127]
	s_add_u32 s56, s56, s4
	s_addc_u32 s57, s57, s5
	v_mfma_f32_16x16x32_bf16 v[120:123], v[216:219], v[192:195], v[120:123]
	s_add_u32 s32, s32, s4
	s_addc_u32 s33, s33, s5
	v_mfma_f32_16x16x32_bf16 v[120:123], v[212:215], v[188:191], v[120:123]
	s_add_u32 s58, s58, s4
	s_addc_u32 s59, s59, s5
	s_add_i32 s34, s34, -1
	s_cmp_lg_u32 s34, 1
	s_cbranch_scc1 .Lp6_nosw1
	s_add_u32 s45, s16, 1
	s_and_b32 s40, s45, 1
	s_lshl_b32 s4, s40, 8
	s_sub_u32 s4, 128, s4
	s_sub_u32 s5, 0, s40
	s_mul_i32 s8, s40, 11136
	s_add_u32 s30, s26, s8
	s_addc_u32 s31, s27, 0
	s_add_u32 s32, s28, s8
	s_addc_u32 s33, s29, 0
	s_add_u32 s56, s30, 0x160000
	s_addc_u32 s57, s31, 0
	s_add_u32 s58, s32, 0x160000
	s_addc_u32 s59, s33, 0

;     __device__ __forceinline__ void operator()(const f32x4 (&acc)[2][2][4][2], const Unit& u, int wr, int wc, int fr, int fq) const {
;     ...
;             u32x4 raw[2][4][2];
; #pragma unroll
;             for (int ai = 0; ai < 2; ++ai)
; #pragma unroll
;                 for (int m = 0; m < 4; ++m) { const int row = u.pm * BM + ai * HALF + wr * 64 + m * 16 + fr; const size_t off = (size_t)row * ldc + col0;
; #pragma unroll
;                     for (int bj = 0; bj < 2; ++bj) raw[ai][m][bj] = *(const u32x4*)((const bf16_t*)base + off + bj * HALF); }
;             asm volatile("" ::: "memory");
; #pragma unroll
;             for (int ai = 0; ai < 2; ++ai)
; #pragma unroll
;                 for (int m = 0; m < 4; ++m) { const int row = u.pm * BM + ai * HALF + wr * 64 + m * 16 + fr; const size_t off = (size_t)row * ldc + col0; float s = 0.f;
; #pragma unroll
;                     for (int bj = 0; bj < 2; ++bj) { const u32x4 r = raw[ai][m][bj];
;                         const f32x4 b0 = {__uint_as_float(r.x << 16), __uint_as_float(r.x & 0xffff0000u), __uint_as_float(r.y << 16), __uint_as_float(r.y & 0xffff0000u)};
;                         const f32x4 b1 = {__uint_as_float(r.z << 16), __uint_as_float(r.z & 0xffff0000u), __uint_as_float(r.w << 16), __uint_as_float(r.w & 0xffff0000u)};
;                         tail(b0, b1, acc[ai][bj][m][0], acc[ai][bj][m][1], out + off + bj * HALF, s); }
.Lp6_kdone:
	s_waitcnt lgkmcnt(0)
	s_nop 7
	s_nop 7
	v_and_b32_e32 v254, 63, v185
	v_and_b32_e32 v255, 15, v254
	v_lshrrev_b32_e32 v234, 4, v254
	s_lshl_b32 s40, s37, 6
	v_add_u32_e32 v255, s40, v255
	v_lshlrev_b32_e32 v230, 2, v255
	v_lshlrev_b32_e32 v228, 12, v255
	v_lshlrev_b32_e32 v229, 13, v255
	s_lshl_b32 s41, s38, 6
	v_lshl_add_u32 v228, v234, 4, v228
	v_add_u32_e32 v228, s41, v228
	s_lshl_b32 s41, s38, 7
	v_lshl_add_u32 v229, v234, 5, v229
	v_add_u32_e32 v229, s41, v229
	v_mov_b32_e32 v231, 0x358637bd
	v_xor_b32_e32 v232, 16, v254
	v_lshlrev_b32_e32 v232, 2, v232
	v_xor_b32_e32 v233, 32, v254
	v_lshlrev_b32_e32 v233, 2, v233
	s_lshl_b32 s40, s17, 20
	s_lshl_b32 s41, s18, 9
	s_add_u32 s40, s40, s41
	s_add_u32 s48, s76, 0x6800000
	s_addc_u32 s49, s77, 0
	s_add_u32 s48, s48, s40
	s_addc_u32 s49, s49, 0
	s_lshl_b32 s40, s17, 10
	s_add_u32 s40, s40, 0x10000
	s_add_u32 s50, s76, s40
	s_addc_u32 s51, s77, 0
	v_readlane_b32 s52, v244, 2
	v_readlane_b32 s53, v244, 3
	s_lshl_b32 s40, s17, 21
	s_lshl_b32 s41, s18, 10
	s_add_u32 s40, s40, s41
	s_add_u32 s52, s52, s40
	s_addc_u32 s53, s53, 0
	s_lshl_b32 s40, s17, 6
	s_add_u32 s40, s40, 0x28000
	s_add_u32 s54, s76, s40
	s_addc_u32 s55, s77, 0
	v_add_u32_e32 v234, 0x0, v228
	global_load_dwordx4 v[128:131], v234, s[48:49] offset:0
	global_load_dwordx4 v[132:135], v234, s[48:49] offset:256
	v_add_u32_e32 v234, 0x10000, v228
	global_load_dwordx4 v[136:139], v234, s[48:49] offset:0
	global_load_dwordx4 v[140:143], v234, s[48:49] offset:256
	v_add_u32_e32 v234, 0x20000, v228
	global_load_dwordx4 v[144:147], v234, s[48:49] offset:0
	global_load_dwordx4 v[148:151], v234, s[48:49] offset:256
	v_add_u32_e32 v234, 0x30000, v228
	global_load_dwordx4 v[152:155], v234, s[48:49] offset:0
	global_load_dwordx4 v[156:159], v234, s[48:49] offset:256
	v_add_u32_e32 v234, 0x80000, v228
	global_load_dwordx4 v[160:163], v234, s[48:49] offset:0
	global_load_dwordx4 v[164:167], v234, s[48:49] offset:256
	v_add_u32_e32 v234, 0x90000, v228
	global_load_dwordx4 v[168:171], v234, s[48:49] offset:0
	global_load_dwordx4 v[172:175], v234, s[48:49] offset:256
	v_add_u32_e32 v234, 0xa0000, v228
	global_load_dwordx4 v[176:179], v234, s[48:49] offset:0
	global_load_dwordx4 v[180:183], v234, s[48:49] offset:256
	v_add_u32_e32 v234, 0xb0000, v228
	global_load_dwordx4 v[188:191], v234, s[48:49] offset:0
	global_load_dwordx4 v[192:195], v234, s[48:49] offset:256
	s_waitcnt vmcnt(0)
	v_lshlrev_b32_e32 v254, 16, v128
	v_and_b32_e32 v255, 0xffff0000, v128
	v_add_f32_e32 v0, v0, v254
	v_add_f32_e32 v1, v1, v255
	v_mul_f32_e32 v238, v0, v0
	v_fmac_f32_e32 v238, v1, v1
	v_lshlrev_b32_e32 v254, 16, v129
	v_and_b32_e32 v255, 0xffff0000, v129
	v_add_f32_e32 v2, v2, v254
	v_add_f32_e32 v3, v3, v255
	v_fmac_f32_e32 v238, v2, v2
	v_fmac_f32_e32 v238, v3, v3
	v_lshlrev_b32_e32 v254, 16, v130
	v_and_b32_e32 v255, 0xffff0000, v130
	v_add_f32_e32 v4, v4, v254
	v_add_f32_e32 v5, v5, v255
	v_fmac_f32_e32 v238, v4, v4
	v_fmac_f32_e32 v238, v5, v5
	v_lshlrev_b32_e32 v254, 16, v131
	v_and_b32_e32 v255, 0xffff0000, v131
	v_add_f32_e32 v6, v6, v254
	v_add_f32_e32 v7, v7, v255
	v_fmac_f32_e32 v238, v6, v6
	v_fmac_f32_e32 v238, v7, v7
	v_lshlrev_b32_e32 v254, 16, v132
	v_and_b32_e32 v255, 0xffff0000, v132
	v_add_f32_e32 v32, v32, v254
	v_add_f32_e32 v33, v33, v255
	v_fmac_f32_e32 v238, v32, v32
	v_fmac_f32_e32 v238, v33, v33
	v_lshlrev_b32_e32 v254, 16, v133
	v_and_b32_e32 v255, 0xffff0000, v133
	v_add_f32_e32 v34, v34, v254
	v_add_f32_e32 v35, v35, v255
	v_fmac_f32_e32 v238, v34, v34
	v_fmac_f32_e32 v238, v35, v35
	v_lshlrev_b32_e32 v254, 16, v134
	v_and_b32_e32 v255, 0xffff0000, v134
	v_add_f32_e32 v36, v36, v254
	v_add_f32_e32 v37, v37, v255
	v_fmac_f32_e32 v238, v36, v36
	v_fmac_f32_e32 v238, v37, v37
	v_lshlrev_b32_e32 v254, 16, v135
	v_and_b32_e32 v255, 0xffff0000, v135
	v_add_f32_e32 v38, v38, v254
	v_add_f32_e32 v39, v39, v255
	v_fmac_f32_e32 v238, v38, v38
	v_fmac_f32_e32 v238, v39, v39
	v_lshlrev_b32_e32 v254, 16, v136
	v_and_b32_e32 v255, 0xffff0000, v136
	v_add_f32_e32 v8, v8, v254
	v_add_f32_e32 v9, v9, v255
	v_mul_f32_e32 v239, v8, v8
	v_fmac_f32_e32 v239, v9, v9
	v_lshlrev_b32_e32 v254, 16, v137
	v_and_b32_e32 v255, 0xffff0000, v137
	v_add_f32_e32 v10, v10, v254
	v_add_f32_e32 v11, v11, v255
	v_fmac_f32_e32 v239, v10, v10
	v_fmac_f32_e32 v239, v11, v11
	v_lshlrev_b32_e32 v254, 16, v138
	v_and_b32_e32 v255, 0xffff0000, v138
	v_add_f32_e32 v12, v12, v254
	v_add_f32_e32 v13, v13, v255
	v_fmac_f32_e32 v239, v12, v12
	v_fmac_f32_e32 v239, v13, v13
	v_lshlrev_b32_e32 v254, 16, v139
	v_and_b32_e32 v255, 0xffff0000, v139
	v_add_f32_e32 v14, v14, v254
	v_add_f32_e32 v15, v15, v255
	v_fmac_f32_e32 v239, v14, v14
	v_fmac_f32_e32 v239, v15, v15
	v_lshlrev_b32_e32 v254, 16, v140
	v_and_b32_e32 v255, 0xffff0000, v140
	v_add_f32_e32 v40, v40, v254
	v_add_f32_e32 v41, v41, v255
	v_fmac_f32_e32 v239, v40, v40
	v_fmac_f32_e32 v239, v41, v41
	v_lshlrev_b32_e32 v254, 16, v141
	v_and_b32_e32 v255, 0xffff0000, v141
	v_add_f32_e32 v42, v42, v254
	v_add_f32_e32 v43, v43, v255
	v_fmac_f32_e32 v239, v42, v42
	v_fmac_f32_e32 v239, v43, v43
	v_lshlrev_b32_e32 v254, 16, v142
	v_and_b32_e32 v255, 0xffff0000, v142
	v_add_f32_e32 v44, v44, v254
	v_add_f32_e32 v45, v45, v255
	v_fmac_f32_e32 v239, v44, v44
	v_fmac_f32_e32 v239, v45, v45
	v_lshlrev_b32_e32 v254, 16, v143
	v_and_b32_e32 v255, 0xffff0000, v143
	v_add_f32_e32 v46, v46, v254
	v_add_f32_e32 v47, v47, v255
	v_fmac_f32_e32 v239, v46, v46
	v_fmac_f32_e32 v239, v47, v47
	v_lshlrev_b32_e32 v254, 16, v144
	v_and_b32_e32 v255, 0xffff0000, v144
	v_add_f32_e32 v16, v16, v254
	v_add_f32_e32 v17, v17, v255
	v_mul_f32_e32 v240, v16, v16
;     __device__ __forceinline__ void tail(const f32x4& b0, const f32x4& b1, const f32x4& a0, const f32x4& a1, bf16_t* dst, float& s) const {
;         const f32x4 o0 = b0 + a0, o1 = b1 + a1;
;         s += ((o0[0] * o0[0] + o0[1] * o0[1]) + (o0[2] * o0[2] + o0[3] * o0[3])) + ((o1[0] * o1[0] + o1[1] * o1[1]) + (o1[2] * o1[2] + o1[3] * o1[3]));
;     __device__ __forceinline__ void operator()(const f32x4 (&acc)[2][2][4][2], const Unit& u, int wr, int wc, int fr, int fq) const {
;     ...
;                     for (int bj = 0; bj < 2; ++bj) { const u32x4 r = raw[ai][m][bj];
;                         const f32x4 b0 = {__uint_as_float(r.x << 16), __uint_as_float(r.x & 0xffff0000u), __uint_as_float(r.y << 16), __uint_as_float(r.y & 0xffff0000u)};
;                         const f32x4 b1 = {__uint_as_float(r.z << 16), __uint_as_float(r.z & 0xffff0000u), __uint_as_float(r.w << 16), __uint_as_float(r.w & 0xffff0000u)};
;                         tail(b0, b1, acc[ai][bj][m][0], acc[ai][bj][m][1], out + off + bj * HALF, s); }
	v_fmac_f32_e32 v240, v17, v17
	v_lshlrev_b32_e32 v254, 16, v145
	v_and_b32_e32 v255, 0xffff0000, v145
	v_add_f32_e32 v18, v18, v254
	v_add_f32_e32 v19, v19, v255
	v_fmac_f32_e32 v240, v18, v18
	v_fmac_f32_e32 v240, v19, v19
	v_lshlrev_b32_e32 v254, 16, v146
	v_and_b32_e32 v255, 0xffff0000, v146
	v_add_f32_e32 v20, v20, v254
	v_add_f32_e32 v21, v21, v255
	v_fmac_f32_e32 v240, v20, v20
	v_fmac_f32_e32 v240, v21, v21
	v_lshlrev_b32_e32 v254, 16, v147
	v_and_b32_e32 v255, 0xffff0000, v147
	v_add_f32_e32 v22, v22, v254
	v_add_f32_e32 v23, v23, v255
	v_fmac_f32_e32 v240, v22, v22
	v_fmac_f32_e32 v240, v23, v23
	v_lshlrev_b32_e32 v254, 16, v148
	v_and_b32_e32 v255, 0xffff0000, v148
	v_add_f32_e32 v48, v48, v254
	v_add_f32_e32 v49, v49, v255
	v_fmac_f32_e32 v240, v48, v48
	v_fmac_f32_e32 v240, v49, v49
	v_lshlrev_b32_e32 v254, 16, v149
	v_and_b32_e32 v255, 0xffff0000, v149
	v_add_f32_e32 v50, v50, v254
	v_add_f32_e32 v51, v51, v255
	v_fmac_f32_e32 v240, v50, v50
	v_fmac_f32_e32 v240, v51, v51
	v_lshlrev_b32_e32 v254, 16, v150
	v_and_b32_e32 v255, 0xffff0000, v150
	v_add_f32_e32 v52, v52, v254
	v_add_f32_e32 v53, v53, v255
	v_fmac_f32_e32 v240, v52, v52
	v_fmac_f32_e32 v240, v53, v53
	v_lshlrev_b32_e32 v254, 16, v151
	v_and_b32_e32 v255, 0xffff0000, v151
	v_add_f32_e32 v54, v54, v254
	v_add_f32_e32 v55, v55, v255
	v_fmac_f32_e32 v240, v54, v54
	v_fmac_f32_e32 v240, v55, v55
	v_lshlrev_b32_e32 v254, 16, v152
	v_and_b32_e32 v255, 0xffff0000, v152
	v_add_f32_e32 v24, v24, v254
	v_add_f32_e32 v25, v25, v255
	v_mul_f32_e32 v241, v24, v24
	v_fmac_f32_e32 v241, v25, v25
	v_lshlrev_b32_e32 v254, 16, v153
	v_and_b32_e32 v255, 0xffff0000, v153
	v_add_f32_e32 v26, v26, v254
	v_add_f32_e32 v27, v27, v255
	v_fmac_f32_e32 v241, v26, v26
	v_fmac_f32_e32 v241, v27, v27
	v_lshlrev_b32_e32 v254, 16, v154
	v_and_b32_e32 v255, 0xffff0000, v154
	v_add_f32_e32 v28, v28, v254
	v_add_f32_e32 v29, v29, v255
	v_fmac_f32_e32 v241, v28, v28
	v_fmac_f32_e32 v241, v29, v29
	v_lshlrev_b32_e32 v254, 16, v155
	v_and_b32_e32 v255, 0xffff0000, v155
	v_add_f32_e32 v30, v30, v254
	v_add_f32_e32 v31, v31, v255
	v_fmac_f32_e32 v241, v30, v30
	v_fmac_f32_e32 v241, v31, v31
	v_lshlrev_b32_e32 v254, 16, v156
	v_and_b32_e32 v255, 0xffff0000, v156
	v_add_f32_e32 v56, v56, v254
	v_add_f32_e32 v57, v57, v255
	v_fmac_f32_e32 v241, v56, v56
	v_fmac_f32_e32 v241, v57, v57
	v_lshlrev_b32_e32 v254, 16, v157
	v_and_b32_e32 v255, 0xffff0000, v157
	v_add_f32_e32 v58, v58, v254
	v_add_f32_e32 v59, v59, v255
	v_fmac_f32_e32 v241, v58, v58
	v_fmac_f32_e32 v241, v59, v59
	v_lshlrev_b32_e32 v254, 16, v158
	v_and_b32_e32 v255, 0xffff0000, v158
	v_add_f32_e32 v60, v60, v254
	v_add_f32_e32 v61, v61, v255
	v_fmac_f32_e32 v241, v60, v60
	v_fmac_f32_e32 v241, v61, v61
	v_lshlrev_b32_e32 v254, 16, v159
	v_and_b32_e32 v255, 0xffff0000, v159
	v_add_f32_e32 v62, v62, v254
	v_add_f32_e32 v63, v63, v255
	v_fmac_f32_e32 v241, v62, v62
	v_fmac_f32_e32 v241, v63, v63
	v_lshlrev_b32_e32 v254, 16, v160
	v_and_b32_e32 v255, 0xffff0000, v160
	v_add_f32_e32 v64, v64, v254
	v_add_f32_e32 v65, v65, v255
	v_mul_f32_e32 v242, v64, v64
	v_fmac_f32_e32 v242, v65, v65
	v_lshlrev_b32_e32 v254, 16, v161
	v_and_b32_e32 v255, 0xffff0000, v161
	v_add_f32_e32 v66, v66, v254
	v_add_f32_e32 v67, v67, v255
	v_fmac_f32_e32 v242, v66, v66
	v_fmac_f32_e32 v242, v67, v67
	v_lshlrev_b32_e32 v254, 16, v162
	v_and_b32_e32 v255, 0xffff0000, v162
	v_add_f32_e32 v68, v68, v254
	v_add_f32_e32 v69, v69, v255
	v_fmac_f32_e32 v242, v68, v68
	v_fmac_f32_e32 v242, v69, v69
	v_lshlrev_b32_e32 v254, 16, v163
	v_and_b32_e32 v255, 0xffff0000, v163
	v_add_f32_e32 v70, v70, v254
	v_add_f32_e32 v71, v71, v255
	v_fmac_f32_e32 v242, v70, v70
	v_fmac_f32_e32 v242, v71, v71
	v_lshlrev_b32_e32 v254, 16, v164
	v_and_b32_e32 v255, 0xffff0000, v164
	v_add_f32_e32 v96, v96, v254
	v_add_f32_e32 v97, v97, v255
	v_fmac_f32_e32 v242, v96, v96
	v_fmac_f32_e32 v242, v97, v97
	v_lshlrev_b32_e32 v254, 16, v165
	v_and_b32_e32 v255, 0xffff0000, v165
	v_add_f32_e32 v98, v98, v254
	v_add_f32_e32 v99, v99, v255
	v_fmac_f32_e32 v242, v98, v98
	v_fmac_f32_e32 v242, v99, v99
	v_lshlrev_b32_e32 v254, 16, v166
	v_and_b32_e32 v255, 0xffff0000, v166
	v_add_f32_e32 v100, v100, v254
	v_add_f32_e32 v101, v101, v255
	v_fmac_f32_e32 v242, v100, v100
	v_fmac_f32_e32 v242, v101, v101
	v_lshlrev_b32_e32 v254, 16, v167
	v_and_b32_e32 v255, 0xffff0000, v167
	v_add_f32_e32 v102, v102, v254
	v_add_f32_e32 v103, v103, v255
	v_fmac_f32_e32 v242, v102, v102
	v_fmac_f32_e32 v242, v103, v103
	v_lshlrev_b32_e32 v254, 16, v168
	v_and_b32_e32 v255, 0xffff0000, v168
	v_add_f32_e32 v72, v72, v254
	v_add_f32_e32 v73, v73, v255
	v_mul_f32_e32 v243, v72, v72
	v_fmac_f32_e32 v243, v73, v73
	v_lshlrev_b32_e32 v254, 16, v169
	v_and_b32_e32 v255, 0xffff0000, v169
	v_add_f32_e32 v74, v74, v254
	v_add_f32_e32 v75, v75, v255
	v_fmac_f32_e32 v243, v74, v74
	v_fmac_f32_e32 v243, v75, v75
	v_lshlrev_b32_e32 v254, 16, v170
	v_and_b32_e32 v255, 0xffff0000, v170
	v_add_f32_e32 v76, v76, v254
	v_add_f32_e32 v77, v77, v255
	v_fmac_f32_e32 v243, v76, v76
	v_fmac_f32_e32 v243, v77, v77
	v_lshlrev_b32_e32 v254, 16, v171
	v_and_b32_e32 v255, 0xffff0000, v171
	v_add_f32_e32 v78, v78, v254
	v_add_f32_e32 v79, v79, v255
	v_fmac_f32_e32 v243, v78, v78
	v_fmac_f32_e32 v243, v79, v79
	v_lshlrev_b32_e32 v254, 16, v172
	v_and_b32_e32 v255, 0xffff0000, v172
	v_add_f32_e32 v104, v104, v254
	v_add_f32_e32 v105, v105, v255
	v_fmac_f32_e32 v243, v104, v104
	v_fmac_f32_e32 v243, v105, v105
	v_lshlrev_b32_e32 v254, 16, v173
	v_and_b32_e32 v255, 0xffff0000, v173
	v_add_f32_e32 v106, v106, v254
	v_add_f32_e32 v107, v107, v255
	v_fmac_f32_e32 v243, v106, v106
;     __device__ __forceinline__ void operator()(const f32x4 (&acc)[2][2][4][2], const Unit& u, int wr, int wc, int fr, int fq) const {
;     ...
;                     for (int bj = 0; bj < 2; ++bj) { const u32x4 r = raw[ai][m][bj];
;                         const f32x4 b0 = {__uint_as_float(r.x << 16), __uint_as_float(r.x & 0xffff0000u), __uint_as_float(r.y << 16), __uint_as_float(r.y & 0xffff0000u)};
;                         const f32x4 b1 = {__uint_as_float(r.z << 16), __uint_as_float(r.z & 0xffff0000u), __uint_as_float(r.w << 16), __uint_as_float(r.w & 0xffff0000u)};
;                         tail(b0, b1, acc[ai][bj][m][0], acc[ai][bj][m][1], out + off + bj * HALF, s); }
;                     s += __shfl_xor(s, 16); s += __shfl_xor(s, 32);
;                     if (fq == 0) atomicAdd(ss + row, s); }
	v_fmac_f32_e32 v243, v107, v107
	v_lshlrev_b32_e32 v254, 16, v174
	v_and_b32_e32 v255, 0xffff0000, v174
	v_add_f32_e32 v108, v108, v254
	v_add_f32_e32 v109, v109, v255
	v_fmac_f32_e32 v243, v108, v108
	v_fmac_f32_e32 v243, v109, v109
	v_lshlrev_b32_e32 v254, 16, v175
	v_and_b32_e32 v255, 0xffff0000, v175
	v_add_f32_e32 v110, v110, v254
	v_add_f32_e32 v111, v111, v255
	v_fmac_f32_e32 v243, v110, v110
	v_fmac_f32_e32 v243, v111, v111
	v_lshlrev_b32_e32 v254, 16, v176
	v_and_b32_e32 v255, 0xffff0000, v176
	v_add_f32_e32 v80, v80, v254
	v_add_f32_e32 v81, v81, v255
	v_mul_f32_e32 v226, v80, v80
	v_fmac_f32_e32 v226, v81, v81
	v_lshlrev_b32_e32 v254, 16, v177
	v_and_b32_e32 v255, 0xffff0000, v177
	v_add_f32_e32 v82, v82, v254
	v_add_f32_e32 v83, v83, v255
	v_fmac_f32_e32 v226, v82, v82
	v_fmac_f32_e32 v226, v83, v83
	v_lshlrev_b32_e32 v254, 16, v178
	v_and_b32_e32 v255, 0xffff0000, v178
	v_add_f32_e32 v84, v84, v254
	v_add_f32_e32 v85, v85, v255
	v_fmac_f32_e32 v226, v84, v84
	v_fmac_f32_e32 v226, v85, v85
	v_lshlrev_b32_e32 v254, 16, v179
	v_and_b32_e32 v255, 0xffff0000, v179
	v_add_f32_e32 v86, v86, v254
	v_add_f32_e32 v87, v87, v255
	v_fmac_f32_e32 v226, v86, v86
	v_fmac_f32_e32 v226, v87, v87
	v_lshlrev_b32_e32 v254, 16, v180
	v_and_b32_e32 v255, 0xffff0000, v180
	v_add_f32_e32 v112, v112, v254
	v_add_f32_e32 v113, v113, v255
	v_fmac_f32_e32 v226, v112, v112
	v_fmac_f32_e32 v226, v113, v113
	v_lshlrev_b32_e32 v254, 16, v181
	v_and_b32_e32 v255, 0xffff0000, v181
	v_add_f32_e32 v114, v114, v254
	v_add_f32_e32 v115, v115, v255
	v_fmac_f32_e32 v226, v114, v114
	v_fmac_f32_e32 v226, v115, v115
	v_lshlrev_b32_e32 v254, 16, v182
	v_and_b32_e32 v255, 0xffff0000, v182
	v_add_f32_e32 v116, v116, v254
	v_add_f32_e32 v117, v117, v255
	v_fmac_f32_e32 v226, v116, v116
	v_fmac_f32_e32 v226, v117, v117
	v_lshlrev_b32_e32 v254, 16, v183
	v_and_b32_e32 v255, 0xffff0000, v183
	v_add_f32_e32 v118, v118, v254
	v_add_f32_e32 v119, v119, v255
	v_fmac_f32_e32 v226, v118, v118
	v_fmac_f32_e32 v226, v119, v119
	v_lshlrev_b32_e32 v254, 16, v188
	v_and_b32_e32 v255, 0xffff0000, v188
	v_add_f32_e32 v88, v88, v254
	v_add_f32_e32 v89, v89, v255
	v_mul_f32_e32 v227, v88, v88
	v_fmac_f32_e32 v227, v89, v89
	v_lshlrev_b32_e32 v254, 16, v189
	v_and_b32_e32 v255, 0xffff0000, v189
	v_add_f32_e32 v90, v90, v254
	v_add_f32_e32 v91, v91, v255
	v_fmac_f32_e32 v227, v90, v90
	v_fmac_f32_e32 v227, v91, v91
	v_lshlrev_b32_e32 v254, 16, v190
	v_and_b32_e32 v255, 0xffff0000, v190
	v_add_f32_e32 v92, v92, v254
	v_add_f32_e32 v93, v93, v255
	v_fmac_f32_e32 v227, v92, v92
	v_fmac_f32_e32 v227, v93, v93
	v_lshlrev_b32_e32 v254, 16, v191
	v_and_b32_e32 v255, 0xffff0000, v191
	v_add_f32_e32 v94, v94, v254
	v_add_f32_e32 v95, v95, v255
	v_fmac_f32_e32 v227, v94, v94
	v_fmac_f32_e32 v227, v95, v95
	v_lshlrev_b32_e32 v254, 16, v192
	v_and_b32_e32 v255, 0xffff0000, v192
	v_add_f32_e32 v120, v120, v254
	v_add_f32_e32 v121, v121, v255
	v_fmac_f32_e32 v227, v120, v120
	v_fmac_f32_e32 v227, v121, v121
	v_lshlrev_b32_e32 v254, 16, v193
	v_and_b32_e32 v255, 0xffff0000, v193
	v_add_f32_e32 v122, v122, v254
	v_add_f32_e32 v123, v123, v255
	v_fmac_f32_e32 v227, v122, v122
	v_fmac_f32_e32 v227, v123, v123
	v_lshlrev_b32_e32 v254, 16, v194
	v_and_b32_e32 v255, 0xffff0000, v194
	v_add_f32_e32 v124, v124, v254
	v_add_f32_e32 v125, v125, v255
	v_fmac_f32_e32 v227, v124, v124
	v_fmac_f32_e32 v227, v125, v125
	v_lshlrev_b32_e32 v254, 16, v195
	v_and_b32_e32 v255, 0xffff0000, v195
	v_add_f32_e32 v126, v126, v254
	v_add_f32_e32 v127, v127, v255
	v_fmac_f32_e32 v227, v126, v126
	v_fmac_f32_e32 v227, v127, v127
	v_readlane_b32 s44, v244, 0
	v_readlane_b32 s45, v244, 1
	v_and_b32_e32 v254, 63, v185
	v_lshrrev_b32_e32 v254, 4, v254
	v_lshlrev_b32_e32 v254, 5, v254
	s_lshl_b32 s40, s38, 7
	s_lshl_b32 s41, s18, 10
	s_add_u32 s40, s40, s41
	v_add_u32_e32 v254, s40, v254
	global_load_dwordx4 v[160:163], v254, s[44:45] offset:0
	global_load_dwordx4 v[164:167], v254, s[44:45] offset:16
	global_load_dwordx4 v[168:171], v254, s[44:45] offset:512
	global_load_dwordx4 v[172:175], v254, s[44:45] offset:528
	ds_bpermute_b32 v128, v232, v238
	ds_bpermute_b32 v132, v232, v239
	ds_bpermute_b32 v136, v232, v240
	ds_bpermute_b32 v140, v232, v241
	ds_bpermute_b32 v144, v232, v242
	ds_bpermute_b32 v148, v232, v243
	ds_bpermute_b32 v152, v232, v226
	ds_bpermute_b32 v156, v232, v227
	s_waitcnt lgkmcnt(0)
	v_add_f32_e32 v238, v238, v128
	v_add_f32_e32 v239, v239, v132
	v_add_f32_e32 v240, v240, v136
	v_add_f32_e32 v241, v241, v140
	v_add_f32_e32 v242, v242, v144
	v_add_f32_e32 v243, v243, v148
	v_add_f32_e32 v226, v226, v152
	v_add_f32_e32 v227, v227, v156
	ds_bpermute_b32 v128, v233, v238
	ds_bpermute_b32 v132, v233, v239
	ds_bpermute_b32 v136, v233, v240
	ds_bpermute_b32 v140, v233, v241
	ds_bpermute_b32 v144, v233, v242
	ds_bpermute_b32 v148, v233, v243
	ds_bpermute_b32 v152, v233, v226
	ds_bpermute_b32 v156, v233, v227
	s_waitcnt lgkmcnt(0)
	v_add_f32_e32 v238, v238, v128
	v_add_f32_e32 v239, v239, v132
	v_add_f32_e32 v240, v240, v136
	v_add_f32_e32 v241, v241, v140
	v_add_f32_e32 v242, v242, v144
	v_add_f32_e32 v243, v243, v148
	v_add_f32_e32 v226, v226, v152
	v_add_f32_e32 v227, v227, v156
	s_mov_b64 exec, 0xffff
	global_atomic_add_f32 v230, v238, s[50:51] offset:0
	global_atomic_add_f32 v230, v239, s[50:51] offset:64
	global_atomic_add_f32 v230, v240, s[50:51] offset:128
	global_atomic_add_f32 v230, v241, s[50:51] offset:192
	global_atomic_add_f32 v230, v242, s[50:51] offset:512
	global_atomic_add_f32 v230, v243, s[50:51] offset:576
	global_atomic_add_f32 v230, v226, s[50:51] offset:640
	global_atomic_add_f32 v230, v227, s[50:51] offset:704
	s_mov_b64 exec, -1
	s_waitcnt vmcnt(0)
	s_barrier
	s_cmp_lg_u32 s36, 0
	s_cbranch_scc1 .Lp6_fin_wait
	s_mov_b64 exec, 1
	v_mov_b32_e32 v237, 0
	v_mov_b32_e32 v236, 1
	global_atomic_add v237, v236, s[54:55]
	s_mov_b32 s42, 0
